# priorities reversed: load segments at prio 1, MFMA segments at prio 0, all GEMM loops + int8 nop trims
# baseline (speedup 1.0000x reference)
.LBB0_308:
	ds_read_b128 v[142:145], v191
	ds_read_b128 v[138:141], v191 offset:1024
	ds_read_b128 v[134:137], v191 offset:2048
	ds_read_b128 v[130:133], v191 offset:3072
	s_add_u32 s46, s44, 0xfff80080
	s_addc_u32 s47, s45, -1
	s_cmp_eq_u32 s37, 28
	s_cselect_b32 s49, s0, s47
	s_cselect_b32 s48, s1, s46
	s_cselect_b32 s47, s7, s31
	s_cselect_b32 s46, s14, s15
	v_lshl_add_u64 v[166:167], s[44:45], 0, v[162:163]
	s_add_i32 m0, s9, 0xc000
	ds_read_b128 v[170:173], v192
	ds_read_b128 v[174:177], v192 offset:1024
	s_waitcnt lgkmcnt(0)
	ds_read_b128 v[178:181], v192 offset:2048
	ds_read_b128 v[182:185], v192 offset:3072
	ds_read_b128 v[204:207], v192 offset:4096
	ds_read_b128 v[208:211], v192 offset:5120
	ds_read_b128 v[212:215], v192 offset:6144
	ds_read_b128 v[216:219], v192 offset:7168
	global_load_lds_dwordx4 v[166:167], off
	v_lshl_add_u64 v[166:167], s[44:45], 0, v[164:165]
	s_add_i32 m0, s9, 0xe000
	s_nop 0
	global_load_lds_dwordx4 v[166:167], off
	s_waitcnt lgkmcnt(8)
	s_barrier
	s_waitcnt lgkmcnt(0)
	s_setprio 0
	s_waitcnt lgkmcnt(0)
	v_mfma_i32_16x16x64_i8 v[126:129], v[142:145], v[170:173], v[126:129]
	v_mfma_i32_16x16x64_i8 v[126:129], v[138:141], v[174:177], v[126:129]
	v_mfma_i32_16x16x64_i8 v[122:125], v[134:137], v[170:173], v[122:125]
	v_mfma_i32_16x16x64_i8 v[122:125], v[130:133], v[174:177], v[122:125]
	v_mfma_i32_16x16x64_i8 v[110:113], v[142:145], v[178:181], v[110:113]
	v_mfma_i32_16x16x64_i8 v[110:113], v[138:141], v[182:185], v[110:113]
	v_mfma_i32_16x16x64_i8 v[106:109], v[134:137], v[178:181], v[106:109]
	v_mfma_i32_16x16x64_i8 v[106:109], v[130:133], v[182:185], v[106:109]
	v_mfma_i32_16x16x64_i8 v[94:97], v[142:145], v[204:207], v[94:97]
	v_mfma_i32_16x16x64_i8 v[94:97], v[138:141], v[208:211], v[94:97]
	v_mfma_i32_16x16x64_i8 v[90:93], v[134:137], v[204:207], v[90:93]
	v_mfma_i32_16x16x64_i8 v[90:93], v[130:133], v[208:211], v[90:93]
	v_mfma_i32_16x16x64_i8 v[78:81], v[142:145], v[212:215], v[78:81]
	v_mfma_i32_16x16x64_i8 v[78:81], v[138:141], v[216:219], v[78:81]
	v_mfma_i32_16x16x64_i8 v[74:77], v[134:137], v[212:215], v[74:77]
	v_mfma_i32_16x16x64_i8 v[74:77], v[130:133], v[216:219], v[74:77]
	s_setprio 1
	s_barrier
	s_add_i32 s50, s55, s8
	v_lshl_add_u64 v[166:167], s[46:47], 0, v[148:149]
	s_mov_b32 m0, s50
	ds_read_b128 v[220:223], v193
	ds_read_b128 v[224:227], v193 offset:1024
	ds_read_b128 v[234:237], v193 offset:2048
	ds_read_b128 v[238:241], v193 offset:3072
	global_load_lds_dwordx4 v[166:167], off
	v_lshl_add_u64 v[168:169], s[46:47], 0, v[152:153]
	s_add_i32 m0, s50, 0x2000
	s_nop 0
	global_load_lds_dwordx4 v[168:169], off
	s_barrier
	s_waitcnt lgkmcnt(0)
	s_setprio 0
	s_waitcnt lgkmcnt(0)
	v_mfma_i32_16x16x64_i8 v[118:121], v[220:223], v[170:173], v[118:121]
	v_mfma_i32_16x16x64_i8 v[118:121], v[224:227], v[174:177], v[118:121]
	v_mfma_i32_16x16x64_i8 v[114:117], v[234:237], v[170:173], v[114:117]
	v_mfma_i32_16x16x64_i8 v[114:117], v[238:241], v[174:177], v[114:117]
	v_mfma_i32_16x16x64_i8 v[102:105], v[220:223], v[178:181], v[102:105]
	v_mfma_i32_16x16x64_i8 v[102:105], v[224:227], v[182:185], v[102:105]
	v_mfma_i32_16x16x64_i8 v[98:101], v[234:237], v[178:181], v[98:101]
	v_mfma_i32_16x16x64_i8 v[98:101], v[238:241], v[182:185], v[98:101]
	v_mfma_i32_16x16x64_i8 v[86:89], v[220:223], v[204:207], v[86:89]
	v_mfma_i32_16x16x64_i8 v[86:89], v[224:227], v[208:211], v[86:89]
	v_mfma_i32_16x16x64_i8 v[82:85], v[234:237], v[204:207], v[82:85]
	v_mfma_i32_16x16x64_i8 v[82:85], v[238:241], v[208:211], v[82:85]
	v_mfma_i32_16x16x64_i8 v[70:73], v[220:223], v[212:215], v[70:73]
	v_mfma_i32_16x16x64_i8 v[70:73], v[224:227], v[216:219], v[70:73]
	v_mfma_i32_16x16x64_i8 v[66:69], v[234:237], v[212:215], v[66:69]
	v_mfma_i32_16x16x64_i8 v[66:69], v[238:241], v[216:219], v[66:69]
	s_setprio 1
	s_mov_b32 m0, s9
	v_lshl_add_u64 v[170:171], s[48:49], 0, v[146:147]
	s_barrier
	ds_read_b128 v[174:177], v192 offset:16384
	ds_read_b128 v[178:181], v192 offset:17408
	ds_read_b128 v[182:185], v192 offset:18432
	ds_read_b128 v[204:207], v192 offset:19456
	ds_read_b128 v[208:211], v192 offset:20480
	ds_read_b128 v[212:215], v192 offset:21504
	ds_read_b128 v[216:219], v192 offset:22528
	ds_read_b128 v[242:245], v192 offset:23552
	global_load_lds_dwordx4 v[170:171], off
	v_lshl_add_u64 v[172:173], s[48:49], 0, v[150:151]
	s_mov_b32 m0, s13
	s_nop 0
	global_load_lds_dwordx4 v[172:173], off
	s_barrier
	s_waitcnt lgkmcnt(0)
	s_setprio 0
	s_waitcnt lgkmcnt(0)
	v_mfma_i32_16x16x64_i8 v[62:65], v[142:145], v[174:177], v[62:65]
	v_mfma_i32_16x16x64_i8 v[62:65], v[138:141], v[178:181], v[62:65]
	v_mfma_i32_16x16x64_i8 v[58:61], v[134:137], v[174:177], v[58:61]
	v_mfma_i32_16x16x64_i8 v[58:61], v[130:133], v[178:181], v[58:61]
	v_mfma_i32_16x16x64_i8 v[46:49], v[142:145], v[182:185], v[46:49]
	v_mfma_i32_16x16x64_i8 v[46:49], v[138:141], v[204:207], v[46:49]
	v_mfma_i32_16x16x64_i8 v[42:45], v[134:137], v[182:185], v[42:45]
	v_mfma_i32_16x16x64_i8 v[42:45], v[130:133], v[204:207], v[42:45]
	v_mfma_i32_16x16x64_i8 v[30:33], v[142:145], v[208:211], v[30:33]
	v_mfma_i32_16x16x64_i8 v[30:33], v[138:141], v[212:215], v[30:33]
	v_mfma_i32_16x16x64_i8 v[26:29], v[134:137], v[208:211], v[26:29]
	v_mfma_i32_16x16x64_i8 v[26:29], v[130:133], v[212:215], v[26:29]
	v_mfma_i32_16x16x64_i8 v[14:17], v[142:145], v[216:219], v[14:17]
	v_mfma_i32_16x16x64_i8 v[14:17], v[138:141], v[242:245], v[14:17]
	v_mfma_i32_16x16x64_i8 v[10:13], v[134:137], v[216:219], v[10:13]
	v_mfma_i32_16x16x64_i8 v[10:13], v[130:133], v[242:245], v[10:13]
	s_setprio 1
	s_barrier
	s_add_u32 s50, s46, 0x80000
	s_addc_u32 s51, s47, 0
	s_add_i32 s59, s56, s8
	v_lshl_add_u64 v[130:131], s[50:51], 0, v[148:149]
	s_mov_b32 m0, s59
	s_nop 0
	global_load_lds_dwordx4 v[130:131], off
	v_lshl_add_u64 v[130:131], s[50:51], 0, v[152:153]
	s_add_i32 m0, s59, 0x2000
	s_nop 0
	global_load_lds_dwordx4 v[130:131], off
	s_waitcnt vmcnt(6)
	s_barrier
	s_setprio 0
	v_mfma_i32_16x16x64_i8 v[54:57], v[220:223], v[174:177], v[54:57]
	v_mfma_i32_16x16x64_i8 v[54:57], v[224:227], v[178:181], v[54:57]
	v_mfma_i32_16x16x64_i8 v[50:53], v[234:237], v[174:177], v[50:53]
	v_mfma_i32_16x16x64_i8 v[50:53], v[238:241], v[178:181], v[50:53]
	v_mfma_i32_16x16x64_i8 v[38:41], v[220:223], v[182:185], v[38:41]
	v_mfma_i32_16x16x64_i8 v[38:41], v[224:227], v[204:207], v[38:41]
	v_mfma_i32_16x16x64_i8 v[34:37], v[234:237], v[182:185], v[34:37]
	v_mfma_i32_16x16x64_i8 v[34:37], v[238:241], v[204:207], v[34:37]
	v_mfma_i32_16x16x64_i8 v[22:25], v[220:223], v[208:211], v[22:25]
	v_mfma_i32_16x16x64_i8 v[22:25], v[224:227], v[212:215], v[22:25]
	v_mfma_i32_16x16x64_i8 v[18:21], v[234:237], v[208:211], v[18:21]
	v_mfma_i32_16x16x64_i8 v[18:21], v[238:241], v[212:215], v[18:21]
	v_mfma_i32_16x16x64_i8 v[6:9], v[220:223], v[216:219], v[6:9]
	v_mfma_i32_16x16x64_i8 v[6:9], v[224:227], v[242:245], v[6:9]
	v_mfma_i32_16x16x64_i8 v[2:5], v[234:237], v[216:219], v[2:5]
	v_mfma_i32_16x16x64_i8 v[2:5], v[238:241], v[242:245], v[2:5]
	s_setprio 1
	s_add_i32 s50, 0, 0x18000
	v_add_u32_e32 v142, s50, v188
	s_barrier
	ds_read_b128 v[130:133], v142
	ds_read_b128 v[134:137], v142 offset:1024
	ds_read_b128 v[138:141], v142 offset:2048
	ds_read_b128 v[142:145], v142 offset:3072
	s_add_u32 s48, s48, 0x80000
	s_addc_u32 s49, s49, 0
	s_mov_b32 m0, s29
	v_lshl_add_u64 v[186:187], s[48:49], 0, v[146:147]
	ds_read_b128 v[174:177], v192 offset:32768
	ds_read_b128 v[178:181], v192 offset:33792
	ds_read_b128 v[182:185], v192 offset:34816
	ds_read_b128 v[204:207], v192 offset:35840
	ds_read_b128 v[208:211], v192 offset:36864
	ds_read_b128 v[212:215], v192 offset:37888
	ds_read_b128 v[216:219], v192 offset:38912
	ds_read_b128 v[220:223], v192 offset:39936
	global_load_lds_dwordx4 v[186:187], off
	v_lshl_add_u64 v[186:187], s[48:49], 0, v[150:151]
	s_mov_b32 m0, s33
	s_nop 0
	global_load_lds_dwordx4 v[186:187], off
	s_waitcnt lgkmcnt(8)
	s_barrier
	s_waitcnt lgkmcnt(0)
	s_setprio 0
	s_waitcnt lgkmcnt(0)
	v_mfma_i32_16x16x64_i8 v[126:129], v[130:133], v[174:177], v[126:129]
	v_mfma_i32_16x16x64_i8 v[126:129], v[134:137], v[178:181], v[126:129]
	v_mfma_i32_16x16x64_i8 v[122:125], v[138:141], v[174:177], v[122:125]
	v_mfma_i32_16x16x64_i8 v[122:125], v[142:145], v[178:181], v[122:125]
	v_mfma_i32_16x16x64_i8 v[110:113], v[130:133], v[182:185], v[110:113]
	v_mfma_i32_16x16x64_i8 v[110:113], v[134:137], v[204:207], v[110:113]
	v_mfma_i32_16x16x64_i8 v[106:109], v[138:141], v[182:185], v[106:109]
	v_mfma_i32_16x16x64_i8 v[106:109], v[142:145], v[204:207], v[106:109]
	v_mfma_i32_16x16x64_i8 v[94:97], v[130:133], v[208:211], v[94:97]
	v_mfma_i32_16x16x64_i8 v[94:97], v[134:137], v[212:215], v[94:97]
	v_mfma_i32_16x16x64_i8 v[90:93], v[138:141], v[208:211], v[90:93]
	v_mfma_i32_16x16x64_i8 v[90:93], v[142:145], v[212:215], v[90:93]
	v_mfma_i32_16x16x64_i8 v[78:81], v[130:133], v[216:219], v[78:81]
	v_mfma_i32_16x16x64_i8 v[78:81], v[134:137], v[220:223], v[78:81]
	v_mfma_i32_16x16x64_i8 v[74:77], v[138:141], v[216:219], v[74:77]
	v_mfma_i32_16x16x64_i8 v[74:77], v[142:145], v[220:223], v[74:77]
	s_setprio 1
	s_barrier
	s_add_i32 s48, 0, 0x1c000
	s_add_i32 s49, s50, s8
	v_add_u32_e32 v156, s48, v188
	v_lshl_add_u64 v[166:167], v[166:167], 0, s[22:23]
	s_mov_b32 m0, s49
	ds_read_b128 v[224:227], v156
	ds_read_b128 v[234:237], v156 offset:1024
	ds_read_b128 v[238:241], v156 offset:2048
	ds_read_b128 v[242:245], v156 offset:3072
	global_load_lds_dwordx4 v[166:167], off
	v_lshl_add_u64 v[166:167], v[168:169], 0, s[22:23]
	s_add_i32 m0, s49, 0x2000
	s_nop 0
	global_load_lds_dwordx4 v[166:167], off
	s_barrier
	s_waitcnt lgkmcnt(0)
	s_setprio 0
	s_waitcnt lgkmcnt(0)
	v_mfma_i32_16x16x64_i8 v[118:121], v[224:227], v[174:177], v[118:121]
	v_mfma_i32_16x16x64_i8 v[118:121], v[234:237], v[178:181], v[118:121]
	v_mfma_i32_16x16x64_i8 v[114:117], v[238:241], v[174:177], v[114:117]
	v_mfma_i32_16x16x64_i8 v[114:117], v[242:245], v[178:181], v[114:117]
	v_mfma_i32_16x16x64_i8 v[102:105], v[224:227], v[182:185], v[102:105]
	v_mfma_i32_16x16x64_i8 v[102:105], v[234:237], v[204:207], v[102:105]
	v_mfma_i32_16x16x64_i8 v[98:101], v[238:241], v[182:185], v[98:101]
	v_mfma_i32_16x16x64_i8 v[98:101], v[242:245], v[204:207], v[98:101]
	v_mfma_i32_16x16x64_i8 v[86:89], v[224:227], v[208:211], v[86:89]
	v_mfma_i32_16x16x64_i8 v[86:89], v[234:237], v[212:215], v[86:89]
	v_mfma_i32_16x16x64_i8 v[82:85], v[238:241], v[208:211], v[82:85]
	v_mfma_i32_16x16x64_i8 v[82:85], v[242:245], v[212:215], v[82:85]
	v_mfma_i32_16x16x64_i8 v[70:73], v[224:227], v[216:219], v[70:73]
	v_mfma_i32_16x16x64_i8 v[70:73], v[234:237], v[220:223], v[70:73]
	v_mfma_i32_16x16x64_i8 v[66:69], v[238:241], v[216:219], v[66:69]
	v_mfma_i32_16x16x64_i8 v[66:69], v[242:245], v[220:223], v[66:69]
	s_setprio 1
	s_mov_b32 m0, s53
	v_lshl_add_u64 v[170:171], v[170:171], 0, s[22:23]
	s_barrier
	ds_read_b128 v[166:169], v192 offset:49152
	ds_read_b128 v[174:177], v192 offset:50176
	ds_read_b128 v[178:181], v192 offset:51200
	ds_read_b128 v[182:185], v192 offset:52224
	ds_read_b128 v[204:207], v192 offset:53248
	ds_read_b128 v[208:211], v192 offset:54272
	ds_read_b128 v[212:215], v192 offset:55296
	ds_read_b128 v[216:219], v192 offset:56320
	global_load_lds_dwordx4 v[170:171], off
	v_lshl_add_u64 v[170:171], v[172:173], 0, s[22:23]
	s_mov_b32 m0, s54
	s_nop 0
	global_load_lds_dwordx4 v[170:171], off
	s_barrier
	s_waitcnt lgkmcnt(0)
	s_setprio 0
	s_waitcnt lgkmcnt(0)
	v_mfma_i32_16x16x64_i8 v[62:65], v[130:133], v[166:169], v[62:65]
	v_mfma_i32_16x16x64_i8 v[62:65], v[134:137], v[174:177], v[62:65]
	v_mfma_i32_16x16x64_i8 v[58:61], v[138:141], v[166:169], v[58:61]
	v_mfma_i32_16x16x64_i8 v[58:61], v[142:145], v[174:177], v[58:61]
	v_mfma_i32_16x16x64_i8 v[46:49], v[130:133], v[178:181], v[46:49]
	v_mfma_i32_16x16x64_i8 v[46:49], v[134:137], v[182:185], v[46:49]
	v_mfma_i32_16x16x64_i8 v[42:45], v[138:141], v[178:181], v[42:45]
	v_mfma_i32_16x16x64_i8 v[42:45], v[142:145], v[182:185], v[42:45]
	v_mfma_i32_16x16x64_i8 v[30:33], v[130:133], v[204:207], v[30:33]
	v_mfma_i32_16x16x64_i8 v[30:33], v[134:137], v[208:211], v[30:33]
	v_mfma_i32_16x16x64_i8 v[26:29], v[138:141], v[204:207], v[26:29]
	v_mfma_i32_16x16x64_i8 v[26:29], v[142:145], v[208:211], v[26:29]
	v_mfma_i32_16x16x64_i8 v[14:17], v[130:133], v[212:215], v[14:17]
	v_mfma_i32_16x16x64_i8 v[14:17], v[134:137], v[216:219], v[14:17]
	v_mfma_i32_16x16x64_i8 v[10:13], v[138:141], v[212:215], v[10:13]
	v_mfma_i32_16x16x64_i8 v[10:13], v[142:145], v[216:219], v[10:13]
	s_setprio 1
	s_barrier
	s_add_u32 s46, s46, 0x80080
	s_addc_u32 s47, s47, 0
	s_add_i32 s48, s48, s8
	v_lshl_add_u64 v[130:131], s[46:47], 0, v[148:149]
	s_mov_b32 m0, s48
	s_nop 0
	global_load_lds_dwordx4 v[130:131], off
	v_lshl_add_u64 v[130:131], s[46:47], 0, v[152:153]
	s_add_i32 m0, s48, 0x2000
	s_nop 0
	global_load_lds_dwordx4 v[130:131], off
	s_waitcnt vmcnt(6)
	s_barrier
	s_setprio 0
	v_mfma_i32_16x16x64_i8 v[54:57], v[224:227], v[166:169], v[54:57]
	v_mfma_i32_16x16x64_i8 v[54:57], v[234:237], v[174:177], v[54:57]
	v_mfma_i32_16x16x64_i8 v[50:53], v[238:241], v[166:169], v[50:53]
	v_mfma_i32_16x16x64_i8 v[50:53], v[242:245], v[174:177], v[50:53]
	v_mfma_i32_16x16x64_i8 v[38:41], v[224:227], v[178:181], v[38:41]
	v_mfma_i32_16x16x64_i8 v[38:41], v[234:237], v[182:185], v[38:41]
	v_mfma_i32_16x16x64_i8 v[34:37], v[238:241], v[178:181], v[34:37]
	v_mfma_i32_16x16x64_i8 v[34:37], v[242:245], v[182:185], v[34:37]
	v_mfma_i32_16x16x64_i8 v[22:25], v[224:227], v[204:207], v[22:25]
	v_mfma_i32_16x16x64_i8 v[22:25], v[234:237], v[208:211], v[22:25]
	v_mfma_i32_16x16x64_i8 v[18:21], v[238:241], v[204:207], v[18:21]
	v_mfma_i32_16x16x64_i8 v[18:21], v[242:245], v[208:211], v[18:21]
	v_mfma_i32_16x16x64_i8 v[6:9], v[224:227], v[212:215], v[6:9]
	v_mfma_i32_16x16x64_i8 v[6:9], v[234:237], v[216:219], v[6:9]
	v_mfma_i32_16x16x64_i8 v[2:5], v[238:241], v[212:215], v[2:5]
	v_mfma_i32_16x16x64_i8 v[2:5], v[242:245], v[216:219], v[2:5]
	s_setprio 1
	s_add_i32 s37, s37, 2
	s_add_u32 s44, s44, 0x100
	s_addc_u32 s45, s45, 0
	s_add_u32 s15, s15, 0x100
	s_addc_u32 s31, s31, 0
	s_cmp_gt_u32 s37, 29
	s_barrier
	s_cbranch_scc0 .LBB0_308
	s_nop 15
	s_nop 15
	s_and_b64 vcc, exec, s[24:25]
	s_cbranch_vccz .LBB0_311
	s_barrier

.LBB0_412:
	ds_read_b128 v[130:133], v191
	ds_read_b128 v[134:137], v191 offset:1024
	ds_read_b128 v[138:141], v191 offset:2048
	ds_read_b128 v[142:145], v191 offset:3072
	ds_read_b128 v[146:149], v192
	ds_read_b128 v[150:153], v192 offset:1024
	ds_read_b128 v[174:177], v192 offset:2048
	s_waitcnt lgkmcnt(0)
	ds_read_b128 v[178:181], v192 offset:3072
	s_add_u32 s42, s40, 0xfff00080
	s_addc_u32 s43, s41, -1
	s_cmp_eq_u32 s29, 60
	s_cselect_b32 s45, s0, s43
	s_cselect_b32 s44, s1, s42
	s_cselect_b32 s43, s7, s27
	s_cselect_b32 s42, s14, s15
	v_lshl_add_u64 v[186:187], s[40:41], 0, v[170:171]
	s_add_i32 m0, s9, 0xc000
	ds_read_b128 v[182:185], v193
	ds_read_b128 v[204:207], v193 offset:1024
	ds_read_b128 v[208:211], v193 offset:2048
	ds_read_b128 v[212:215], v193 offset:3072
	ds_read_b128 v[216:219], v193 offset:4096
	ds_read_b128 v[220:223], v193 offset:5120
	ds_read_b128 v[224:227], v193 offset:6144
	ds_read_b128 v[234:237], v193 offset:7168
	global_load_lds_dwordx4 v[186:187], off
	v_lshl_add_u64 v[186:187], s[40:41], 0, v[172:173]
	s_add_i32 m0, s9, 0xe000
	s_nop 0
	global_load_lds_dwordx4 v[186:187], off
	s_waitcnt vmcnt(8)
	s_waitcnt lgkmcnt(0)
	s_barrier
	s_setprio 0
	s_waitcnt lgkmcnt(0)
	v_mfma_f32_16x16x32_bf16 v[126:129], v[130:133], v[182:185], v[126:129]
	v_mfma_f32_16x16x32_bf16 v[122:125], v[138:141], v[182:185], v[122:125]
	v_mfma_f32_16x16x32_bf16 v[118:121], v[130:133], v[208:211], v[118:121]
	v_mfma_f32_16x16x32_bf16 v[110:113], v[138:141], v[208:211], v[110:113]
	v_mfma_f32_16x16x32_bf16 v[102:105], v[130:133], v[216:219], v[102:105]
	v_mfma_f32_16x16x32_bf16 v[94:97], v[138:141], v[216:219], v[94:97]
	v_mfma_f32_16x16x32_bf16 v[86:89], v[130:133], v[224:227], v[86:89]
	v_mfma_f32_16x16x32_bf16 v[78:81], v[138:141], v[224:227], v[78:81]
	v_mfma_f32_16x16x32_bf16 v[126:129], v[134:137], v[204:207], v[126:129]
	v_mfma_f32_16x16x32_bf16 v[122:125], v[142:145], v[204:207], v[122:125]
	v_mfma_f32_16x16x32_bf16 v[118:121], v[134:137], v[212:215], v[118:121]
	v_mfma_f32_16x16x32_bf16 v[110:113], v[142:145], v[212:215], v[110:113]
	v_mfma_f32_16x16x32_bf16 v[102:105], v[134:137], v[220:223], v[102:105]
	v_mfma_f32_16x16x32_bf16 v[94:97], v[142:145], v[220:223], v[94:97]
	v_mfma_f32_16x16x32_bf16 v[86:89], v[134:137], v[234:237], v[86:89]
	v_mfma_f32_16x16x32_bf16 v[78:81], v[142:145], v[234:237], v[78:81]
	v_mfma_f32_16x16x32_bf16 v[114:117], v[146:149], v[182:185], v[114:117]
	v_mfma_f32_16x16x32_bf16 v[106:109], v[174:177], v[182:185], v[106:109]
	v_mfma_f32_16x16x32_bf16 v[98:101], v[146:149], v[208:211], v[98:101]
	v_mfma_f32_16x16x32_bf16 v[90:93], v[174:177], v[208:211], v[90:93]
	v_mfma_f32_16x16x32_bf16 v[82:85], v[146:149], v[216:219], v[82:85]
	v_mfma_f32_16x16x32_bf16 v[74:77], v[174:177], v[216:219], v[74:77]
	v_mfma_f32_16x16x32_bf16 v[70:73], v[146:149], v[224:227], v[70:73]
	v_mfma_f32_16x16x32_bf16 v[66:69], v[174:177], v[224:227], v[66:69]
	v_mfma_f32_16x16x32_bf16 v[114:117], v[150:153], v[204:207], v[114:117]
	v_mfma_f32_16x16x32_bf16 v[106:109], v[178:181], v[204:207], v[106:109]
	v_mfma_f32_16x16x32_bf16 v[98:101], v[150:153], v[212:215], v[98:101]
	v_mfma_f32_16x16x32_bf16 v[90:93], v[178:181], v[212:215], v[90:93]
	v_mfma_f32_16x16x32_bf16 v[82:85], v[150:153], v[220:223], v[82:85]
	v_mfma_f32_16x16x32_bf16 v[74:77], v[178:181], v[220:223], v[74:77]
	v_mfma_f32_16x16x32_bf16 v[70:73], v[150:153], v[234:237], v[70:73]
	v_mfma_f32_16x16x32_bf16 v[66:69], v[178:181], v[234:237], v[66:69]
	s_setprio 1
	s_barrier
	s_add_i32 s46, s52, s8
	v_lshl_add_u64 v[186:187], s[42:43], 0, v[158:159]
	s_mov_b32 m0, s46
	ds_read_b128 v[182:185], v193 offset:16384
	ds_read_b128 v[204:207], v193 offset:17408
	ds_read_b128 v[208:211], v193 offset:18432
	ds_read_b128 v[212:215], v193 offset:19456
	ds_read_b128 v[216:219], v193 offset:20480
	ds_read_b128 v[220:223], v193 offset:21504
	ds_read_b128 v[224:227], v193 offset:22528
	ds_read_b128 v[234:237], v193 offset:23552
	global_load_lds_dwordx4 v[186:187], off
	s_add_i32 m0, s46, 0x2000
	s_add_u32 s46, s42, 0x100000
	v_lshl_add_u64 v[194:195], s[42:43], 0, v[162:163]
	s_addc_u32 s47, s43, 0
	s_add_i32 s56, s53, s8
	global_load_lds_dwordx4 v[194:195], off
	v_lshl_add_u64 v[200:201], s[46:47], 0, v[158:159]
	s_mov_b32 m0, s56
	v_lshl_add_u64 v[238:239], s[44:45], 0, v[160:161]
	global_load_lds_dwordx4 v[200:201], off
	v_lshl_add_u64 v[200:201], s[46:47], 0, v[162:163]
	s_add_i32 m0, s56, 0x2000
	s_nop 0
	global_load_lds_dwordx4 v[200:201], off
	v_lshl_add_u64 v[200:201], s[44:45], 0, v[156:157]
	s_mov_b32 m0, s9
	s_nop 0
	global_load_lds_dwordx4 v[200:201], off
	s_mov_b32 m0, s13
	s_nop 0
	global_load_lds_dwordx4 v[238:239], off
	s_waitcnt vmcnt(8)
	s_waitcnt lgkmcnt(0)
	s_barrier
	s_setprio 0
	s_waitcnt lgkmcnt(0)
	v_mfma_f32_16x16x32_bf16 v[62:65], v[130:133], v[182:185], v[62:65]
	v_mfma_f32_16x16x32_bf16 v[58:61], v[138:141], v[182:185], v[58:61]
	v_mfma_f32_16x16x32_bf16 v[54:57], v[130:133], v[208:211], v[54:57]
	v_mfma_f32_16x16x32_bf16 v[46:49], v[138:141], v[208:211], v[46:49]
	v_mfma_f32_16x16x32_bf16 v[38:41], v[130:133], v[216:219], v[38:41]
	v_mfma_f32_16x16x32_bf16 v[30:33], v[138:141], v[216:219], v[30:33]
	v_mfma_f32_16x16x32_bf16 v[22:25], v[130:133], v[224:227], v[22:25]
	v_mfma_f32_16x16x32_bf16 v[14:17], v[138:141], v[224:227], v[14:17]
	v_mfma_f32_16x16x32_bf16 v[62:65], v[134:137], v[204:207], v[62:65]
	v_mfma_f32_16x16x32_bf16 v[58:61], v[142:145], v[204:207], v[58:61]
	v_mfma_f32_16x16x32_bf16 v[54:57], v[134:137], v[212:215], v[54:57]
	v_mfma_f32_16x16x32_bf16 v[46:49], v[142:145], v[212:215], v[46:49]
	v_mfma_f32_16x16x32_bf16 v[38:41], v[134:137], v[220:223], v[38:41]
	v_mfma_f32_16x16x32_bf16 v[30:33], v[142:145], v[220:223], v[30:33]
	v_mfma_f32_16x16x32_bf16 v[22:25], v[134:137], v[234:237], v[22:25]
	v_mfma_f32_16x16x32_bf16 v[14:17], v[142:145], v[234:237], v[14:17]
	v_mfma_f32_16x16x32_bf16 v[50:53], v[146:149], v[182:185], v[50:53]
	v_mfma_f32_16x16x32_bf16 v[42:45], v[174:177], v[182:185], v[42:45]
	v_mfma_f32_16x16x32_bf16 v[34:37], v[146:149], v[208:211], v[34:37]
	v_mfma_f32_16x16x32_bf16 v[26:29], v[174:177], v[208:211], v[26:29]
	v_mfma_f32_16x16x32_bf16 v[18:21], v[146:149], v[216:219], v[18:21]
	v_mfma_f32_16x16x32_bf16 v[10:13], v[174:177], v[216:219], v[10:13]
	v_mfma_f32_16x16x32_bf16 v[6:9], v[146:149], v[224:227], v[6:9]
	v_mfma_f32_16x16x32_bf16 v[2:5], v[174:177], v[224:227], v[2:5]
	v_mfma_f32_16x16x32_bf16 v[50:53], v[150:153], v[204:207], v[50:53]
	v_mfma_f32_16x16x32_bf16 v[42:45], v[178:181], v[204:207], v[42:45]
	v_mfma_f32_16x16x32_bf16 v[34:37], v[150:153], v[212:215], v[34:37]
	v_mfma_f32_16x16x32_bf16 v[26:29], v[178:181], v[212:215], v[26:29]
	v_mfma_f32_16x16x32_bf16 v[18:21], v[150:153], v[220:223], v[18:21]
	v_mfma_f32_16x16x32_bf16 v[10:13], v[178:181], v[220:223], v[10:13]
	v_mfma_f32_16x16x32_bf16 v[6:9], v[150:153], v[234:237], v[6:9]
	v_mfma_f32_16x16x32_bf16 v[2:5], v[178:181], v[234:237], v[2:5]
	s_setprio 1
	s_barrier
	s_add_i32 s46, 0, 0x18000
	s_add_i32 s47, 0, 0x1c000
	v_add_u32_e32 v142, s46, v188
	v_add_u32_e32 v164, s47, v188
	ds_read_b128 v[130:133], v142
	ds_read_b128 v[134:137], v142 offset:1024
	ds_read_b128 v[138:141], v142 offset:2048
	ds_read_b128 v[142:145], v142 offset:3072
	ds_read_b128 v[146:149], v164
	ds_read_b128 v[150:153], v164 offset:1024
	ds_read_b128 v[174:177], v164 offset:2048
	ds_read_b128 v[178:181], v164 offset:3072
	s_add_u32 s44, s44, 0x100000
	s_addc_u32 s45, s45, 0
	s_mov_b32 m0, s33
	v_lshl_add_u64 v[240:241], s[44:45], 0, v[156:157]
	ds_read_b128 v[182:185], v193 offset:32768
	ds_read_b128 v[204:207], v193 offset:33792
	ds_read_b128 v[208:211], v193 offset:34816
	ds_read_b128 v[212:215], v193 offset:35840
	ds_read_b128 v[216:219], v193 offset:36864
	ds_read_b128 v[220:223], v193 offset:37888
	ds_read_b128 v[224:227], v193 offset:38912
	ds_read_b128 v[234:237], v193 offset:39936
	global_load_lds_dwordx4 v[240:241], off
	v_lshl_add_u64 v[240:241], s[44:45], 0, v[160:161]
	s_mov_b32 m0, s39
	s_nop 0
	global_load_lds_dwordx4 v[240:241], off
	s_waitcnt vmcnt(8)
	s_waitcnt lgkmcnt(0)
	s_barrier
	s_setprio 0
	s_waitcnt lgkmcnt(0)
	v_mfma_f32_16x16x32_bf16 v[126:129], v[130:133], v[182:185], v[126:129]
	v_mfma_f32_16x16x32_bf16 v[122:125], v[138:141], v[182:185], v[122:125]
	v_mfma_f32_16x16x32_bf16 v[118:121], v[130:133], v[208:211], v[118:121]
	v_mfma_f32_16x16x32_bf16 v[110:113], v[138:141], v[208:211], v[110:113]
	v_mfma_f32_16x16x32_bf16 v[102:105], v[130:133], v[216:219], v[102:105]
	v_mfma_f32_16x16x32_bf16 v[94:97], v[138:141], v[216:219], v[94:97]
	v_mfma_f32_16x16x32_bf16 v[86:89], v[130:133], v[224:227], v[86:89]
	v_mfma_f32_16x16x32_bf16 v[78:81], v[138:141], v[224:227], v[78:81]
	v_mfma_f32_16x16x32_bf16 v[126:129], v[134:137], v[204:207], v[126:129]
	v_mfma_f32_16x16x32_bf16 v[122:125], v[142:145], v[204:207], v[122:125]
	v_mfma_f32_16x16x32_bf16 v[118:121], v[134:137], v[212:215], v[118:121]
	v_mfma_f32_16x16x32_bf16 v[110:113], v[142:145], v[212:215], v[110:113]
	v_mfma_f32_16x16x32_bf16 v[102:105], v[134:137], v[220:223], v[102:105]
	v_mfma_f32_16x16x32_bf16 v[94:97], v[142:145], v[220:223], v[94:97]
	v_mfma_f32_16x16x32_bf16 v[86:89], v[134:137], v[234:237], v[86:89]
	v_mfma_f32_16x16x32_bf16 v[78:81], v[142:145], v[234:237], v[78:81]
	v_mfma_f32_16x16x32_bf16 v[114:117], v[146:149], v[182:185], v[114:117]
	v_mfma_f32_16x16x32_bf16 v[106:109], v[174:177], v[182:185], v[106:109]
	v_mfma_f32_16x16x32_bf16 v[98:101], v[146:149], v[208:211], v[98:101]
	v_mfma_f32_16x16x32_bf16 v[90:93], v[174:177], v[208:211], v[90:93]
	v_mfma_f32_16x16x32_bf16 v[82:85], v[146:149], v[216:219], v[82:85]
	v_mfma_f32_16x16x32_bf16 v[74:77], v[174:177], v[216:219], v[74:77]
	v_mfma_f32_16x16x32_bf16 v[70:73], v[146:149], v[224:227], v[70:73]
	v_mfma_f32_16x16x32_bf16 v[66:69], v[174:177], v[224:227], v[66:69]
	v_mfma_f32_16x16x32_bf16 v[114:117], v[150:153], v[204:207], v[114:117]
	v_mfma_f32_16x16x32_bf16 v[106:109], v[178:181], v[204:207], v[106:109]
	v_mfma_f32_16x16x32_bf16 v[98:101], v[150:153], v[212:215], v[98:101]
	v_mfma_f32_16x16x32_bf16 v[90:93], v[178:181], v[212:215], v[90:93]
	v_mfma_f32_16x16x32_bf16 v[82:85], v[150:153], v[220:223], v[82:85]
	v_mfma_f32_16x16x32_bf16 v[74:77], v[178:181], v[220:223], v[74:77]
	v_mfma_f32_16x16x32_bf16 v[70:73], v[150:153], v[234:237], v[70:73]
	v_mfma_f32_16x16x32_bf16 v[66:69], v[178:181], v[234:237], v[66:69]
	s_setprio 1
	s_barrier
	s_add_i32 s44, s46, s8
	v_lshl_add_u64 v[186:187], v[186:187], 0, s[20:21]
	s_mov_b32 m0, s44
	ds_read_b128 v[182:185], v193 offset:49152
	ds_read_b128 v[204:207], v193 offset:50176
	ds_read_b128 v[208:211], v193 offset:51200
	ds_read_b128 v[212:215], v193 offset:52224
	ds_read_b128 v[216:219], v193 offset:53248
	ds_read_b128 v[220:223], v193 offset:54272
	ds_read_b128 v[224:227], v193 offset:55296
	ds_read_b128 v[234:237], v193 offset:56320
	global_load_lds_dwordx4 v[186:187], off
	s_add_i32 m0, s44, 0x2000
	s_add_u32 s42, s42, 0x100080
	v_lshl_add_u64 v[186:187], v[194:195], 0, s[20:21]
	s_addc_u32 s43, s43, 0
	s_add_i32 s44, s47, s8
	global_load_lds_dwordx4 v[186:187], off
	v_lshl_add_u64 v[186:187], s[42:43], 0, v[158:159]
	s_mov_b32 m0, s44
	s_nop 0
	global_load_lds_dwordx4 v[186:187], off
	v_lshl_add_u64 v[186:187], s[42:43], 0, v[162:163]
	s_add_i32 m0, s44, 0x2000
	s_nop 0
	global_load_lds_dwordx4 v[186:187], off
	v_lshl_add_u64 v[186:187], v[200:201], 0, s[20:21]
	s_mov_b32 m0, s50
	s_nop 0
	global_load_lds_dwordx4 v[186:187], off
	v_lshl_add_u64 v[186:187], v[238:239], 0, s[20:21]
	s_mov_b32 m0, s51
	s_nop 0
	global_load_lds_dwordx4 v[186:187], off
	s_waitcnt vmcnt(8)
	s_waitcnt lgkmcnt(0)
	s_barrier
	s_setprio 0
	s_waitcnt lgkmcnt(0)
	v_mfma_f32_16x16x32_bf16 v[62:65], v[130:133], v[182:185], v[62:65]
	v_mfma_f32_16x16x32_bf16 v[58:61], v[138:141], v[182:185], v[58:61]
	v_mfma_f32_16x16x32_bf16 v[54:57], v[130:133], v[208:211], v[54:57]
	v_mfma_f32_16x16x32_bf16 v[46:49], v[138:141], v[208:211], v[46:49]
	v_mfma_f32_16x16x32_bf16 v[38:41], v[130:133], v[216:219], v[38:41]
	v_mfma_f32_16x16x32_bf16 v[30:33], v[138:141], v[216:219], v[30:33]
	v_mfma_f32_16x16x32_bf16 v[22:25], v[130:133], v[224:227], v[22:25]
	v_mfma_f32_16x16x32_bf16 v[14:17], v[138:141], v[224:227], v[14:17]
	v_mfma_f32_16x16x32_bf16 v[62:65], v[134:137], v[204:207], v[62:65]
	v_mfma_f32_16x16x32_bf16 v[58:61], v[142:145], v[204:207], v[58:61]
	v_mfma_f32_16x16x32_bf16 v[54:57], v[134:137], v[212:215], v[54:57]
	v_mfma_f32_16x16x32_bf16 v[46:49], v[142:145], v[212:215], v[46:49]
	v_mfma_f32_16x16x32_bf16 v[38:41], v[134:137], v[220:223], v[38:41]
	v_mfma_f32_16x16x32_bf16 v[30:33], v[142:145], v[220:223], v[30:33]
	v_mfma_f32_16x16x32_bf16 v[22:25], v[134:137], v[234:237], v[22:25]
	v_mfma_f32_16x16x32_bf16 v[14:17], v[142:145], v[234:237], v[14:17]
	v_mfma_f32_16x16x32_bf16 v[50:53], v[146:149], v[182:185], v[50:53]
	v_mfma_f32_16x16x32_bf16 v[42:45], v[174:177], v[182:185], v[42:45]
	v_mfma_f32_16x16x32_bf16 v[34:37], v[146:149], v[208:211], v[34:37]
	v_mfma_f32_16x16x32_bf16 v[26:29], v[174:177], v[208:211], v[26:29]
	v_mfma_f32_16x16x32_bf16 v[18:21], v[146:149], v[216:219], v[18:21]
	v_mfma_f32_16x16x32_bf16 v[10:13], v[174:177], v[216:219], v[10:13]
	v_mfma_f32_16x16x32_bf16 v[6:9], v[146:149], v[224:227], v[6:9]
	v_mfma_f32_16x16x32_bf16 v[2:5], v[174:177], v[224:227], v[2:5]
	v_mfma_f32_16x16x32_bf16 v[50:53], v[150:153], v[204:207], v[50:53]
	v_mfma_f32_16x16x32_bf16 v[42:45], v[178:181], v[204:207], v[42:45]
	v_mfma_f32_16x16x32_bf16 v[34:37], v[150:153], v[212:215], v[34:37]
	v_mfma_f32_16x16x32_bf16 v[26:29], v[178:181], v[212:215], v[26:29]
	v_mfma_f32_16x16x32_bf16 v[18:21], v[150:153], v[220:223], v[18:21]
	v_mfma_f32_16x16x32_bf16 v[10:13], v[178:181], v[220:223], v[10:13]
	v_mfma_f32_16x16x32_bf16 v[6:9], v[150:153], v[234:237], v[6:9]
	v_mfma_f32_16x16x32_bf16 v[2:5], v[178:181], v[234:237], v[2:5]
	s_setprio 1
	s_barrier
	s_add_i32 s29, s29, 2
	s_add_u32 s40, s40, 0x100
	s_addc_u32 s41, s41, 0
	s_add_u32 s15, s15, 0x100
	s_addc_u32 s27, s27, 0
	s_cmp_gt_u32 s29, 61
	s_cbranch_scc0 .LBB0_412
	s_and_b64 vcc, exec, s[22:23]
	s_cbranch_vccz .LBB0_415
	s_barrier

.LBB0_514:
	ds_read_b128 v[156:159], v146
	ds_read_b128 v[160:163], v146 offset:1024
	ds_read_b128 v[164:167], v146 offset:2048
	ds_read_b128 v[168:171], v146 offset:3072
	ds_read_b128 v[172:175], v147
	s_waitcnt lgkmcnt(0)
	ds_read_b128 v[176:179], v147 offset:1024
	ds_read_b128 v[180:183], v147 offset:2048
	ds_read_b128 v[184:187], v147 offset:3072
	s_add_u32 s28, s26, 0xfff00080
	s_addc_u32 s29, s27, -1
	s_cmp_eq_u32 s50, 4
	s_cselect_b32 s31, s19, s29
	s_cselect_b32 s30, s18, s28
	s_cselect_b32 s29, s21, s49
	s_cselect_b32 s28, s20, s23
	s_mov_b32 m0, s36
	v_lshl_add_u64 v[142:143], s[26:27], 0, v[138:139]
	ds_read_b128 v[190:193], v148
	ds_read_b128 v[204:207], v148 offset:1024
	ds_read_b128 v[208:211], v148 offset:2048
	ds_read_b128 v[212:215], v148 offset:3072
	ds_read_b128 v[216:219], v148 offset:4096
	ds_read_b128 v[220:223], v148 offset:5120
	ds_read_b128 v[224:227], v148 offset:6144
	ds_read_b128 v[234:237], v148 offset:7168
	global_load_lds_dwordx4 v[142:143], off
	v_lshl_add_u64 v[142:143], s[26:27], 0, v[140:141]
	s_mov_b32 m0, s37
	s_nop 0
	global_load_lds_dwordx4 v[142:143], off
	s_waitcnt vmcnt(8)
	s_waitcnt lgkmcnt(0)
	s_barrier
	s_setprio 0
	s_waitcnt lgkmcnt(0)
	v_mfma_f32_16x16x32_bf16 v[126:129], v[156:159], v[190:193], v[126:129]
	v_mfma_f32_16x16x32_bf16 v[122:125], v[164:167], v[190:193], v[122:125]
	v_mfma_f32_16x16x32_bf16 v[118:121], v[156:159], v[208:211], v[118:121]
	v_mfma_f32_16x16x32_bf16 v[110:113], v[164:167], v[208:211], v[110:113]
	v_mfma_f32_16x16x32_bf16 v[102:105], v[156:159], v[216:219], v[102:105]
	v_mfma_f32_16x16x32_bf16 v[94:97], v[164:167], v[216:219], v[94:97]
	v_mfma_f32_16x16x32_bf16 v[82:85], v[156:159], v[224:227], v[82:85]
	v_mfma_f32_16x16x32_bf16 v[74:77], v[164:167], v[224:227], v[74:77]
	v_mfma_f32_16x16x32_bf16 v[126:129], v[160:163], v[204:207], v[126:129]
	v_mfma_f32_16x16x32_bf16 v[122:125], v[168:171], v[204:207], v[122:125]
	v_mfma_f32_16x16x32_bf16 v[118:121], v[160:163], v[212:215], v[118:121]
	v_mfma_f32_16x16x32_bf16 v[110:113], v[168:171], v[212:215], v[110:113]
	v_mfma_f32_16x16x32_bf16 v[102:105], v[160:163], v[220:223], v[102:105]
	v_mfma_f32_16x16x32_bf16 v[94:97], v[168:171], v[220:223], v[94:97]
	v_mfma_f32_16x16x32_bf16 v[82:85], v[160:163], v[234:237], v[82:85]
	v_mfma_f32_16x16x32_bf16 v[74:77], v[168:171], v[234:237], v[74:77]
	v_mfma_f32_16x16x32_bf16 v[114:117], v[172:175], v[190:193], v[114:117]
	v_mfma_f32_16x16x32_bf16 v[106:109], v[180:183], v[190:193], v[106:109]
	v_mfma_f32_16x16x32_bf16 v[98:101], v[172:175], v[208:211], v[98:101]
	v_mfma_f32_16x16x32_bf16 v[90:93], v[180:183], v[208:211], v[90:93]
	v_mfma_f32_16x16x32_bf16 v[86:89], v[172:175], v[216:219], v[86:89]
	v_mfma_f32_16x16x32_bf16 v[78:81], v[180:183], v[216:219], v[78:81]
	v_mfma_f32_16x16x32_bf16 v[70:73], v[172:175], v[224:227], v[70:73]
	v_mfma_f32_16x16x32_bf16 v[66:69], v[180:183], v[224:227], v[66:69]
	v_mfma_f32_16x16x32_bf16 v[114:117], v[176:179], v[204:207], v[114:117]
	v_mfma_f32_16x16x32_bf16 v[106:109], v[184:187], v[204:207], v[106:109]
	v_mfma_f32_16x16x32_bf16 v[98:101], v[176:179], v[212:215], v[98:101]
	v_mfma_f32_16x16x32_bf16 v[90:93], v[184:187], v[212:215], v[90:93]
	v_mfma_f32_16x16x32_bf16 v[86:89], v[176:179], v[220:223], v[86:89]
	v_mfma_f32_16x16x32_bf16 v[78:81], v[184:187], v[220:223], v[78:81]
	v_mfma_f32_16x16x32_bf16 v[70:73], v[176:179], v[234:237], v[70:73]
	v_mfma_f32_16x16x32_bf16 v[66:69], v[184:187], v[234:237], v[66:69]
	s_setprio 1
	s_barrier
	s_mov_b32 m0, s38
	v_lshl_add_u64 v[142:143], s[28:29], 0, v[134:135]
	s_add_u32 s52, s28, 0x20000
	ds_read_b128 v[190:193], v148 offset:16384
	ds_read_b128 v[204:207], v148 offset:17408
	ds_read_b128 v[208:211], v148 offset:18432
	ds_read_b128 v[212:215], v148 offset:19456
	ds_read_b128 v[216:219], v148 offset:20480
	ds_read_b128 v[220:223], v148 offset:21504
	ds_read_b128 v[224:227], v148 offset:22528
	ds_read_b128 v[234:237], v148 offset:23552
	global_load_lds_dwordx4 v[142:143], off
	v_lshl_add_u64 v[152:153], s[28:29], 0, v[130:131]
	s_mov_b32 m0, s39
	s_addc_u32 s53, s29, 0
	global_load_lds_dwordx4 v[152:153], off
	v_lshl_add_u64 v[194:195], s[52:53], 0, v[134:135]
	s_mov_b32 m0, s40
	v_lshl_add_u64 v[200:201], s[30:31], 0, v[132:133]
	global_load_lds_dwordx4 v[194:195], off
	v_lshl_add_u64 v[194:195], s[52:53], 0, v[130:131]
	s_mov_b32 m0, s41
	s_nop 0
	global_load_lds_dwordx4 v[194:195], off
	v_lshl_add_u64 v[194:195], s[30:31], 0, v[136:137]
	s_mov_b32 m0, s9
	s_nop 0
	global_load_lds_dwordx4 v[194:195], off
	s_mov_b32 m0, s13
	s_nop 0
	global_load_lds_dwordx4 v[200:201], off
	s_waitcnt vmcnt(8)
	s_waitcnt lgkmcnt(0)
	s_barrier
	s_setprio 0
	s_waitcnt lgkmcnt(0)
	v_mfma_f32_16x16x32_bf16 v[62:65], v[156:159], v[190:193], v[62:65]
	v_mfma_f32_16x16x32_bf16 v[58:61], v[164:167], v[190:193], v[58:61]
	v_mfma_f32_16x16x32_bf16 v[54:57], v[156:159], v[208:211], v[54:57]
	v_mfma_f32_16x16x32_bf16 v[46:49], v[164:167], v[208:211], v[46:49]
	v_mfma_f32_16x16x32_bf16 v[38:41], v[156:159], v[216:219], v[38:41]
	v_mfma_f32_16x16x32_bf16 v[30:33], v[164:167], v[216:219], v[30:33]
	v_mfma_f32_16x16x32_bf16 v[22:25], v[156:159], v[224:227], v[22:25]
	v_mfma_f32_16x16x32_bf16 v[14:17], v[164:167], v[224:227], v[14:17]
	v_mfma_f32_16x16x32_bf16 v[62:65], v[160:163], v[204:207], v[62:65]
	v_mfma_f32_16x16x32_bf16 v[58:61], v[168:171], v[204:207], v[58:61]
	v_mfma_f32_16x16x32_bf16 v[54:57], v[160:163], v[212:215], v[54:57]
	v_mfma_f32_16x16x32_bf16 v[46:49], v[168:171], v[212:215], v[46:49]
	v_mfma_f32_16x16x32_bf16 v[38:41], v[160:163], v[220:223], v[38:41]
	v_mfma_f32_16x16x32_bf16 v[30:33], v[168:171], v[220:223], v[30:33]
	v_mfma_f32_16x16x32_bf16 v[22:25], v[160:163], v[234:237], v[22:25]
	v_mfma_f32_16x16x32_bf16 v[14:17], v[168:171], v[234:237], v[14:17]
	v_mfma_f32_16x16x32_bf16 v[50:53], v[172:175], v[190:193], v[50:53]
	v_mfma_f32_16x16x32_bf16 v[42:45], v[180:183], v[190:193], v[42:45]
	v_mfma_f32_16x16x32_bf16 v[34:37], v[172:175], v[208:211], v[34:37]
	v_mfma_f32_16x16x32_bf16 v[26:29], v[180:183], v[208:211], v[26:29]
	v_mfma_f32_16x16x32_bf16 v[18:21], v[172:175], v[216:219], v[18:21]
	v_mfma_f32_16x16x32_bf16 v[10:13], v[180:183], v[216:219], v[10:13]
	v_mfma_f32_16x16x32_bf16 v[6:9], v[172:175], v[224:227], v[6:9]
	v_mfma_f32_16x16x32_bf16 v[2:5], v[180:183], v[224:227], v[2:5]
	v_mfma_f32_16x16x32_bf16 v[50:53], v[176:179], v[204:207], v[50:53]
	v_mfma_f32_16x16x32_bf16 v[42:45], v[184:187], v[204:207], v[42:45]
	v_mfma_f32_16x16x32_bf16 v[34:37], v[176:179], v[212:215], v[34:37]
	v_mfma_f32_16x16x32_bf16 v[26:29], v[184:187], v[212:215], v[26:29]
	v_mfma_f32_16x16x32_bf16 v[18:21], v[176:179], v[220:223], v[18:21]
	v_mfma_f32_16x16x32_bf16 v[10:13], v[184:187], v[220:223], v[10:13]
	v_mfma_f32_16x16x32_bf16 v[6:9], v[176:179], v[234:237], v[6:9]
	v_mfma_f32_16x16x32_bf16 v[2:5], v[184:187], v[234:237], v[2:5]
	s_setprio 1
	s_barrier
	ds_read_b128 v[156:159], v149
	ds_read_b128 v[160:163], v149 offset:1024
	ds_read_b128 v[164:167], v149 offset:2048
	ds_read_b128 v[168:171], v149 offset:3072
	ds_read_b128 v[172:175], v150
	ds_read_b128 v[176:179], v150 offset:1024
	ds_read_b128 v[180:183], v150 offset:2048
	ds_read_b128 v[184:187], v150 offset:3072
	s_add_u32 s30, s30, 0x100000
	s_addc_u32 s31, s31, 0
	s_mov_b32 m0, s14
	v_lshl_add_u64 v[238:239], s[30:31], 0, v[136:137]
	ds_read_b128 v[190:193], v148 offset:32768
	ds_read_b128 v[204:207], v148 offset:33792
	ds_read_b128 v[208:211], v148 offset:34816
	ds_read_b128 v[212:215], v148 offset:35840
	ds_read_b128 v[216:219], v148 offset:36864
	ds_read_b128 v[220:223], v148 offset:37888
	ds_read_b128 v[224:227], v148 offset:38912
	ds_read_b128 v[234:237], v148 offset:39936
	global_load_lds_dwordx4 v[238:239], off
	v_lshl_add_u64 v[238:239], s[30:31], 0, v[132:133]
	s_mov_b32 m0, s15
	s_nop 0
	global_load_lds_dwordx4 v[238:239], off
	s_waitcnt vmcnt(8)
	s_waitcnt lgkmcnt(0)
	s_barrier
	s_setprio 0
	s_waitcnt lgkmcnt(0)
	v_mfma_f32_16x16x32_bf16 v[126:129], v[156:159], v[190:193], v[126:129]
	v_mfma_f32_16x16x32_bf16 v[122:125], v[164:167], v[190:193], v[122:125]
	v_mfma_f32_16x16x32_bf16 v[118:121], v[156:159], v[208:211], v[118:121]
	v_mfma_f32_16x16x32_bf16 v[110:113], v[164:167], v[208:211], v[110:113]
	v_mfma_f32_16x16x32_bf16 v[102:105], v[156:159], v[216:219], v[102:105]
	v_mfma_f32_16x16x32_bf16 v[94:97], v[164:167], v[216:219], v[94:97]
	v_mfma_f32_16x16x32_bf16 v[82:85], v[156:159], v[224:227], v[82:85]
	v_mfma_f32_16x16x32_bf16 v[74:77], v[164:167], v[224:227], v[74:77]
	v_mfma_f32_16x16x32_bf16 v[126:129], v[160:163], v[204:207], v[126:129]
	v_mfma_f32_16x16x32_bf16 v[122:125], v[168:171], v[204:207], v[122:125]
	v_mfma_f32_16x16x32_bf16 v[118:121], v[160:163], v[212:215], v[118:121]
	v_mfma_f32_16x16x32_bf16 v[110:113], v[168:171], v[212:215], v[110:113]
	v_mfma_f32_16x16x32_bf16 v[102:105], v[160:163], v[220:223], v[102:105]
	v_mfma_f32_16x16x32_bf16 v[94:97], v[168:171], v[220:223], v[94:97]
	v_mfma_f32_16x16x32_bf16 v[82:85], v[160:163], v[234:237], v[82:85]
	v_mfma_f32_16x16x32_bf16 v[74:77], v[168:171], v[234:237], v[74:77]
	v_mfma_f32_16x16x32_bf16 v[114:117], v[172:175], v[190:193], v[114:117]
	v_mfma_f32_16x16x32_bf16 v[106:109], v[180:183], v[190:193], v[106:109]
	v_mfma_f32_16x16x32_bf16 v[98:101], v[172:175], v[208:211], v[98:101]
	v_mfma_f32_16x16x32_bf16 v[90:93], v[180:183], v[208:211], v[90:93]
	v_mfma_f32_16x16x32_bf16 v[86:89], v[172:175], v[216:219], v[86:89]
	v_mfma_f32_16x16x32_bf16 v[78:81], v[180:183], v[216:219], v[78:81]
	v_mfma_f32_16x16x32_bf16 v[70:73], v[172:175], v[224:227], v[70:73]
	v_mfma_f32_16x16x32_bf16 v[66:69], v[180:183], v[224:227], v[66:69]
	v_mfma_f32_16x16x32_bf16 v[114:117], v[176:179], v[204:207], v[114:117]
	v_mfma_f32_16x16x32_bf16 v[106:109], v[184:187], v[204:207], v[106:109]
	v_mfma_f32_16x16x32_bf16 v[98:101], v[176:179], v[212:215], v[98:101]
	v_mfma_f32_16x16x32_bf16 v[90:93], v[184:187], v[212:215], v[90:93]
	v_mfma_f32_16x16x32_bf16 v[86:89], v[176:179], v[220:223], v[86:89]
	v_mfma_f32_16x16x32_bf16 v[78:81], v[184:187], v[220:223], v[78:81]
	v_mfma_f32_16x16x32_bf16 v[70:73], v[176:179], v[234:237], v[70:73]
	v_mfma_f32_16x16x32_bf16 v[66:69], v[184:187], v[234:237], v[66:69]
	s_setprio 1
	s_barrier
	s_mov_b32 m0, s42
	v_lshl_add_u64 v[142:143], v[142:143], 0, s[4:5]
	s_add_u32 s28, s28, 0x20080
	ds_read_b128 v[190:193], v148 offset:49152
	ds_read_b128 v[204:207], v148 offset:50176
	ds_read_b128 v[208:211], v148 offset:51200
	ds_read_b128 v[212:215], v148 offset:52224
	ds_read_b128 v[216:219], v148 offset:53248
	ds_read_b128 v[220:223], v148 offset:54272
	ds_read_b128 v[224:227], v148 offset:55296
	ds_read_b128 v[234:237], v148 offset:56320
	global_load_lds_dwordx4 v[142:143], off
	v_lshl_add_u64 v[142:143], v[152:153], 0, s[4:5]
	s_mov_b32 m0, s43
	s_addc_u32 s29, s29, 0
	global_load_lds_dwordx4 v[142:143], off
	v_lshl_add_u64 v[142:143], s[28:29], 0, v[134:135]
	s_mov_b32 m0, s44
	s_nop 0
	global_load_lds_dwordx4 v[142:143], off
	v_lshl_add_u64 v[142:143], s[28:29], 0, v[130:131]
	s_mov_b32 m0, s45
	s_nop 0
	global_load_lds_dwordx4 v[142:143], off
	v_lshl_add_u64 v[142:143], v[194:195], 0, s[4:5]
	s_mov_b32 m0, s34
	s_nop 0
	global_load_lds_dwordx4 v[142:143], off
	v_lshl_add_u64 v[142:143], v[200:201], 0, s[4:5]
	s_mov_b32 m0, s35
	s_nop 0
	global_load_lds_dwordx4 v[142:143], off
	s_waitcnt vmcnt(8)
	s_waitcnt lgkmcnt(0)
	s_barrier
	s_setprio 0
	s_waitcnt lgkmcnt(0)
	v_mfma_f32_16x16x32_bf16 v[62:65], v[156:159], v[190:193], v[62:65]
	v_mfma_f32_16x16x32_bf16 v[58:61], v[164:167], v[190:193], v[58:61]
	v_mfma_f32_16x16x32_bf16 v[54:57], v[156:159], v[208:211], v[54:57]
	v_mfma_f32_16x16x32_bf16 v[46:49], v[164:167], v[208:211], v[46:49]
	v_mfma_f32_16x16x32_bf16 v[38:41], v[156:159], v[216:219], v[38:41]
	v_mfma_f32_16x16x32_bf16 v[30:33], v[164:167], v[216:219], v[30:33]
	v_mfma_f32_16x16x32_bf16 v[22:25], v[156:159], v[224:227], v[22:25]
	v_mfma_f32_16x16x32_bf16 v[14:17], v[164:167], v[224:227], v[14:17]
	v_mfma_f32_16x16x32_bf16 v[62:65], v[160:163], v[204:207], v[62:65]
	v_mfma_f32_16x16x32_bf16 v[58:61], v[168:171], v[204:207], v[58:61]
	v_mfma_f32_16x16x32_bf16 v[54:57], v[160:163], v[212:215], v[54:57]
	v_mfma_f32_16x16x32_bf16 v[46:49], v[168:171], v[212:215], v[46:49]
	v_mfma_f32_16x16x32_bf16 v[38:41], v[160:163], v[220:223], v[38:41]
	v_mfma_f32_16x16x32_bf16 v[30:33], v[168:171], v[220:223], v[30:33]
	v_mfma_f32_16x16x32_bf16 v[22:25], v[160:163], v[234:237], v[22:25]
	v_mfma_f32_16x16x32_bf16 v[14:17], v[168:171], v[234:237], v[14:17]
	v_mfma_f32_16x16x32_bf16 v[50:53], v[172:175], v[190:193], v[50:53]
	v_mfma_f32_16x16x32_bf16 v[42:45], v[180:183], v[190:193], v[42:45]
	v_mfma_f32_16x16x32_bf16 v[34:37], v[172:175], v[208:211], v[34:37]
	v_mfma_f32_16x16x32_bf16 v[26:29], v[180:183], v[208:211], v[26:29]
	v_mfma_f32_16x16x32_bf16 v[18:21], v[172:175], v[216:219], v[18:21]
	v_mfma_f32_16x16x32_bf16 v[10:13], v[180:183], v[216:219], v[10:13]
	v_mfma_f32_16x16x32_bf16 v[6:9], v[172:175], v[224:227], v[6:9]
	v_mfma_f32_16x16x32_bf16 v[2:5], v[180:183], v[224:227], v[2:5]
	v_mfma_f32_16x16x32_bf16 v[50:53], v[176:179], v[204:207], v[50:53]
	v_mfma_f32_16x16x32_bf16 v[42:45], v[184:187], v[204:207], v[42:45]
	v_mfma_f32_16x16x32_bf16 v[34:37], v[176:179], v[212:215], v[34:37]
	v_mfma_f32_16x16x32_bf16 v[26:29], v[184:187], v[212:215], v[26:29]
	v_mfma_f32_16x16x32_bf16 v[18:21], v[176:179], v[220:223], v[18:21]
	v_mfma_f32_16x16x32_bf16 v[10:13], v[184:187], v[220:223], v[10:13]
	v_mfma_f32_16x16x32_bf16 v[6:9], v[176:179], v[234:237], v[6:9]
	v_mfma_f32_16x16x32_bf16 v[2:5], v[184:187], v[234:237], v[2:5]
	s_setprio 1
	s_barrier
	s_add_i32 s50, s50, 2
	s_add_u32 s26, s26, 0x100
	s_addc_u32 s27, s27, 0
	s_add_u32 s23, s23, 0x100
	s_addc_u32 s49, s49, 0
	s_cmp_gt_u32 s50, 5
	s_cbranch_scc0 .LBB0_514
	s_and_b64 vcc, exec, s[6:7]
	s_cbranch_vccz .LBB0_517
	s_barrier

.LBB0_734:
	ds_read_b128 v[158:161], v227
	ds_read_b128 v[154:157], v227 offset:1024
	ds_read_b128 v[150:153], v227 offset:2048
	ds_read_b128 v[146:149], v227 offset:3072
	ds_read_b128 v[62:65], v233
	ds_read_b128 v[58:61], v233 offset:1024
	ds_read_b128 v[54:57], v233 offset:2048
	ds_read_b128 v[50:53], v233 offset:3072
	s_add_u32 s14, s30, s34
	s_addc_u32 s15, s31, s35
	s_add_u32 s14, s14, 0x100
	s_addc_u32 s15, s15, 0
	s_add_u32 s25, s77, s34
	s_addc_u32 s29, s78, s35
	s_cmpk_eq_i32 s34, 0xf00
	s_cselect_b32 s41, s31, s15
	s_cselect_b32 s40, s30, s14
	s_cselect_b32 s39, s1, s29
	s_cselect_b32 s38, s0, s25
	s_add_i32 s66, s23, 0xc000
	v_lshl_add_u64 v[240:241], v[162:163], 0, s[34:35]
	s_mov_b32 m0, s66
	s_add_i32 s67, s23, 0xe000
	ds_read_b128 v[166:169], v226
	ds_read_b128 v[170:173], v226 offset:1024
	ds_read_b128 v[174:177], v226 offset:2048
	ds_read_b128 v[178:181], v226 offset:3072
	ds_read_b128 v[182:185], v226 offset:4096
	ds_read_b128 v[186:189], v226 offset:5120
	ds_read_b128 v[190:193], v226 offset:6144
	ds_read_b128 v[236:239], v226 offset:7168
	global_load_lds_dwordx4 v[240:241], off
	v_lshl_add_u64 v[240:241], v[164:165], 0, s[34:35]
	s_mov_b32 m0, s67
	s_nop 0
	global_load_lds_dwordx4 v[240:241], off
	s_waitcnt vmcnt(8)
	s_waitcnt lgkmcnt(0)
	s_barrier
	s_setprio 0
	s_waitcnt lgkmcnt(0)
	v_mfma_i32_16x16x64_i8 v[142:145], v[158:161], v[166:169], v[142:145]
	v_mfma_i32_16x16x64_i8 v[142:145], v[154:157], v[170:173], v[142:145]
	v_mfma_i32_16x16x64_i8 v[138:141], v[150:153], v[166:169], v[138:141]
	v_mfma_i32_16x16x64_i8 v[138:141], v[146:149], v[170:173], v[138:141]
	v_mfma_i32_16x16x64_i8 v[126:129], v[158:161], v[174:177], v[126:129]
	v_mfma_i32_16x16x64_i8 v[126:129], v[154:157], v[178:181], v[126:129]
	v_mfma_i32_16x16x64_i8 v[122:125], v[150:153], v[174:177], v[122:125]
	v_mfma_i32_16x16x64_i8 v[122:125], v[146:149], v[178:181], v[122:125]
	v_mfma_i32_16x16x64_i8 v[110:113], v[158:161], v[182:185], v[110:113]
	v_mfma_i32_16x16x64_i8 v[110:113], v[154:157], v[186:189], v[110:113]
	v_mfma_i32_16x16x64_i8 v[106:109], v[150:153], v[182:185], v[106:109]
	v_mfma_i32_16x16x64_i8 v[106:109], v[146:149], v[186:189], v[106:109]
	v_mfma_i32_16x16x64_i8 v[94:97], v[158:161], v[190:193], v[94:97]
	v_mfma_i32_16x16x64_i8 v[94:97], v[154:157], v[236:239], v[94:97]
	v_mfma_i32_16x16x64_i8 v[90:93], v[150:153], v[190:193], v[90:93]
	v_mfma_i32_16x16x64_i8 v[90:93], v[146:149], v[236:239], v[90:93]
	v_mfma_i32_16x16x64_i8 v[134:137], v[62:65], v[166:169], v[134:137]
	v_mfma_i32_16x16x64_i8 v[134:137], v[58:61], v[170:173], v[134:137]
	v_mfma_i32_16x16x64_i8 v[130:133], v[54:57], v[166:169], v[130:133]
	v_mfma_i32_16x16x64_i8 v[130:133], v[50:53], v[170:173], v[130:133]
	v_mfma_i32_16x16x64_i8 v[118:121], v[62:65], v[174:177], v[118:121]
	v_mfma_i32_16x16x64_i8 v[118:121], v[58:61], v[178:181], v[118:121]
	v_mfma_i32_16x16x64_i8 v[114:117], v[54:57], v[174:177], v[114:117]
	v_mfma_i32_16x16x64_i8 v[114:117], v[50:53], v[178:181], v[114:117]
	v_mfma_i32_16x16x64_i8 v[102:105], v[62:65], v[182:185], v[102:105]
	v_mfma_i32_16x16x64_i8 v[102:105], v[58:61], v[186:189], v[102:105]
	v_mfma_i32_16x16x64_i8 v[98:101], v[54:57], v[182:185], v[98:101]
	v_mfma_i32_16x16x64_i8 v[98:101], v[50:53], v[186:189], v[98:101]
	v_mfma_i32_16x16x64_i8 v[86:89], v[62:65], v[190:193], v[86:89]
	v_mfma_i32_16x16x64_i8 v[86:89], v[58:61], v[236:239], v[86:89]
	v_mfma_i32_16x16x64_i8 v[82:85], v[54:57], v[190:193], v[82:85]
	v_mfma_i32_16x16x64_i8 v[82:85], v[50:53], v[236:239], v[82:85]
	s_setprio 1
	s_barrier
	s_add_i32 s68, s60, s21
	s_add_i32 s69, s68, 0x2000
	v_lshl_add_u64 v[166:167], s[38:39], 0, v[202:203]
	s_mov_b32 m0, s68
	s_add_u32 s14, s38, 0x80000
	ds_read_b128 v[174:177], v226 offset:16384
	ds_read_b128 v[178:181], v226 offset:17408
	ds_read_b128 v[182:185], v226 offset:18432
	ds_read_b128 v[186:189], v226 offset:19456
	ds_read_b128 v[190:193], v226 offset:20480
	ds_read_b128 v[236:239], v226 offset:21504
	ds_read_b128 v[240:243], v226 offset:22528
	ds_read_b128 v[244:247], v226 offset:23552
	global_load_lds_dwordx4 v[166:167], off
	v_lshl_add_u64 v[168:169], s[38:39], 0, v[206:207]
	s_mov_b32 m0, s69
	s_addc_u32 s15, s39, 0
	s_add_i32 s70, s61, s21
	global_load_lds_dwordx4 v[168:169], off
	v_lshl_add_u64 v[170:171], s[14:15], 0, v[202:203]
	s_mov_b32 m0, s70
	s_add_i32 s71, s70, 0x2000
	global_load_lds_dwordx4 v[170:171], off
	v_lshl_add_u64 v[170:171], s[14:15], 0, v[206:207]
	s_mov_b32 m0, s71
	v_lshl_add_u64 v[172:173], s[40:41], 0, v[204:205]
	global_load_lds_dwordx4 v[170:171], off
	v_lshl_add_u64 v[170:171], s[40:41], 0, v[194:195]
	s_mov_b32 m0, s23
	s_nop 0
	global_load_lds_dwordx4 v[170:171], off
	s_mov_b32 m0, s42
	s_nop 0
	global_load_lds_dwordx4 v[172:173], off
	s_waitcnt vmcnt(8)
	s_waitcnt lgkmcnt(0)
	s_barrier
	s_setprio 0
	s_waitcnt lgkmcnt(0)
	v_mfma_i32_16x16x64_i8 v[78:81], v[158:161], v[174:177], v[78:81]
	v_mfma_i32_16x16x64_i8 v[78:81], v[154:157], v[178:181], v[78:81]
	v_mfma_i32_16x16x64_i8 v[74:77], v[150:153], v[174:177], v[74:77]
	v_mfma_i32_16x16x64_i8 v[74:77], v[146:149], v[178:181], v[74:77]
	v_mfma_i32_16x16x64_i8 v[46:49], v[158:161], v[182:185], v[46:49]
	v_mfma_i32_16x16x64_i8 v[46:49], v[154:157], v[186:189], v[46:49]
	v_mfma_i32_16x16x64_i8 v[42:45], v[150:153], v[182:185], v[42:45]
	v_mfma_i32_16x16x64_i8 v[42:45], v[146:149], v[186:189], v[42:45]
	v_mfma_i32_16x16x64_i8 v[30:33], v[158:161], v[190:193], v[30:33]
	v_mfma_i32_16x16x64_i8 v[30:33], v[154:157], v[236:239], v[30:33]
	v_mfma_i32_16x16x64_i8 v[26:29], v[150:153], v[190:193], v[26:29]
	v_mfma_i32_16x16x64_i8 v[26:29], v[146:149], v[236:239], v[26:29]
	v_mfma_i32_16x16x64_i8 v[14:17], v[158:161], v[240:243], v[14:17]
	v_mfma_i32_16x16x64_i8 v[14:17], v[154:157], v[244:247], v[14:17]
	v_mfma_i32_16x16x64_i8 v[10:13], v[150:153], v[240:243], v[10:13]
	v_mfma_i32_16x16x64_i8 v[10:13], v[146:149], v[244:247], v[10:13]
	v_mfma_i32_16x16x64_i8 v[70:73], v[62:65], v[174:177], v[70:73]
	v_mfma_i32_16x16x64_i8 v[70:73], v[58:61], v[178:181], v[70:73]
	v_mfma_i32_16x16x64_i8 v[66:69], v[54:57], v[174:177], v[66:69]
	v_mfma_i32_16x16x64_i8 v[66:69], v[50:53], v[178:181], v[66:69]
	v_mfma_i32_16x16x64_i8 v[38:41], v[62:65], v[182:185], v[38:41]
	v_mfma_i32_16x16x64_i8 v[38:41], v[58:61], v[186:189], v[38:41]
	v_mfma_i32_16x16x64_i8 v[34:37], v[54:57], v[182:185], v[34:37]
	v_mfma_i32_16x16x64_i8 v[34:37], v[50:53], v[186:189], v[34:37]
	v_mfma_i32_16x16x64_i8 v[22:25], v[62:65], v[190:193], v[22:25]
	v_mfma_i32_16x16x64_i8 v[22:25], v[58:61], v[236:239], v[22:25]
	v_mfma_i32_16x16x64_i8 v[18:21], v[54:57], v[190:193], v[18:21]
	v_mfma_i32_16x16x64_i8 v[18:21], v[50:53], v[236:239], v[18:21]
	v_mfma_i32_16x16x64_i8 v[6:9], v[62:65], v[240:243], v[6:9]
	v_mfma_i32_16x16x64_i8 v[6:9], v[58:61], v[244:247], v[6:9]
	v_mfma_i32_16x16x64_i8 v[2:5], v[54:57], v[240:243], v[2:5]
	v_mfma_i32_16x16x64_i8 v[2:5], v[50:53], v[244:247], v[2:5]
	s_setprio 1
	s_barrier
	s_add_i32 s72, 0, 0x18000
	v_add_u32_e32 v235, s72, v225
	s_add_i32 s74, 0, 0x1c000
	v_add_u32_e32 v236, s74, v225
	ds_read_b128 v[50:53], v235
	ds_read_b128 v[54:57], v235 offset:1024
	ds_read_b128 v[58:61], v235 offset:2048
	ds_read_b128 v[62:65], v235 offset:3072
	ds_read_b128 v[146:149], v236
	ds_read_b128 v[150:153], v236 offset:1024
	ds_read_b128 v[154:157], v236 offset:2048
	ds_read_b128 v[158:161], v236 offset:3072
	s_add_u32 s14, s40, 0x80000
	s_addc_u32 s15, s41, 0
	s_mov_b32 m0, s43
	v_lshl_add_u64 v[250:251], s[14:15], 0, v[194:195]
	ds_read_b128 v[174:177], v226 offset:32768
	ds_read_b128 v[178:181], v226 offset:33792
	ds_read_b128 v[182:185], v226 offset:34816
	ds_read_b128 v[186:189], v226 offset:35840
	ds_read_b128 v[190:193], v226 offset:36864
	ds_read_b128 v[238:241], v226 offset:37888
	ds_read_b128 v[242:245], v226 offset:38912
	ds_read_b128 v[246:249], v226 offset:39936
	global_load_lds_dwordx4 v[250:251], off
	v_lshl_add_u64 v[250:251], s[14:15], 0, v[204:205]
	s_mov_b32 m0, s44
	s_nop 0
	global_load_lds_dwordx4 v[250:251], off
	s_waitcnt vmcnt(8)
	s_waitcnt lgkmcnt(0)
	s_barrier
	s_setprio 0
	s_waitcnt lgkmcnt(0)
	v_mfma_i32_16x16x64_i8 v[142:145], v[50:53], v[174:177], v[142:145]
	v_mfma_i32_16x16x64_i8 v[142:145], v[54:57], v[178:181], v[142:145]
	v_mfma_i32_16x16x64_i8 v[138:141], v[58:61], v[174:177], v[138:141]
	v_mfma_i32_16x16x64_i8 v[138:141], v[62:65], v[178:181], v[138:141]
	v_mfma_i32_16x16x64_i8 v[126:129], v[50:53], v[182:185], v[126:129]
	v_mfma_i32_16x16x64_i8 v[126:129], v[54:57], v[186:189], v[126:129]
	v_mfma_i32_16x16x64_i8 v[122:125], v[58:61], v[182:185], v[122:125]
	v_mfma_i32_16x16x64_i8 v[122:125], v[62:65], v[186:189], v[122:125]
	v_mfma_i32_16x16x64_i8 v[110:113], v[50:53], v[190:193], v[110:113]
	v_mfma_i32_16x16x64_i8 v[110:113], v[54:57], v[238:241], v[110:113]
	v_mfma_i32_16x16x64_i8 v[106:109], v[58:61], v[190:193], v[106:109]
	v_mfma_i32_16x16x64_i8 v[106:109], v[62:65], v[238:241], v[106:109]
	v_mfma_i32_16x16x64_i8 v[94:97], v[50:53], v[242:245], v[94:97]
	v_mfma_i32_16x16x64_i8 v[94:97], v[54:57], v[246:249], v[94:97]
	v_mfma_i32_16x16x64_i8 v[90:93], v[58:61], v[242:245], v[90:93]
	v_mfma_i32_16x16x64_i8 v[90:93], v[62:65], v[246:249], v[90:93]
	v_mfma_i32_16x16x64_i8 v[134:137], v[146:149], v[174:177], v[134:137]
	v_mfma_i32_16x16x64_i8 v[134:137], v[150:153], v[178:181], v[134:137]
	v_mfma_i32_16x16x64_i8 v[130:133], v[154:157], v[174:177], v[130:133]
	v_mfma_i32_16x16x64_i8 v[130:133], v[158:161], v[178:181], v[130:133]
	v_mfma_i32_16x16x64_i8 v[118:121], v[146:149], v[182:185], v[118:121]
	v_mfma_i32_16x16x64_i8 v[118:121], v[150:153], v[186:189], v[118:121]
	v_mfma_i32_16x16x64_i8 v[114:117], v[154:157], v[182:185], v[114:117]
	v_mfma_i32_16x16x64_i8 v[114:117], v[158:161], v[186:189], v[114:117]
	v_mfma_i32_16x16x64_i8 v[102:105], v[146:149], v[190:193], v[102:105]
	v_mfma_i32_16x16x64_i8 v[102:105], v[150:153], v[238:241], v[102:105]
	v_mfma_i32_16x16x64_i8 v[98:101], v[154:157], v[190:193], v[98:101]
	v_mfma_i32_16x16x64_i8 v[98:101], v[158:161], v[238:241], v[98:101]
	v_mfma_i32_16x16x64_i8 v[86:89], v[146:149], v[242:245], v[86:89]
	v_mfma_i32_16x16x64_i8 v[86:89], v[150:153], v[246:249], v[86:89]
	v_mfma_i32_16x16x64_i8 v[82:85], v[154:157], v[242:245], v[82:85]
	v_mfma_i32_16x16x64_i8 v[82:85], v[158:161], v[246:249], v[82:85]
	s_setprio 1
	s_barrier
	s_add_i32 s72, s72, s21
	s_add_i32 s73, s72, 0x2000
	v_lshl_add_u64 v[166:167], v[166:167], 0, s[6:7]
	s_mov_b32 m0, s72
	s_add_u32 s14, s38, 0x80080
	ds_read_b128 v[174:177], v226 offset:49152
	ds_read_b128 v[178:181], v226 offset:50176
	ds_read_b128 v[182:185], v226 offset:51200
	ds_read_b128 v[186:189], v226 offset:52224
	ds_read_b128 v[190:193], v226 offset:53248
	ds_read_b128 v[238:241], v226 offset:54272
	ds_read_b128 v[242:245], v226 offset:55296
	ds_read_b128 v[246:249], v226 offset:56320
	global_load_lds_dwordx4 v[166:167], off
	v_lshl_add_u64 v[166:167], v[168:169], 0, s[6:7]
	s_mov_b32 m0, s73
	s_addc_u32 s15, s39, 0
	s_add_i32 s74, s74, s21
	global_load_lds_dwordx4 v[166:167], off
	v_lshl_add_u64 v[166:167], s[14:15], 0, v[202:203]
	s_mov_b32 m0, s74
	s_add_i32 s75, s74, 0x2000
	global_load_lds_dwordx4 v[166:167], off
	v_lshl_add_u64 v[166:167], s[14:15], 0, v[206:207]
	s_mov_b32 m0, s75
	s_nop 0
	global_load_lds_dwordx4 v[166:167], off
	v_lshl_add_u64 v[166:167], v[170:171], 0, s[6:7]
	s_mov_b32 m0, s51
	s_nop 0
	global_load_lds_dwordx4 v[166:167], off
	v_lshl_add_u64 v[166:167], v[172:173], 0, s[6:7]
	s_mov_b32 m0, s53
	s_nop 0
	global_load_lds_dwordx4 v[166:167], off
	s_waitcnt vmcnt(8)
	s_waitcnt lgkmcnt(0)
	s_barrier
	s_setprio 0
	s_waitcnt lgkmcnt(0)
	v_mfma_i32_16x16x64_i8 v[78:81], v[50:53], v[174:177], v[78:81]
	v_mfma_i32_16x16x64_i8 v[78:81], v[54:57], v[178:181], v[78:81]
	v_mfma_i32_16x16x64_i8 v[74:77], v[58:61], v[174:177], v[74:77]
	v_mfma_i32_16x16x64_i8 v[74:77], v[62:65], v[178:181], v[74:77]
	v_mfma_i32_16x16x64_i8 v[46:49], v[50:53], v[182:185], v[46:49]
	v_mfma_i32_16x16x64_i8 v[46:49], v[54:57], v[186:189], v[46:49]
	v_mfma_i32_16x16x64_i8 v[42:45], v[58:61], v[182:185], v[42:45]
	v_mfma_i32_16x16x64_i8 v[42:45], v[62:65], v[186:189], v[42:45]
	v_mfma_i32_16x16x64_i8 v[30:33], v[50:53], v[190:193], v[30:33]
	v_mfma_i32_16x16x64_i8 v[30:33], v[54:57], v[238:241], v[30:33]
	v_mfma_i32_16x16x64_i8 v[26:29], v[58:61], v[190:193], v[26:29]
	v_mfma_i32_16x16x64_i8 v[26:29], v[62:65], v[238:241], v[26:29]
	v_mfma_i32_16x16x64_i8 v[14:17], v[50:53], v[242:245], v[14:17]
	v_mfma_i32_16x16x64_i8 v[14:17], v[54:57], v[246:249], v[14:17]
	v_mfma_i32_16x16x64_i8 v[10:13], v[58:61], v[242:245], v[10:13]
	v_mfma_i32_16x16x64_i8 v[10:13], v[62:65], v[246:249], v[10:13]
	v_mfma_i32_16x16x64_i8 v[70:73], v[146:149], v[174:177], v[70:73]
	v_mfma_i32_16x16x64_i8 v[70:73], v[150:153], v[178:181], v[70:73]
	v_mfma_i32_16x16x64_i8 v[66:69], v[154:157], v[174:177], v[66:69]
	v_mfma_i32_16x16x64_i8 v[66:69], v[158:161], v[178:181], v[66:69]
	v_mfma_i32_16x16x64_i8 v[38:41], v[146:149], v[182:185], v[38:41]
	v_mfma_i32_16x16x64_i8 v[38:41], v[150:153], v[186:189], v[38:41]
	v_mfma_i32_16x16x64_i8 v[34:37], v[154:157], v[182:185], v[34:37]
	v_mfma_i32_16x16x64_i8 v[34:37], v[158:161], v[186:189], v[34:37]
	v_mfma_i32_16x16x64_i8 v[22:25], v[146:149], v[190:193], v[22:25]
	v_mfma_i32_16x16x64_i8 v[22:25], v[150:153], v[238:241], v[22:25]
	v_mfma_i32_16x16x64_i8 v[18:21], v[154:157], v[190:193], v[18:21]
	v_mfma_i32_16x16x64_i8 v[18:21], v[158:161], v[238:241], v[18:21]
	v_mfma_i32_16x16x64_i8 v[6:9], v[146:149], v[242:245], v[6:9]
	v_mfma_i32_16x16x64_i8 v[6:9], v[150:153], v[246:249], v[6:9]
	v_mfma_i32_16x16x64_i8 v[2:5], v[154:157], v[242:245], v[2:5]
	v_mfma_i32_16x16x64_i8 v[2:5], v[158:161], v[246:249], v[2:5]
	s_setprio 1
	s_barrier
	s_add_i32 s3, s3, 2
	s_add_u32 s34, s34, 0x100
	s_addc_u32 s35, s35, 0
	s_cmp_gt_u32 s3, 29
	s_cbranch_scc0 .LBB0_734
	s_nop 15
	s_nop 15
	s_and_b64 vcc, exec, s[8:9]
	s_cbranch_vccz .LBB0_737
	s_barrier

.LBB0_740:
	ds_read_b128 v[158:161], v227
	ds_read_b128 v[154:157], v227 offset:1024
	ds_read_b128 v[150:153], v227 offset:2048
	ds_read_b128 v[146:149], v227 offset:3072
	ds_read_b128 v[62:65], v233
	ds_read_b128 v[58:61], v233 offset:1024
	ds_read_b128 v[54:57], v233 offset:2048
	ds_read_b128 v[50:53], v233 offset:3072
	s_add_u32 s36, s38, 0xfff80080
	s_addc_u32 s37, s39, -1
	s_cmp_eq_u32 s33, 28
	s_cselect_b32 s41, s1, s37
	s_cselect_b32 s40, s0, s36
	s_cselect_b32 s37, s15, s29
	s_cselect_b32 s36, s14, s25
	s_mov_b32 m0, s66
	v_lshl_add_u64 v[238:239], s[38:39], 0, v[208:209]
	ds_read_b128 v[162:165], v226
	ds_read_b128 v[166:169], v226 offset:1024
	ds_read_b128 v[170:173], v226 offset:2048
	ds_read_b128 v[174:177], v226 offset:3072
	ds_read_b128 v[178:181], v226 offset:4096
	ds_read_b128 v[182:185], v226 offset:5120
	ds_read_b128 v[186:189], v226 offset:6144
	ds_read_b128 v[190:193], v226 offset:7168
	global_load_lds_dwordx4 v[238:239], off
	v_lshl_add_u64 v[238:239], s[38:39], 0, v[212:213]
	s_mov_b32 m0, s67
	s_nop 0
	global_load_lds_dwordx4 v[238:239], off
	s_waitcnt vmcnt(8)
	s_waitcnt lgkmcnt(0)
	s_barrier
	s_setprio 0
	s_waitcnt lgkmcnt(0)
	v_mfma_i32_16x16x64_i8 v[142:145], v[158:161], v[162:165], v[142:145]
	v_mfma_i32_16x16x64_i8 v[142:145], v[154:157], v[166:169], v[142:145]
	v_mfma_i32_16x16x64_i8 v[138:141], v[150:153], v[162:165], v[138:141]
	v_mfma_i32_16x16x64_i8 v[138:141], v[146:149], v[166:169], v[138:141]
	v_mfma_i32_16x16x64_i8 v[126:129], v[158:161], v[170:173], v[126:129]
	v_mfma_i32_16x16x64_i8 v[126:129], v[154:157], v[174:177], v[126:129]
	v_mfma_i32_16x16x64_i8 v[122:125], v[150:153], v[170:173], v[122:125]
	v_mfma_i32_16x16x64_i8 v[122:125], v[146:149], v[174:177], v[122:125]
	v_mfma_i32_16x16x64_i8 v[110:113], v[158:161], v[178:181], v[110:113]
	v_mfma_i32_16x16x64_i8 v[110:113], v[154:157], v[182:185], v[110:113]
	v_mfma_i32_16x16x64_i8 v[106:109], v[150:153], v[178:181], v[106:109]
	v_mfma_i32_16x16x64_i8 v[106:109], v[146:149], v[182:185], v[106:109]
	v_mfma_i32_16x16x64_i8 v[94:97], v[158:161], v[186:189], v[94:97]
	v_mfma_i32_16x16x64_i8 v[94:97], v[154:157], v[190:193], v[94:97]
	v_mfma_i32_16x16x64_i8 v[90:93], v[150:153], v[186:189], v[90:93]
	v_mfma_i32_16x16x64_i8 v[90:93], v[146:149], v[190:193], v[90:93]
	v_mfma_i32_16x16x64_i8 v[134:137], v[62:65], v[162:165], v[134:137]
	v_mfma_i32_16x16x64_i8 v[134:137], v[58:61], v[166:169], v[134:137]
	v_mfma_i32_16x16x64_i8 v[130:133], v[54:57], v[162:165], v[130:133]
	v_mfma_i32_16x16x64_i8 v[130:133], v[50:53], v[166:169], v[130:133]
	v_mfma_i32_16x16x64_i8 v[118:121], v[62:65], v[170:173], v[118:121]
	v_mfma_i32_16x16x64_i8 v[118:121], v[58:61], v[174:177], v[118:121]
	v_mfma_i32_16x16x64_i8 v[114:117], v[54:57], v[170:173], v[114:117]
	v_mfma_i32_16x16x64_i8 v[114:117], v[50:53], v[174:177], v[114:117]
	v_mfma_i32_16x16x64_i8 v[102:105], v[62:65], v[178:181], v[102:105]
	v_mfma_i32_16x16x64_i8 v[102:105], v[58:61], v[182:185], v[102:105]
	v_mfma_i32_16x16x64_i8 v[98:101], v[54:57], v[178:181], v[98:101]
	v_mfma_i32_16x16x64_i8 v[98:101], v[50:53], v[182:185], v[98:101]
	v_mfma_i32_16x16x64_i8 v[86:89], v[62:65], v[186:189], v[86:89]
	v_mfma_i32_16x16x64_i8 v[86:89], v[58:61], v[190:193], v[86:89]
	v_mfma_i32_16x16x64_i8 v[82:85], v[54:57], v[186:189], v[82:85]
	v_mfma_i32_16x16x64_i8 v[82:85], v[50:53], v[190:193], v[82:85]
	s_setprio 1
	s_barrier
	s_mov_b32 m0, s68
	v_lshl_add_u64 v[162:163], s[36:37], 0, v[202:203]
	s_add_u32 s80, s36, 0x80000
	ds_read_b128 v[170:173], v226 offset:16384
	ds_read_b128 v[174:177], v226 offset:17408
	ds_read_b128 v[178:181], v226 offset:18432
	ds_read_b128 v[182:185], v226 offset:19456
	ds_read_b128 v[186:189], v226 offset:20480
	ds_read_b128 v[190:193], v226 offset:21504
	ds_read_b128 v[238:241], v226 offset:22528
	ds_read_b128 v[242:245], v226 offset:23552
	global_load_lds_dwordx4 v[162:163], off
	v_lshl_add_u64 v[164:165], s[36:37], 0, v[206:207]
	s_mov_b32 m0, s69
	s_addc_u32 s81, s37, 0
	global_load_lds_dwordx4 v[164:165], off
	v_lshl_add_u64 v[166:167], s[80:81], 0, v[202:203]
	s_mov_b32 m0, s70
	v_lshl_add_u64 v[168:169], s[40:41], 0, v[204:205]
	global_load_lds_dwordx4 v[166:167], off
	v_lshl_add_u64 v[166:167], s[80:81], 0, v[206:207]
	s_mov_b32 m0, s71
	s_nop 0
	global_load_lds_dwordx4 v[166:167], off
	v_lshl_add_u64 v[166:167], s[40:41], 0, v[194:195]
	s_mov_b32 m0, s23
	s_nop 0
	global_load_lds_dwordx4 v[166:167], off
	s_mov_b32 m0, s42
	s_nop 0
	global_load_lds_dwordx4 v[168:169], off
	s_waitcnt vmcnt(8)
	s_waitcnt lgkmcnt(0)
	s_barrier
	s_setprio 0
	s_waitcnt lgkmcnt(0)
	v_mfma_i32_16x16x64_i8 v[78:81], v[158:161], v[170:173], v[78:81]
	v_mfma_i32_16x16x64_i8 v[78:81], v[154:157], v[174:177], v[78:81]
	v_mfma_i32_16x16x64_i8 v[74:77], v[150:153], v[170:173], v[74:77]
	v_mfma_i32_16x16x64_i8 v[74:77], v[146:149], v[174:177], v[74:77]
	v_mfma_i32_16x16x64_i8 v[46:49], v[158:161], v[178:181], v[46:49]
	v_mfma_i32_16x16x64_i8 v[46:49], v[154:157], v[182:185], v[46:49]
	v_mfma_i32_16x16x64_i8 v[42:45], v[150:153], v[178:181], v[42:45]
	v_mfma_i32_16x16x64_i8 v[42:45], v[146:149], v[182:185], v[42:45]
	v_mfma_i32_16x16x64_i8 v[30:33], v[158:161], v[186:189], v[30:33]
	v_mfma_i32_16x16x64_i8 v[30:33], v[154:157], v[190:193], v[30:33]
	v_mfma_i32_16x16x64_i8 v[26:29], v[150:153], v[186:189], v[26:29]
	v_mfma_i32_16x16x64_i8 v[26:29], v[146:149], v[190:193], v[26:29]
	v_mfma_i32_16x16x64_i8 v[14:17], v[158:161], v[238:241], v[14:17]
	v_mfma_i32_16x16x64_i8 v[14:17], v[154:157], v[242:245], v[14:17]
	v_mfma_i32_16x16x64_i8 v[10:13], v[150:153], v[238:241], v[10:13]
	v_mfma_i32_16x16x64_i8 v[10:13], v[146:149], v[242:245], v[10:13]
	v_mfma_i32_16x16x64_i8 v[70:73], v[62:65], v[170:173], v[70:73]
	v_mfma_i32_16x16x64_i8 v[70:73], v[58:61], v[174:177], v[70:73]
	v_mfma_i32_16x16x64_i8 v[66:69], v[54:57], v[170:173], v[66:69]
	v_mfma_i32_16x16x64_i8 v[66:69], v[50:53], v[174:177], v[66:69]
	v_mfma_i32_16x16x64_i8 v[38:41], v[62:65], v[178:181], v[38:41]
	v_mfma_i32_16x16x64_i8 v[38:41], v[58:61], v[182:185], v[38:41]
	v_mfma_i32_16x16x64_i8 v[34:37], v[54:57], v[178:181], v[34:37]
	v_mfma_i32_16x16x64_i8 v[34:37], v[50:53], v[182:185], v[34:37]
	v_mfma_i32_16x16x64_i8 v[22:25], v[62:65], v[186:189], v[22:25]
	v_mfma_i32_16x16x64_i8 v[22:25], v[58:61], v[190:193], v[22:25]
	v_mfma_i32_16x16x64_i8 v[18:21], v[54:57], v[186:189], v[18:21]
	v_mfma_i32_16x16x64_i8 v[18:21], v[50:53], v[190:193], v[18:21]
	v_mfma_i32_16x16x64_i8 v[6:9], v[62:65], v[238:241], v[6:9]
	v_mfma_i32_16x16x64_i8 v[6:9], v[58:61], v[242:245], v[6:9]
	v_mfma_i32_16x16x64_i8 v[2:5], v[54:57], v[238:241], v[2:5]
	v_mfma_i32_16x16x64_i8 v[2:5], v[50:53], v[242:245], v[2:5]
	s_setprio 1
	s_barrier
	ds_read_b128 v[50:53], v235
	ds_read_b128 v[54:57], v235 offset:1024
	ds_read_b128 v[58:61], v235 offset:2048
	ds_read_b128 v[62:65], v235 offset:3072
	ds_read_b128 v[146:149], v236
	ds_read_b128 v[150:153], v236 offset:1024
	ds_read_b128 v[154:157], v236 offset:2048
	ds_read_b128 v[158:161], v236 offset:3072
	s_add_u32 s40, s40, 0x80000
	s_addc_u32 s41, s41, 0
	s_mov_b32 m0, s43
	v_lshl_add_u64 v[246:247], s[40:41], 0, v[194:195]
	ds_read_b128 v[170:173], v226 offset:32768
	ds_read_b128 v[174:177], v226 offset:33792
	ds_read_b128 v[178:181], v226 offset:34816
	ds_read_b128 v[182:185], v226 offset:35840
	ds_read_b128 v[186:189], v226 offset:36864
	ds_read_b128 v[190:193], v226 offset:37888
	ds_read_b128 v[238:241], v226 offset:38912
	ds_read_b128 v[242:245], v226 offset:39936
	global_load_lds_dwordx4 v[246:247], off
	v_lshl_add_u64 v[246:247], s[40:41], 0, v[204:205]
	s_mov_b32 m0, s44
	s_nop 0
	global_load_lds_dwordx4 v[246:247], off
	s_waitcnt vmcnt(8)
	s_waitcnt lgkmcnt(0)
	s_barrier
	s_setprio 0
	s_waitcnt lgkmcnt(0)
	v_mfma_i32_16x16x64_i8 v[142:145], v[50:53], v[170:173], v[142:145]
	v_mfma_i32_16x16x64_i8 v[142:145], v[54:57], v[174:177], v[142:145]
	v_mfma_i32_16x16x64_i8 v[138:141], v[58:61], v[170:173], v[138:141]
	v_mfma_i32_16x16x64_i8 v[138:141], v[62:65], v[174:177], v[138:141]
	v_mfma_i32_16x16x64_i8 v[126:129], v[50:53], v[178:181], v[126:129]
	v_mfma_i32_16x16x64_i8 v[126:129], v[54:57], v[182:185], v[126:129]
	v_mfma_i32_16x16x64_i8 v[122:125], v[58:61], v[178:181], v[122:125]
	v_mfma_i32_16x16x64_i8 v[122:125], v[62:65], v[182:185], v[122:125]
	v_mfma_i32_16x16x64_i8 v[110:113], v[50:53], v[186:189], v[110:113]
	v_mfma_i32_16x16x64_i8 v[110:113], v[54:57], v[190:193], v[110:113]
	v_mfma_i32_16x16x64_i8 v[106:109], v[58:61], v[186:189], v[106:109]
	v_mfma_i32_16x16x64_i8 v[106:109], v[62:65], v[190:193], v[106:109]
	v_mfma_i32_16x16x64_i8 v[94:97], v[50:53], v[238:241], v[94:97]
	v_mfma_i32_16x16x64_i8 v[94:97], v[54:57], v[242:245], v[94:97]
	v_mfma_i32_16x16x64_i8 v[90:93], v[58:61], v[238:241], v[90:93]
	v_mfma_i32_16x16x64_i8 v[90:93], v[62:65], v[242:245], v[90:93]
	v_mfma_i32_16x16x64_i8 v[134:137], v[146:149], v[170:173], v[134:137]
	v_mfma_i32_16x16x64_i8 v[134:137], v[150:153], v[174:177], v[134:137]
	v_mfma_i32_16x16x64_i8 v[130:133], v[154:157], v[170:173], v[130:133]
	v_mfma_i32_16x16x64_i8 v[130:133], v[158:161], v[174:177], v[130:133]
	v_mfma_i32_16x16x64_i8 v[118:121], v[146:149], v[178:181], v[118:121]
	v_mfma_i32_16x16x64_i8 v[118:121], v[150:153], v[182:185], v[118:121]
	v_mfma_i32_16x16x64_i8 v[114:117], v[154:157], v[178:181], v[114:117]
	v_mfma_i32_16x16x64_i8 v[114:117], v[158:161], v[182:185], v[114:117]
	v_mfma_i32_16x16x64_i8 v[102:105], v[146:149], v[186:189], v[102:105]
	v_mfma_i32_16x16x64_i8 v[102:105], v[150:153], v[190:193], v[102:105]
	v_mfma_i32_16x16x64_i8 v[98:101], v[154:157], v[186:189], v[98:101]
	v_mfma_i32_16x16x64_i8 v[98:101], v[158:161], v[190:193], v[98:101]
	v_mfma_i32_16x16x64_i8 v[86:89], v[146:149], v[238:241], v[86:89]
	v_mfma_i32_16x16x64_i8 v[86:89], v[150:153], v[242:245], v[86:89]
	v_mfma_i32_16x16x64_i8 v[82:85], v[154:157], v[238:241], v[82:85]
	v_mfma_i32_16x16x64_i8 v[82:85], v[158:161], v[242:245], v[82:85]
	s_setprio 1
	s_barrier
	s_mov_b32 m0, s72
	v_lshl_add_u64 v[162:163], v[162:163], 0, s[6:7]
	s_add_u32 s36, s36, 0x80080
	ds_read_b128 v[170:173], v226 offset:49152
	ds_read_b128 v[174:177], v226 offset:50176
	ds_read_b128 v[178:181], v226 offset:51200
	ds_read_b128 v[182:185], v226 offset:52224
	ds_read_b128 v[186:189], v226 offset:53248
	ds_read_b128 v[190:193], v226 offset:54272
	ds_read_b128 v[238:241], v226 offset:55296
	ds_read_b128 v[242:245], v226 offset:56320
	global_load_lds_dwordx4 v[162:163], off
	v_lshl_add_u64 v[162:163], v[164:165], 0, s[6:7]
	s_mov_b32 m0, s73
	s_addc_u32 s37, s37, 0
	global_load_lds_dwordx4 v[162:163], off
	v_lshl_add_u64 v[162:163], s[36:37], 0, v[202:203]
	s_mov_b32 m0, s74
	s_nop 0
	global_load_lds_dwordx4 v[162:163], off
	v_lshl_add_u64 v[162:163], s[36:37], 0, v[206:207]
	s_mov_b32 m0, s75
	s_nop 0
	global_load_lds_dwordx4 v[162:163], off
	v_lshl_add_u64 v[162:163], v[166:167], 0, s[6:7]
	s_mov_b32 m0, s51
	s_nop 0
	global_load_lds_dwordx4 v[162:163], off
	v_lshl_add_u64 v[162:163], v[168:169], 0, s[6:7]
	s_mov_b32 m0, s53
	s_nop 0
	global_load_lds_dwordx4 v[162:163], off
	s_waitcnt vmcnt(8)
	s_waitcnt lgkmcnt(0)
	s_barrier
	s_setprio 0
	s_waitcnt lgkmcnt(0)
	v_mfma_i32_16x16x64_i8 v[78:81], v[50:53], v[170:173], v[78:81]
	v_mfma_i32_16x16x64_i8 v[78:81], v[54:57], v[174:177], v[78:81]
	v_mfma_i32_16x16x64_i8 v[74:77], v[58:61], v[170:173], v[74:77]
	v_mfma_i32_16x16x64_i8 v[74:77], v[62:65], v[174:177], v[74:77]
	v_mfma_i32_16x16x64_i8 v[46:49], v[50:53], v[178:181], v[46:49]
	v_mfma_i32_16x16x64_i8 v[46:49], v[54:57], v[182:185], v[46:49]
	v_mfma_i32_16x16x64_i8 v[42:45], v[58:61], v[178:181], v[42:45]
	v_mfma_i32_16x16x64_i8 v[42:45], v[62:65], v[182:185], v[42:45]
	v_mfma_i32_16x16x64_i8 v[30:33], v[50:53], v[186:189], v[30:33]
	v_mfma_i32_16x16x64_i8 v[30:33], v[54:57], v[190:193], v[30:33]
	v_mfma_i32_16x16x64_i8 v[26:29], v[58:61], v[186:189], v[26:29]
	v_mfma_i32_16x16x64_i8 v[26:29], v[62:65], v[190:193], v[26:29]
	v_mfma_i32_16x16x64_i8 v[14:17], v[50:53], v[238:241], v[14:17]
	v_mfma_i32_16x16x64_i8 v[14:17], v[54:57], v[242:245], v[14:17]
	v_mfma_i32_16x16x64_i8 v[10:13], v[58:61], v[238:241], v[10:13]
	v_mfma_i32_16x16x64_i8 v[10:13], v[62:65], v[242:245], v[10:13]
	v_mfma_i32_16x16x64_i8 v[70:73], v[146:149], v[170:173], v[70:73]
	v_mfma_i32_16x16x64_i8 v[70:73], v[150:153], v[174:177], v[70:73]
	v_mfma_i32_16x16x64_i8 v[66:69], v[154:157], v[170:173], v[66:69]
	v_mfma_i32_16x16x64_i8 v[66:69], v[158:161], v[174:177], v[66:69]
	v_mfma_i32_16x16x64_i8 v[38:41], v[146:149], v[178:181], v[38:41]
	v_mfma_i32_16x16x64_i8 v[38:41], v[150:153], v[182:185], v[38:41]
	v_mfma_i32_16x16x64_i8 v[34:37], v[154:157], v[178:181], v[34:37]
	v_mfma_i32_16x16x64_i8 v[34:37], v[158:161], v[182:185], v[34:37]
	v_mfma_i32_16x16x64_i8 v[22:25], v[146:149], v[186:189], v[22:25]
	v_mfma_i32_16x16x64_i8 v[22:25], v[150:153], v[190:193], v[22:25]
	v_mfma_i32_16x16x64_i8 v[18:21], v[154:157], v[186:189], v[18:21]
	v_mfma_i32_16x16x64_i8 v[18:21], v[158:161], v[190:193], v[18:21]
	v_mfma_i32_16x16x64_i8 v[6:9], v[146:149], v[238:241], v[6:9]
	v_mfma_i32_16x16x64_i8 v[6:9], v[150:153], v[242:245], v[6:9]
	v_mfma_i32_16x16x64_i8 v[2:5], v[154:157], v[238:241], v[2:5]
	v_mfma_i32_16x16x64_i8 v[2:5], v[158:161], v[242:245], v[2:5]
	s_setprio 1
	s_barrier
	s_add_i32 s33, s33, 2
	s_add_u32 s38, s38, 0x100
	s_addc_u32 s39, s39, 0
	s_add_u32 s25, s25, 0x100
	s_addc_u32 s29, s29, 0
	s_cmp_gt_u32 s33, 29
	s_cbranch_scc0 .LBB0_740
	s_nop 15
	s_nop 15
	s_and_b64 vcc, exec, s[8:9]
	s_cbranch_vccz .LBB0_743
	s_barrier

.LBB0_746:
	ds_read_b128 v[158:161], v227
	ds_read_b128 v[154:157], v227 offset:1024
	ds_read_b128 v[150:153], v227 offset:2048
	ds_read_b128 v[146:149], v227 offset:3072
	ds_read_b128 v[142:145], v233
	ds_read_b128 v[138:141], v233 offset:1024
	ds_read_b128 v[134:137], v233 offset:2048
	ds_read_b128 v[130:133], v233 offset:3072
	s_add_u32 s38, s29, s36
	s_addc_u32 s39, s33, s37
	s_add_u32 s38, s38, 0x3d000100
	s_addc_u32 s39, s39, 0
	s_add_u32 s81, s25, s36
	s_addc_u32 s82, s79, s37
	s_cmpk_eq_i32 s36, 0x700
	s_cselect_b32 s41, s1, s39
	s_cselect_b32 s40, s0, s38
	s_cselect_b32 s39, s15, s82
	s_cselect_b32 s38, s14, s81
	s_mov_b32 m0, s66
	v_lshl_add_u64 v[242:243], v[162:163], 0, s[36:37]
	ds_read_b128 v[166:169], v226
	ds_read_b128 v[170:173], v226 offset:1024
	ds_read_b128 v[174:177], v226 offset:2048
	ds_read_b128 v[178:181], v226 offset:3072
	ds_read_b128 v[182:185], v226 offset:4096
	ds_read_b128 v[186:189], v226 offset:5120
	ds_read_b128 v[190:193], v226 offset:6144
	ds_read_b128 v[238:241], v226 offset:7168
	global_load_lds_dwordx4 v[242:243], off
	v_lshl_add_u64 v[242:243], v[164:165], 0, s[36:37]
	s_mov_b32 m0, s67
	s_nop 0
	global_load_lds_dwordx4 v[242:243], off
	s_waitcnt vmcnt(8)
	s_waitcnt lgkmcnt(0)
	s_barrier
	s_setprio 0
	s_waitcnt lgkmcnt(0)
	v_mfma_i32_16x16x64_i8 v[30:33], v[158:161], v[166:169], v[30:33]
	v_mfma_i32_16x16x64_i8 v[30:33], v[154:157], v[170:173], v[30:33]
	v_mfma_i32_16x16x64_i8 v[26:29], v[150:153], v[166:169], v[26:29]
	v_mfma_i32_16x16x64_i8 v[26:29], v[146:149], v[170:173], v[26:29]
	v_mfma_i32_16x16x64_i8 v[46:49], v[158:161], v[174:177], v[46:49]
	v_mfma_i32_16x16x64_i8 v[46:49], v[154:157], v[178:181], v[46:49]
	v_mfma_i32_16x16x64_i8 v[42:45], v[150:153], v[174:177], v[42:45]
	v_mfma_i32_16x16x64_i8 v[42:45], v[146:149], v[178:181], v[42:45]
	v_mfma_i32_16x16x64_i8 v[74:77], v[158:161], v[182:185], v[74:77]
	v_mfma_i32_16x16x64_i8 v[74:77], v[154:157], v[186:189], v[74:77]
	v_mfma_i32_16x16x64_i8 v[70:73], v[150:153], v[182:185], v[70:73]
	v_mfma_i32_16x16x64_i8 v[70:73], v[146:149], v[186:189], v[70:73]
	v_mfma_i32_16x16x64_i8 v[94:97], v[158:161], v[190:193], v[94:97]
	v_mfma_i32_16x16x64_i8 v[94:97], v[154:157], v[238:241], v[94:97]
	v_mfma_i32_16x16x64_i8 v[90:93], v[150:153], v[190:193], v[90:93]
	v_mfma_i32_16x16x64_i8 v[90:93], v[146:149], v[238:241], v[90:93]
	v_mfma_i32_16x16x64_i8 v[38:41], v[142:145], v[166:169], v[38:41]
	v_mfma_i32_16x16x64_i8 v[38:41], v[138:141], v[170:173], v[38:41]
	v_mfma_i32_16x16x64_i8 v[34:37], v[134:137], v[166:169], v[34:37]
	v_mfma_i32_16x16x64_i8 v[34:37], v[130:133], v[170:173], v[34:37]
	v_mfma_i32_16x16x64_i8 v[58:61], v[142:145], v[174:177], v[58:61]
	v_mfma_i32_16x16x64_i8 v[58:61], v[138:141], v[178:181], v[58:61]
	v_mfma_i32_16x16x64_i8 v[54:57], v[134:137], v[174:177], v[54:57]
	v_mfma_i32_16x16x64_i8 v[54:57], v[130:133], v[178:181], v[54:57]
	v_mfma_i32_16x16x64_i8 v[86:89], v[142:145], v[182:185], v[86:89]
	v_mfma_i32_16x16x64_i8 v[86:89], v[138:141], v[186:189], v[86:89]
	v_mfma_i32_16x16x64_i8 v[82:85], v[134:137], v[182:185], v[82:85]
	v_mfma_i32_16x16x64_i8 v[82:85], v[130:133], v[186:189], v[82:85]
	v_mfma_i32_16x16x64_i8 v[102:105], v[142:145], v[190:193], v[102:105]
	v_mfma_i32_16x16x64_i8 v[102:105], v[138:141], v[238:241], v[102:105]
	v_mfma_i32_16x16x64_i8 v[98:101], v[134:137], v[190:193], v[98:101]
	v_mfma_i32_16x16x64_i8 v[98:101], v[130:133], v[238:241], v[98:101]
	s_setprio 1
	s_barrier
	s_mov_b32 m0, s68
	v_lshl_add_u64 v[166:167], s[38:39], 0, v[202:203]
	s_add_u32 s82, s38, 0x80000
	ds_read_b128 v[174:177], v226 offset:16384
	ds_read_b128 v[178:181], v226 offset:17408
	ds_read_b128 v[182:185], v226 offset:18432
	ds_read_b128 v[186:189], v226 offset:19456
	ds_read_b128 v[190:193], v226 offset:20480
	ds_read_b128 v[238:241], v226 offset:21504
	ds_read_b128 v[242:245], v226 offset:22528
	ds_read_b128 v[246:249], v226 offset:23552
	global_load_lds_dwordx4 v[166:167], off
	v_lshl_add_u64 v[168:169], s[38:39], 0, v[206:207]
	s_mov_b32 m0, s69
	s_addc_u32 s83, s39, 0
	global_load_lds_dwordx4 v[168:169], off
	v_lshl_add_u64 v[170:171], s[82:83], 0, v[202:203]
	s_mov_b32 m0, s70
	v_lshl_add_u64 v[172:173], s[40:41], 0, v[204:205]
	global_load_lds_dwordx4 v[170:171], off
	v_lshl_add_u64 v[170:171], s[82:83], 0, v[206:207]
	s_mov_b32 m0, s71
	s_nop 0
	global_load_lds_dwordx4 v[170:171], off
	v_lshl_add_u64 v[170:171], s[40:41], 0, v[194:195]
	s_mov_b32 m0, s23
	s_nop 0
	global_load_lds_dwordx4 v[170:171], off
	s_mov_b32 m0, s42
	s_nop 0
	global_load_lds_dwordx4 v[172:173], off
	s_waitcnt vmcnt(8)
	s_waitcnt lgkmcnt(0)
	s_barrier
	s_setprio 0
	s_waitcnt lgkmcnt(0)
	v_mfma_i32_16x16x64_i8 v[110:113], v[158:161], v[174:177], v[110:113]
	v_mfma_i32_16x16x64_i8 v[110:113], v[154:157], v[178:181], v[110:113]
	v_mfma_i32_16x16x64_i8 v[106:109], v[150:153], v[174:177], v[106:109]
	v_mfma_i32_16x16x64_i8 v[106:109], v[146:149], v[178:181], v[106:109]
	v_mfma_i32_16x16x64_i8 v[126:129], v[158:161], v[182:185], v[126:129]
	v_mfma_i32_16x16x64_i8 v[126:129], v[154:157], v[186:189], v[126:129]
	v_mfma_i32_16x16x64_i8 v[118:121], v[150:153], v[182:185], v[118:121]
	v_mfma_i32_16x16x64_i8 v[118:121], v[146:149], v[186:189], v[118:121]
	v_mfma_i32_16x16x64_i8 v[62:65], v[158:161], v[190:193], v[62:65]
	v_mfma_i32_16x16x64_i8 v[62:65], v[154:157], v[238:241], v[62:65]
	v_mfma_i32_16x16x64_i8 v[50:53], v[150:153], v[190:193], v[50:53]
	v_mfma_i32_16x16x64_i8 v[50:53], v[146:149], v[238:241], v[50:53]
	v_mfma_i32_16x16x64_i8 v[14:17], v[158:161], v[242:245], v[14:17]
	v_mfma_i32_16x16x64_i8 v[14:17], v[154:157], v[246:249], v[14:17]
	v_mfma_i32_16x16x64_i8 v[10:13], v[150:153], v[242:245], v[10:13]
	v_mfma_i32_16x16x64_i8 v[10:13], v[146:149], v[246:249], v[10:13]
	v_mfma_i32_16x16x64_i8 v[122:125], v[142:145], v[174:177], v[122:125]
	v_mfma_i32_16x16x64_i8 v[122:125], v[138:141], v[178:181], v[122:125]
	v_mfma_i32_16x16x64_i8 v[114:117], v[134:137], v[174:177], v[114:117]
	v_mfma_i32_16x16x64_i8 v[114:117], v[130:133], v[178:181], v[114:117]
	v_mfma_i32_16x16x64_i8 v[78:81], v[142:145], v[182:185], v[78:81]
	v_mfma_i32_16x16x64_i8 v[78:81], v[138:141], v[186:189], v[78:81]
	v_mfma_i32_16x16x64_i8 v[66:69], v[134:137], v[182:185], v[66:69]
	v_mfma_i32_16x16x64_i8 v[66:69], v[130:133], v[186:189], v[66:69]
	v_mfma_i32_16x16x64_i8 v[22:25], v[142:145], v[190:193], v[22:25]
	v_mfma_i32_16x16x64_i8 v[22:25], v[138:141], v[238:241], v[22:25]
	v_mfma_i32_16x16x64_i8 v[18:21], v[134:137], v[190:193], v[18:21]
	v_mfma_i32_16x16x64_i8 v[18:21], v[130:133], v[238:241], v[18:21]
	v_mfma_i32_16x16x64_i8 v[6:9], v[142:145], v[242:245], v[6:9]
	v_mfma_i32_16x16x64_i8 v[6:9], v[138:141], v[246:249], v[6:9]
	v_mfma_i32_16x16x64_i8 v[2:5], v[134:137], v[242:245], v[2:5]
	v_mfma_i32_16x16x64_i8 v[2:5], v[130:133], v[246:249], v[2:5]
	s_setprio 1
	s_barrier
	ds_read_b128 v[130:133], v235
	ds_read_b128 v[134:137], v235 offset:1024
	ds_read_b128 v[138:141], v235 offset:2048
	ds_read_b128 v[142:145], v235 offset:3072
	ds_read_b128 v[146:149], v236
	ds_read_b128 v[150:153], v236 offset:1024
	ds_read_b128 v[154:157], v236 offset:2048
	ds_read_b128 v[158:161], v236 offset:3072
	s_add_u32 s40, s40, 0x80000
	s_addc_u32 s41, s41, 0
	s_mov_b32 m0, s43
	v_lshl_add_u64 v[250:251], s[40:41], 0, v[194:195]
	ds_read_b128 v[174:177], v226 offset:32768
	ds_read_b128 v[178:181], v226 offset:33792
	ds_read_b128 v[182:185], v226 offset:34816
	ds_read_b128 v[186:189], v226 offset:35840
	ds_read_b128 v[190:193], v226 offset:36864
	ds_read_b128 v[238:241], v226 offset:37888
	ds_read_b128 v[242:245], v226 offset:38912
	ds_read_b128 v[246:249], v226 offset:39936
	global_load_lds_dwordx4 v[250:251], off
	v_lshl_add_u64 v[250:251], s[40:41], 0, v[204:205]
	s_mov_b32 m0, s44
	s_nop 0
	global_load_lds_dwordx4 v[250:251], off
	s_waitcnt vmcnt(8)
	s_waitcnt lgkmcnt(0)
	s_barrier
	s_setprio 0
	s_waitcnt lgkmcnt(0)
	v_mfma_i32_16x16x64_i8 v[30:33], v[130:133], v[174:177], v[30:33]
	v_mfma_i32_16x16x64_i8 v[30:33], v[134:137], v[178:181], v[30:33]
	v_mfma_i32_16x16x64_i8 v[26:29], v[138:141], v[174:177], v[26:29]
	v_mfma_i32_16x16x64_i8 v[26:29], v[142:145], v[178:181], v[26:29]
	v_mfma_i32_16x16x64_i8 v[46:49], v[130:133], v[182:185], v[46:49]
	v_mfma_i32_16x16x64_i8 v[46:49], v[134:137], v[186:189], v[46:49]
	v_mfma_i32_16x16x64_i8 v[42:45], v[138:141], v[182:185], v[42:45]
	v_mfma_i32_16x16x64_i8 v[42:45], v[142:145], v[186:189], v[42:45]
	v_mfma_i32_16x16x64_i8 v[74:77], v[130:133], v[190:193], v[74:77]
	v_mfma_i32_16x16x64_i8 v[74:77], v[134:137], v[238:241], v[74:77]
	v_mfma_i32_16x16x64_i8 v[70:73], v[138:141], v[190:193], v[70:73]
	v_mfma_i32_16x16x64_i8 v[70:73], v[142:145], v[238:241], v[70:73]
	v_mfma_i32_16x16x64_i8 v[94:97], v[130:133], v[242:245], v[94:97]
	v_mfma_i32_16x16x64_i8 v[94:97], v[134:137], v[246:249], v[94:97]
	v_mfma_i32_16x16x64_i8 v[90:93], v[138:141], v[242:245], v[90:93]
	v_mfma_i32_16x16x64_i8 v[90:93], v[142:145], v[246:249], v[90:93]
	v_mfma_i32_16x16x64_i8 v[38:41], v[146:149], v[174:177], v[38:41]
	v_mfma_i32_16x16x64_i8 v[38:41], v[150:153], v[178:181], v[38:41]
	v_mfma_i32_16x16x64_i8 v[34:37], v[154:157], v[174:177], v[34:37]
	v_mfma_i32_16x16x64_i8 v[34:37], v[158:161], v[178:181], v[34:37]
	v_mfma_i32_16x16x64_i8 v[58:61], v[146:149], v[182:185], v[58:61]
	v_mfma_i32_16x16x64_i8 v[58:61], v[150:153], v[186:189], v[58:61]
	v_mfma_i32_16x16x64_i8 v[54:57], v[154:157], v[182:185], v[54:57]
	v_mfma_i32_16x16x64_i8 v[54:57], v[158:161], v[186:189], v[54:57]
	v_mfma_i32_16x16x64_i8 v[86:89], v[146:149], v[190:193], v[86:89]
	v_mfma_i32_16x16x64_i8 v[86:89], v[150:153], v[238:241], v[86:89]
	v_mfma_i32_16x16x64_i8 v[82:85], v[154:157], v[190:193], v[82:85]
	v_mfma_i32_16x16x64_i8 v[82:85], v[158:161], v[238:241], v[82:85]
	v_mfma_i32_16x16x64_i8 v[102:105], v[146:149], v[242:245], v[102:105]
	v_mfma_i32_16x16x64_i8 v[102:105], v[150:153], v[246:249], v[102:105]
	v_mfma_i32_16x16x64_i8 v[98:101], v[154:157], v[242:245], v[98:101]
	v_mfma_i32_16x16x64_i8 v[98:101], v[158:161], v[246:249], v[98:101]
	s_setprio 1
	s_barrier
	s_mov_b32 m0, s72
	v_lshl_add_u64 v[166:167], v[166:167], 0, s[6:7]
	s_add_u32 s38, s38, 0x80080
	ds_read_b128 v[174:177], v226 offset:49152
	ds_read_b128 v[178:181], v226 offset:50176
	ds_read_b128 v[182:185], v226 offset:51200
	ds_read_b128 v[186:189], v226 offset:52224
	ds_read_b128 v[190:193], v226 offset:53248
	ds_read_b128 v[238:241], v226 offset:54272
	ds_read_b128 v[242:245], v226 offset:55296
	ds_read_b128 v[246:249], v226 offset:56320
	global_load_lds_dwordx4 v[166:167], off
	v_lshl_add_u64 v[166:167], v[168:169], 0, s[6:7]
	s_mov_b32 m0, s73
	s_addc_u32 s39, s39, 0
	global_load_lds_dwordx4 v[166:167], off
	v_lshl_add_u64 v[166:167], s[38:39], 0, v[202:203]
	s_mov_b32 m0, s74
	s_nop 0
	global_load_lds_dwordx4 v[166:167], off
	v_lshl_add_u64 v[166:167], s[38:39], 0, v[206:207]
	s_mov_b32 m0, s75
	s_nop 0
	global_load_lds_dwordx4 v[166:167], off
	v_lshl_add_u64 v[166:167], v[170:171], 0, s[6:7]
	s_mov_b32 m0, s51
	s_nop 0
	global_load_lds_dwordx4 v[166:167], off
	v_lshl_add_u64 v[166:167], v[172:173], 0, s[6:7]
	s_mov_b32 m0, s53
	s_nop 0
	global_load_lds_dwordx4 v[166:167], off
	s_waitcnt vmcnt(8)
	s_waitcnt lgkmcnt(0)
	s_barrier
	s_setprio 0
	s_waitcnt lgkmcnt(0)
	v_mfma_i32_16x16x64_i8 v[110:113], v[130:133], v[174:177], v[110:113]
	v_mfma_i32_16x16x64_i8 v[110:113], v[134:137], v[178:181], v[110:113]
	v_mfma_i32_16x16x64_i8 v[106:109], v[138:141], v[174:177], v[106:109]
	v_mfma_i32_16x16x64_i8 v[106:109], v[142:145], v[178:181], v[106:109]
	v_mfma_i32_16x16x64_i8 v[126:129], v[130:133], v[182:185], v[126:129]
	v_mfma_i32_16x16x64_i8 v[126:129], v[134:137], v[186:189], v[126:129]
	v_mfma_i32_16x16x64_i8 v[118:121], v[138:141], v[182:185], v[118:121]
	v_mfma_i32_16x16x64_i8 v[118:121], v[142:145], v[186:189], v[118:121]
	v_mfma_i32_16x16x64_i8 v[62:65], v[130:133], v[190:193], v[62:65]
	v_mfma_i32_16x16x64_i8 v[62:65], v[134:137], v[238:241], v[62:65]
	v_mfma_i32_16x16x64_i8 v[50:53], v[138:141], v[190:193], v[50:53]
	v_mfma_i32_16x16x64_i8 v[50:53], v[142:145], v[238:241], v[50:53]
	v_mfma_i32_16x16x64_i8 v[14:17], v[130:133], v[242:245], v[14:17]
	v_mfma_i32_16x16x64_i8 v[14:17], v[134:137], v[246:249], v[14:17]
	v_mfma_i32_16x16x64_i8 v[10:13], v[138:141], v[242:245], v[10:13]
	v_mfma_i32_16x16x64_i8 v[10:13], v[142:145], v[246:249], v[10:13]
	v_mfma_i32_16x16x64_i8 v[122:125], v[146:149], v[174:177], v[122:125]
	v_mfma_i32_16x16x64_i8 v[122:125], v[150:153], v[178:181], v[122:125]
	v_mfma_i32_16x16x64_i8 v[114:117], v[154:157], v[174:177], v[114:117]
	v_mfma_i32_16x16x64_i8 v[114:117], v[158:161], v[178:181], v[114:117]
	v_mfma_i32_16x16x64_i8 v[78:81], v[146:149], v[182:185], v[78:81]
	v_mfma_i32_16x16x64_i8 v[78:81], v[150:153], v[186:189], v[78:81]
	v_mfma_i32_16x16x64_i8 v[66:69], v[154:157], v[182:185], v[66:69]
	v_mfma_i32_16x16x64_i8 v[66:69], v[158:161], v[186:189], v[66:69]
	v_mfma_i32_16x16x64_i8 v[22:25], v[146:149], v[190:193], v[22:25]
	v_mfma_i32_16x16x64_i8 v[22:25], v[150:153], v[238:241], v[22:25]
	v_mfma_i32_16x16x64_i8 v[18:21], v[154:157], v[190:193], v[18:21]
	v_mfma_i32_16x16x64_i8 v[18:21], v[158:161], v[238:241], v[18:21]
	v_mfma_i32_16x16x64_i8 v[6:9], v[146:149], v[242:245], v[6:9]
	v_mfma_i32_16x16x64_i8 v[6:9], v[150:153], v[246:249], v[6:9]
	v_mfma_i32_16x16x64_i8 v[2:5], v[154:157], v[242:245], v[2:5]
	v_mfma_i32_16x16x64_i8 v[2:5], v[158:161], v[246:249], v[2:5]
	s_setprio 1
	s_barrier
	s_add_i32 s80, s80, 2
	s_add_u32 s36, s36, 0x100
	s_addc_u32 s37, s37, 0
	s_cmp_gt_u32 s80, 13
	s_cbranch_scc0 .LBB0_746
	s_nop 15
	s_nop 15
	s_and_b64 vcc, exec, s[8:9]
	s_cbranch_vccz .LBB0_749
	s_barrier

.LBB0_752:
	ds_read_b128 v[134:137], v227
	ds_read_b128 v[138:141], v227 offset:1024
	ds_read_b128 v[142:145], v227 offset:2048
	ds_read_b128 v[146:149], v227 offset:3072
	ds_read_b128 v[150:153], v233
	ds_read_b128 v[154:157], v233 offset:1024
	ds_read_b128 v[158:161], v233 offset:2048
	ds_read_b128 v[162:165], v233 offset:3072
	s_add_u32 s30, s29, s2
	s_addc_u32 s31, s33, s3
	s_add_u32 s30, s30, 0x200100
	s_addc_u32 s31, s31, 0
	s_add_u32 s77, s25, s2
	s_addc_u32 s78, s40, s3
	s_cmpk_eq_i32 s2, 0xf00
	s_cselect_b32 s35, s0, s31
	s_cselect_b32 s34, s1, s30
	s_cselect_b32 s31, s14, s78
	s_cselect_b32 s30, s15, s77
	s_mov_b32 m0, s66
	v_lshl_add_u64 v[242:243], v[130:131], 0, s[2:3]
	ds_read_b128 v[166:169], v226
	ds_read_b128 v[170:173], v226 offset:1024
	ds_read_b128 v[174:177], v226 offset:2048
	ds_read_b128 v[178:181], v226 offset:3072
	ds_read_b128 v[182:185], v226 offset:4096
	ds_read_b128 v[186:189], v226 offset:5120
	ds_read_b128 v[190:193], v226 offset:6144
	ds_read_b128 v[238:241], v226 offset:7168
	global_load_lds_dwordx4 v[242:243], off
	v_lshl_add_u64 v[242:243], v[132:133], 0, s[2:3]
	s_mov_b32 m0, s67
	s_nop 0
	global_load_lds_dwordx4 v[242:243], off
	s_waitcnt vmcnt(8)
	s_waitcnt lgkmcnt(0)
	s_barrier
	s_setprio 0
	s_waitcnt lgkmcnt(0)
	v_mfma_f32_16x16x32_bf16 v[26:29], v[134:137], v[166:169], v[26:29]
	v_mfma_f32_16x16x32_bf16 v[30:33], v[142:145], v[166:169], v[30:33]
	v_mfma_f32_16x16x32_bf16 v[42:45], v[134:137], v[174:177], v[42:45]
	v_mfma_f32_16x16x32_bf16 v[46:49], v[142:145], v[174:177], v[46:49]
	v_mfma_f32_16x16x32_bf16 v[70:73], v[134:137], v[182:185], v[70:73]
	v_mfma_f32_16x16x32_bf16 v[74:77], v[142:145], v[182:185], v[74:77]
	v_mfma_f32_16x16x32_bf16 v[90:93], v[134:137], v[190:193], v[90:93]
	v_mfma_f32_16x16x32_bf16 v[94:97], v[142:145], v[190:193], v[94:97]
	v_mfma_f32_16x16x32_bf16 v[26:29], v[138:141], v[170:173], v[26:29]
	v_mfma_f32_16x16x32_bf16 v[30:33], v[146:149], v[170:173], v[30:33]
	v_mfma_f32_16x16x32_bf16 v[42:45], v[138:141], v[178:181], v[42:45]
	v_mfma_f32_16x16x32_bf16 v[46:49], v[146:149], v[178:181], v[46:49]
	v_mfma_f32_16x16x32_bf16 v[70:73], v[138:141], v[186:189], v[70:73]
	v_mfma_f32_16x16x32_bf16 v[74:77], v[146:149], v[186:189], v[74:77]
	v_mfma_f32_16x16x32_bf16 v[90:93], v[138:141], v[238:241], v[90:93]
	v_mfma_f32_16x16x32_bf16 v[94:97], v[146:149], v[238:241], v[94:97]
	v_mfma_f32_16x16x32_bf16 v[34:37], v[150:153], v[166:169], v[34:37]
	v_mfma_f32_16x16x32_bf16 v[38:41], v[158:161], v[166:169], v[38:41]
	v_mfma_f32_16x16x32_bf16 v[54:57], v[150:153], v[174:177], v[54:57]
	v_mfma_f32_16x16x32_bf16 v[58:61], v[158:161], v[174:177], v[58:61]
	v_mfma_f32_16x16x32_bf16 v[82:85], v[150:153], v[182:185], v[82:85]
	v_mfma_f32_16x16x32_bf16 v[86:89], v[158:161], v[182:185], v[86:89]
	v_mfma_f32_16x16x32_bf16 v[98:101], v[150:153], v[190:193], v[98:101]
	v_mfma_f32_16x16x32_bf16 v[102:105], v[158:161], v[190:193], v[102:105]
	v_mfma_f32_16x16x32_bf16 v[34:37], v[154:157], v[170:173], v[34:37]
	v_mfma_f32_16x16x32_bf16 v[38:41], v[162:165], v[170:173], v[38:41]
	v_mfma_f32_16x16x32_bf16 v[54:57], v[154:157], v[178:181], v[54:57]
	v_mfma_f32_16x16x32_bf16 v[58:61], v[162:165], v[178:181], v[58:61]
	v_mfma_f32_16x16x32_bf16 v[82:85], v[154:157], v[186:189], v[82:85]
	v_mfma_f32_16x16x32_bf16 v[86:89], v[162:165], v[186:189], v[86:89]
	v_mfma_f32_16x16x32_bf16 v[98:101], v[154:157], v[238:241], v[98:101]
	v_mfma_f32_16x16x32_bf16 v[102:105], v[162:165], v[238:241], v[102:105]
	s_setprio 1
	s_barrier
	s_mov_b32 m0, s68
	v_lshl_add_u64 v[242:243], s[30:31], 0, v[202:203]
	s_add_u32 s78, s30, 0x80000
	ds_read_b128 v[166:169], v226 offset:16384
	ds_read_b128 v[170:173], v226 offset:17408
	ds_read_b128 v[174:177], v226 offset:18432
	ds_read_b128 v[178:181], v226 offset:19456
	ds_read_b128 v[182:185], v226 offset:20480
	ds_read_b128 v[186:189], v226 offset:21504
	ds_read_b128 v[190:193], v226 offset:22528
	ds_read_b128 v[238:241], v226 offset:23552
	global_load_lds_dwordx4 v[242:243], off
	v_lshl_add_u64 v[244:245], s[30:31], 0, v[206:207]
	s_mov_b32 m0, s69
	s_addc_u32 s79, s31, 0
	global_load_lds_dwordx4 v[244:245], off
	v_lshl_add_u64 v[246:247], s[78:79], 0, v[202:203]
	s_mov_b32 m0, s70
	v_lshl_add_u64 v[248:249], s[34:35], 0, v[204:205]
	global_load_lds_dwordx4 v[246:247], off
	v_lshl_add_u64 v[246:247], s[78:79], 0, v[206:207]
	s_mov_b32 m0, s71
	s_nop 0
	global_load_lds_dwordx4 v[246:247], off
	v_lshl_add_u64 v[246:247], s[34:35], 0, v[194:195]
	s_mov_b32 m0, s23
	s_nop 0
	global_load_lds_dwordx4 v[246:247], off
	s_mov_b32 m0, s42
	s_nop 0
	global_load_lds_dwordx4 v[248:249], off
	s_waitcnt vmcnt(8)
	s_waitcnt lgkmcnt(0)
	s_barrier
	s_setprio 0
	s_waitcnt lgkmcnt(0)
	v_mfma_f32_16x16x32_bf16 v[106:109], v[134:137], v[166:169], v[106:109]
	v_mfma_f32_16x16x32_bf16 v[110:113], v[142:145], v[166:169], v[110:113]
	v_mfma_f32_16x16x32_bf16 v[118:121], v[134:137], v[174:177], v[118:121]
	v_mfma_f32_16x16x32_bf16 v[126:129], v[142:145], v[174:177], v[126:129]
	v_mfma_f32_16x16x32_bf16 v[50:53], v[134:137], v[182:185], v[50:53]
	v_mfma_f32_16x16x32_bf16 v[62:65], v[142:145], v[182:185], v[62:65]
	v_mfma_f32_16x16x32_bf16 v[10:13], v[134:137], v[190:193], v[10:13]
	v_mfma_f32_16x16x32_bf16 v[14:17], v[142:145], v[190:193], v[14:17]
	v_mfma_f32_16x16x32_bf16 v[106:109], v[138:141], v[170:173], v[106:109]
	v_mfma_f32_16x16x32_bf16 v[110:113], v[146:149], v[170:173], v[110:113]
	v_mfma_f32_16x16x32_bf16 v[118:121], v[138:141], v[178:181], v[118:121]
	v_mfma_f32_16x16x32_bf16 v[126:129], v[146:149], v[178:181], v[126:129]
	v_mfma_f32_16x16x32_bf16 v[50:53], v[138:141], v[186:189], v[50:53]
	v_mfma_f32_16x16x32_bf16 v[62:65], v[146:149], v[186:189], v[62:65]
	v_mfma_f32_16x16x32_bf16 v[10:13], v[138:141], v[238:241], v[10:13]
	v_mfma_f32_16x16x32_bf16 v[14:17], v[146:149], v[238:241], v[14:17]
	v_mfma_f32_16x16x32_bf16 v[114:117], v[150:153], v[166:169], v[114:117]
	v_mfma_f32_16x16x32_bf16 v[122:125], v[158:161], v[166:169], v[122:125]
	v_mfma_f32_16x16x32_bf16 v[66:69], v[150:153], v[174:177], v[66:69]
	v_mfma_f32_16x16x32_bf16 v[78:81], v[158:161], v[174:177], v[78:81]
	v_mfma_f32_16x16x32_bf16 v[18:21], v[150:153], v[182:185], v[18:21]
	v_mfma_f32_16x16x32_bf16 v[22:25], v[158:161], v[182:185], v[22:25]
	v_mfma_f32_16x16x32_bf16 v[2:5], v[150:153], v[190:193], v[2:5]
	v_mfma_f32_16x16x32_bf16 v[6:9], v[158:161], v[190:193], v[6:9]
	v_mfma_f32_16x16x32_bf16 v[114:117], v[154:157], v[170:173], v[114:117]
	v_mfma_f32_16x16x32_bf16 v[122:125], v[162:165], v[170:173], v[122:125]
	v_mfma_f32_16x16x32_bf16 v[66:69], v[154:157], v[178:181], v[66:69]
	v_mfma_f32_16x16x32_bf16 v[78:81], v[162:165], v[178:181], v[78:81]
	v_mfma_f32_16x16x32_bf16 v[18:21], v[154:157], v[186:189], v[18:21]
	v_mfma_f32_16x16x32_bf16 v[22:25], v[162:165], v[186:189], v[22:25]
	v_mfma_f32_16x16x32_bf16 v[2:5], v[154:157], v[238:241], v[2:5]
	v_mfma_f32_16x16x32_bf16 v[6:9], v[162:165], v[238:241], v[6:9]
	s_setprio 1
	s_barrier
	ds_read_b128 v[134:137], v235
	ds_read_b128 v[138:141], v235 offset:1024
	ds_read_b128 v[142:145], v235 offset:2048
	ds_read_b128 v[146:149], v235 offset:3072
	ds_read_b128 v[150:153], v236
	ds_read_b128 v[154:157], v236 offset:1024
	ds_read_b128 v[158:161], v236 offset:2048
	ds_read_b128 v[162:165], v236 offset:3072
	s_add_u32 s34, s34, 0x80000
	s_addc_u32 s35, s35, 0
	s_mov_b32 m0, s43
	v_lshl_add_u64 v[250:251], s[34:35], 0, v[194:195]
	ds_read_b128 v[166:169], v226 offset:32768
	ds_read_b128 v[170:173], v226 offset:33792
	ds_read_b128 v[174:177], v226 offset:34816
	ds_read_b128 v[178:181], v226 offset:35840
	ds_read_b128 v[182:185], v226 offset:36864
	ds_read_b128 v[186:189], v226 offset:37888
	ds_read_b128 v[190:193], v226 offset:38912
	ds_read_b128 v[238:241], v226 offset:39936
	global_load_lds_dwordx4 v[250:251], off
	v_lshl_add_u64 v[250:251], s[34:35], 0, v[204:205]
	s_mov_b32 m0, s44
	s_nop 0
	global_load_lds_dwordx4 v[250:251], off
	s_waitcnt vmcnt(8)
	s_waitcnt lgkmcnt(0)
	s_barrier
	s_setprio 0
	s_waitcnt lgkmcnt(0)
	v_mfma_f32_16x16x32_bf16 v[26:29], v[134:137], v[166:169], v[26:29]
	v_mfma_f32_16x16x32_bf16 v[30:33], v[142:145], v[166:169], v[30:33]
	v_mfma_f32_16x16x32_bf16 v[42:45], v[134:137], v[174:177], v[42:45]
	v_mfma_f32_16x16x32_bf16 v[46:49], v[142:145], v[174:177], v[46:49]
	v_mfma_f32_16x16x32_bf16 v[70:73], v[134:137], v[182:185], v[70:73]
	v_mfma_f32_16x16x32_bf16 v[74:77], v[142:145], v[182:185], v[74:77]
	v_mfma_f32_16x16x32_bf16 v[90:93], v[134:137], v[190:193], v[90:93]
	v_mfma_f32_16x16x32_bf16 v[94:97], v[142:145], v[190:193], v[94:97]
	v_mfma_f32_16x16x32_bf16 v[26:29], v[138:141], v[170:173], v[26:29]
	v_mfma_f32_16x16x32_bf16 v[30:33], v[146:149], v[170:173], v[30:33]
	v_mfma_f32_16x16x32_bf16 v[42:45], v[138:141], v[178:181], v[42:45]
	v_mfma_f32_16x16x32_bf16 v[46:49], v[146:149], v[178:181], v[46:49]
	v_mfma_f32_16x16x32_bf16 v[70:73], v[138:141], v[186:189], v[70:73]
	v_mfma_f32_16x16x32_bf16 v[74:77], v[146:149], v[186:189], v[74:77]
	v_mfma_f32_16x16x32_bf16 v[90:93], v[138:141], v[238:241], v[90:93]
	v_mfma_f32_16x16x32_bf16 v[94:97], v[146:149], v[238:241], v[94:97]
	v_mfma_f32_16x16x32_bf16 v[34:37], v[150:153], v[166:169], v[34:37]
	v_mfma_f32_16x16x32_bf16 v[38:41], v[158:161], v[166:169], v[38:41]
	v_mfma_f32_16x16x32_bf16 v[54:57], v[150:153], v[174:177], v[54:57]
	v_mfma_f32_16x16x32_bf16 v[58:61], v[158:161], v[174:177], v[58:61]
	v_mfma_f32_16x16x32_bf16 v[82:85], v[150:153], v[182:185], v[82:85]
	v_mfma_f32_16x16x32_bf16 v[86:89], v[158:161], v[182:185], v[86:89]
	v_mfma_f32_16x16x32_bf16 v[98:101], v[150:153], v[190:193], v[98:101]
	v_mfma_f32_16x16x32_bf16 v[102:105], v[158:161], v[190:193], v[102:105]
	v_mfma_f32_16x16x32_bf16 v[34:37], v[154:157], v[170:173], v[34:37]
	v_mfma_f32_16x16x32_bf16 v[38:41], v[162:165], v[170:173], v[38:41]
	v_mfma_f32_16x16x32_bf16 v[54:57], v[154:157], v[178:181], v[54:57]
	v_mfma_f32_16x16x32_bf16 v[58:61], v[162:165], v[178:181], v[58:61]
	v_mfma_f32_16x16x32_bf16 v[82:85], v[154:157], v[186:189], v[82:85]
	v_mfma_f32_16x16x32_bf16 v[86:89], v[162:165], v[186:189], v[86:89]
	v_mfma_f32_16x16x32_bf16 v[98:101], v[154:157], v[238:241], v[98:101]
	v_mfma_f32_16x16x32_bf16 v[102:105], v[162:165], v[238:241], v[102:105]
	s_setprio 1
	s_barrier
	s_mov_b32 m0, s72
	v_lshl_add_u64 v[242:243], v[242:243], 0, s[6:7]
	s_add_u32 s30, s30, 0x80080
	ds_read_b128 v[166:169], v226 offset:49152
	ds_read_b128 v[170:173], v226 offset:50176
	ds_read_b128 v[174:177], v226 offset:51200
	ds_read_b128 v[178:181], v226 offset:52224
	ds_read_b128 v[182:185], v226 offset:53248
	ds_read_b128 v[186:189], v226 offset:54272
	ds_read_b128 v[190:193], v226 offset:55296
	ds_read_b128 v[238:241], v226 offset:56320
	global_load_lds_dwordx4 v[242:243], off
	v_lshl_add_u64 v[242:243], v[244:245], 0, s[6:7]
	s_mov_b32 m0, s73
	s_addc_u32 s31, s31, 0
	global_load_lds_dwordx4 v[242:243], off
	v_lshl_add_u64 v[242:243], s[30:31], 0, v[202:203]
	s_mov_b32 m0, s74
	s_nop 0
	global_load_lds_dwordx4 v[242:243], off
	v_lshl_add_u64 v[242:243], s[30:31], 0, v[206:207]
	s_mov_b32 m0, s75
	s_nop 0
	global_load_lds_dwordx4 v[242:243], off
	v_lshl_add_u64 v[242:243], v[246:247], 0, s[6:7]
	s_mov_b32 m0, s51
	s_nop 0
	global_load_lds_dwordx4 v[242:243], off
	v_lshl_add_u64 v[242:243], v[248:249], 0, s[6:7]
	s_mov_b32 m0, s53
	s_nop 0
	global_load_lds_dwordx4 v[242:243], off
	s_waitcnt vmcnt(8)
	s_waitcnt lgkmcnt(0)
	s_barrier
	s_setprio 0
	s_waitcnt lgkmcnt(0)
	v_mfma_f32_16x16x32_bf16 v[106:109], v[134:137], v[166:169], v[106:109]
	v_mfma_f32_16x16x32_bf16 v[110:113], v[142:145], v[166:169], v[110:113]
	v_mfma_f32_16x16x32_bf16 v[118:121], v[134:137], v[174:177], v[118:121]
	v_mfma_f32_16x16x32_bf16 v[126:129], v[142:145], v[174:177], v[126:129]
	v_mfma_f32_16x16x32_bf16 v[50:53], v[134:137], v[182:185], v[50:53]
	v_mfma_f32_16x16x32_bf16 v[62:65], v[142:145], v[182:185], v[62:65]
	v_mfma_f32_16x16x32_bf16 v[10:13], v[134:137], v[190:193], v[10:13]
	v_mfma_f32_16x16x32_bf16 v[14:17], v[142:145], v[190:193], v[14:17]
	v_mfma_f32_16x16x32_bf16 v[106:109], v[138:141], v[170:173], v[106:109]
	v_mfma_f32_16x16x32_bf16 v[110:113], v[146:149], v[170:173], v[110:113]
	v_mfma_f32_16x16x32_bf16 v[118:121], v[138:141], v[178:181], v[118:121]
	v_mfma_f32_16x16x32_bf16 v[126:129], v[146:149], v[178:181], v[126:129]
	v_mfma_f32_16x16x32_bf16 v[50:53], v[138:141], v[186:189], v[50:53]
	v_mfma_f32_16x16x32_bf16 v[62:65], v[146:149], v[186:189], v[62:65]
	v_mfma_f32_16x16x32_bf16 v[10:13], v[138:141], v[238:241], v[10:13]
	v_mfma_f32_16x16x32_bf16 v[14:17], v[146:149], v[238:241], v[14:17]
	v_mfma_f32_16x16x32_bf16 v[114:117], v[150:153], v[166:169], v[114:117]
	v_mfma_f32_16x16x32_bf16 v[122:125], v[158:161], v[166:169], v[122:125]
	v_mfma_f32_16x16x32_bf16 v[66:69], v[150:153], v[174:177], v[66:69]
	v_mfma_f32_16x16x32_bf16 v[78:81], v[158:161], v[174:177], v[78:81]
	v_mfma_f32_16x16x32_bf16 v[18:21], v[150:153], v[182:185], v[18:21]
	v_mfma_f32_16x16x32_bf16 v[22:25], v[158:161], v[182:185], v[22:25]
	v_mfma_f32_16x16x32_bf16 v[2:5], v[150:153], v[190:193], v[2:5]
	v_mfma_f32_16x16x32_bf16 v[6:9], v[158:161], v[190:193], v[6:9]
	v_mfma_f32_16x16x32_bf16 v[114:117], v[154:157], v[170:173], v[114:117]
	v_mfma_f32_16x16x32_bf16 v[122:125], v[162:165], v[170:173], v[122:125]
	v_mfma_f32_16x16x32_bf16 v[66:69], v[154:157], v[178:181], v[66:69]
	v_mfma_f32_16x16x32_bf16 v[78:81], v[162:165], v[178:181], v[78:81]
	v_mfma_f32_16x16x32_bf16 v[18:21], v[154:157], v[186:189], v[18:21]
	v_mfma_f32_16x16x32_bf16 v[22:25], v[162:165], v[186:189], v[22:25]
	v_mfma_f32_16x16x32_bf16 v[2:5], v[154:157], v[238:241], v[2:5]
	v_mfma_f32_16x16x32_bf16 v[6:9], v[162:165], v[238:241], v[6:9]
	s_setprio 1
	s_barrier
	s_add_i32 s41, s41, 2
	s_add_u32 s2, s2, 0x100
	s_addc_u32 s3, s3, 0
	s_cmp_gt_u32 s41, 29
	s_cbranch_scc0 .LBB0_752
	s_and_b64 vcc, exec, s[8:9]
	s_cbranch_vccz .LBB0_755
	s_barrier

.LBB0_817:
	ds_read_b128 v[130:133], v223
	ds_read_b128 v[134:137], v223 offset:1024
	ds_read_b128 v[138:141], v223 offset:2048
	ds_read_b128 v[142:145], v223 offset:3072
	ds_read_b128 v[146:149], v224
	ds_read_b128 v[150:153], v224 offset:1024
	ds_read_b128 v[154:157], v224 offset:2048
	ds_read_b128 v[158:161], v224 offset:3072
	s_add_u32 s6, s4, 0xfff00080
	s_addc_u32 s7, s5, -1
	s_cmp_eq_u32 s14, 60
	s_cselect_b32 s9, s19, s7
	s_cselect_b32 s8, s18, s6
	s_cselect_b32 s7, s79, s1
	s_cselect_b32 s6, s78, s0
	v_lshl_add_u64 v[194:195], s[4:5], 0, v[170:171]
	s_add_i32 m0, s35, 0xc000
	ds_read_b128 v[174:177], v225
	ds_read_b128 v[178:181], v225 offset:1024
	ds_read_b128 v[182:185], v225 offset:2048
	ds_read_b128 v[186:189], v225 offset:3072
	ds_read_b128 v[190:193], v225 offset:4096
	ds_read_b128 v[202:205], v225 offset:5120
	ds_read_b128 v[206:209], v225 offset:6144
	ds_read_b128 v[210:213], v225 offset:7168
	global_load_lds_dwordx4 v[194:195], off
	v_lshl_add_u64 v[194:195], s[4:5], 0, v[172:173]
	s_add_i32 m0, s35, 0xe000
	s_nop 0
	global_load_lds_dwordx4 v[194:195], off
	s_waitcnt vmcnt(8)
	s_waitcnt lgkmcnt(0)
	s_barrier
	s_setprio 0
	s_waitcnt lgkmcnt(0)
	v_mfma_f32_16x16x32_bf16 v[14:17], v[130:133], v[174:177], v[14:17]
	v_mfma_f32_16x16x32_bf16 v[10:13], v[138:141], v[174:177], v[10:13]
	v_mfma_f32_16x16x32_bf16 v[34:37], v[130:133], v[182:185], v[34:37]
	v_mfma_f32_16x16x32_bf16 v[26:29], v[138:141], v[182:185], v[26:29]
	v_mfma_f32_16x16x32_bf16 v[46:49], v[130:133], v[190:193], v[46:49]
	v_mfma_f32_16x16x32_bf16 v[42:45], v[138:141], v[190:193], v[42:45]
	v_mfma_f32_16x16x32_bf16 v[62:65], v[130:133], v[206:209], v[62:65]
	v_mfma_f32_16x16x32_bf16 v[58:61], v[138:141], v[206:209], v[58:61]
	v_mfma_f32_16x16x32_bf16 v[14:17], v[134:137], v[178:181], v[14:17]
	v_mfma_f32_16x16x32_bf16 v[10:13], v[142:145], v[178:181], v[10:13]
	v_mfma_f32_16x16x32_bf16 v[34:37], v[134:137], v[186:189], v[34:37]
	v_mfma_f32_16x16x32_bf16 v[26:29], v[142:145], v[186:189], v[26:29]
	v_mfma_f32_16x16x32_bf16 v[46:49], v[134:137], v[202:205], v[46:49]
	v_mfma_f32_16x16x32_bf16 v[42:45], v[142:145], v[202:205], v[42:45]
	v_mfma_f32_16x16x32_bf16 v[62:65], v[134:137], v[210:213], v[62:65]
	v_mfma_f32_16x16x32_bf16 v[58:61], v[142:145], v[210:213], v[58:61]
	v_mfma_f32_16x16x32_bf16 v[6:9], v[146:149], v[174:177], v[6:9]
	v_mfma_f32_16x16x32_bf16 v[2:5], v[154:157], v[174:177], v[2:5]
	v_mfma_f32_16x16x32_bf16 v[22:25], v[146:149], v[182:185], v[22:25]
	v_mfma_f32_16x16x32_bf16 v[18:21], v[154:157], v[182:185], v[18:21]
	v_mfma_f32_16x16x32_bf16 v[38:41], v[146:149], v[190:193], v[38:41]
	v_mfma_f32_16x16x32_bf16 v[30:33], v[154:157], v[190:193], v[30:33]
	v_mfma_f32_16x16x32_bf16 v[54:57], v[146:149], v[206:209], v[54:57]
	v_mfma_f32_16x16x32_bf16 v[50:53], v[154:157], v[206:209], v[50:53]
	v_mfma_f32_16x16x32_bf16 v[6:9], v[150:153], v[178:181], v[6:9]
	v_mfma_f32_16x16x32_bf16 v[2:5], v[158:161], v[178:181], v[2:5]
	v_mfma_f32_16x16x32_bf16 v[22:25], v[150:153], v[186:189], v[22:25]
	v_mfma_f32_16x16x32_bf16 v[18:21], v[158:161], v[186:189], v[18:21]
	v_mfma_f32_16x16x32_bf16 v[38:41], v[150:153], v[202:205], v[38:41]
	v_mfma_f32_16x16x32_bf16 v[30:33], v[158:161], v[202:205], v[30:33]
	v_mfma_f32_16x16x32_bf16 v[54:57], v[150:153], v[210:213], v[54:57]
	v_mfma_f32_16x16x32_bf16 v[50:53], v[158:161], v[210:213], v[50:53]
	s_setprio 1
	s_barrier
	s_add_i32 s15, s17, s33
	v_lshl_add_u64 v[194:195], s[6:7], 0, v[164:165]
	s_mov_b32 m0, s15
	ds_read_b128 v[174:177], v225 offset:16384
	ds_read_b128 v[178:181], v225 offset:17408
	ds_read_b128 v[182:185], v225 offset:18432
	ds_read_b128 v[186:189], v225 offset:19456
	ds_read_b128 v[190:193], v225 offset:20480
	ds_read_b128 v[202:205], v225 offset:21504
	ds_read_b128 v[206:209], v225 offset:22528
	ds_read_b128 v[210:213], v225 offset:23552
	global_load_lds_dwordx4 v[194:195], off
	s_add_i32 m0, s15, 0x2000
	s_add_u32 s44, s6, 0x100000
	v_lshl_add_u64 v[214:215], s[6:7], 0, v[168:169]
	s_addc_u32 s45, s7, 0
	s_add_i32 s15, s55, s33
	global_load_lds_dwordx4 v[214:215], off
	v_lshl_add_u64 v[216:217], s[44:45], 0, v[164:165]
	s_mov_b32 m0, s15
	v_lshl_add_u64 v[218:219], s[8:9], 0, v[166:167]
	global_load_lds_dwordx4 v[216:217], off
	v_lshl_add_u64 v[216:217], s[44:45], 0, v[168:169]
	s_add_i32 m0, s15, 0x2000
	s_nop 0
	global_load_lds_dwordx4 v[216:217], off
	v_lshl_add_u64 v[216:217], s[8:9], 0, v[162:163]
	s_mov_b32 m0, s35
	s_nop 0
	global_load_lds_dwordx4 v[216:217], off
	s_mov_b32 m0, s80
	s_nop 0
	global_load_lds_dwordx4 v[218:219], off
	s_waitcnt vmcnt(8)
	s_waitcnt lgkmcnt(0)
	s_barrier
	s_setprio 0
	s_waitcnt lgkmcnt(0)
	v_mfma_f32_16x16x32_bf16 v[78:81], v[130:133], v[174:177], v[78:81]
	v_mfma_f32_16x16x32_bf16 v[74:77], v[138:141], v[174:177], v[74:77]
	v_mfma_f32_16x16x32_bf16 v[94:97], v[130:133], v[182:185], v[94:97]
	v_mfma_f32_16x16x32_bf16 v[90:93], v[138:141], v[182:185], v[90:93]
	v_mfma_f32_16x16x32_bf16 v[110:113], v[130:133], v[190:193], v[110:113]
	v_mfma_f32_16x16x32_bf16 v[106:109], v[138:141], v[190:193], v[106:109]
	v_mfma_f32_16x16x32_bf16 v[118:121], v[130:133], v[206:209], v[118:121]
	v_mfma_f32_16x16x32_bf16 v[114:117], v[138:141], v[206:209], v[114:117]
	v_mfma_f32_16x16x32_bf16 v[78:81], v[134:137], v[178:181], v[78:81]
	v_mfma_f32_16x16x32_bf16 v[74:77], v[142:145], v[178:181], v[74:77]
	v_mfma_f32_16x16x32_bf16 v[94:97], v[134:137], v[186:189], v[94:97]
	v_mfma_f32_16x16x32_bf16 v[90:93], v[142:145], v[186:189], v[90:93]
	v_mfma_f32_16x16x32_bf16 v[110:113], v[134:137], v[202:205], v[110:113]
	v_mfma_f32_16x16x32_bf16 v[106:109], v[142:145], v[202:205], v[106:109]
	v_mfma_f32_16x16x32_bf16 v[118:121], v[134:137], v[210:213], v[118:121]
	v_mfma_f32_16x16x32_bf16 v[114:117], v[142:145], v[210:213], v[114:117]
	v_mfma_f32_16x16x32_bf16 v[70:73], v[146:149], v[174:177], v[70:73]
	v_mfma_f32_16x16x32_bf16 v[66:69], v[154:157], v[174:177], v[66:69]
	v_mfma_f32_16x16x32_bf16 v[86:89], v[146:149], v[182:185], v[86:89]
	v_mfma_f32_16x16x32_bf16 v[82:85], v[154:157], v[182:185], v[82:85]
	v_mfma_f32_16x16x32_bf16 v[102:105], v[146:149], v[190:193], v[102:105]
	v_mfma_f32_16x16x32_bf16 v[98:101], v[154:157], v[190:193], v[98:101]
	v_mfma_f32_16x16x32_bf16 v[122:125], v[146:149], v[206:209], v[122:125]
	v_mfma_f32_16x16x32_bf16 v[126:129], v[154:157], v[206:209], v[126:129]
	v_mfma_f32_16x16x32_bf16 v[70:73], v[150:153], v[178:181], v[70:73]
	v_mfma_f32_16x16x32_bf16 v[66:69], v[158:161], v[178:181], v[66:69]
	v_mfma_f32_16x16x32_bf16 v[86:89], v[150:153], v[186:189], v[86:89]
	v_mfma_f32_16x16x32_bf16 v[82:85], v[158:161], v[186:189], v[82:85]
	v_mfma_f32_16x16x32_bf16 v[102:105], v[150:153], v[202:205], v[102:105]
	v_mfma_f32_16x16x32_bf16 v[98:101], v[158:161], v[202:205], v[98:101]
	v_mfma_f32_16x16x32_bf16 v[122:125], v[150:153], v[210:213], v[122:125]
	v_mfma_f32_16x16x32_bf16 v[126:129], v[158:161], v[210:213], v[126:129]
	s_setprio 1
	s_barrier
	s_add_i32 s56, 0, 0x18000
	s_add_i32 s57, 0, 0x1c000
	v_add_u32_e32 v142, s56, v222
	v_add_u32_e32 v158, s57, v222
	ds_read_b128 v[130:133], v142
	ds_read_b128 v[134:137], v142 offset:1024
	ds_read_b128 v[138:141], v142 offset:2048
	ds_read_b128 v[142:145], v142 offset:3072
	ds_read_b128 v[146:149], v158
	ds_read_b128 v[150:153], v158 offset:1024
	ds_read_b128 v[154:157], v158 offset:2048
	ds_read_b128 v[158:161], v158 offset:3072
	s_add_u32 s8, s8, 0x100000
	s_addc_u32 s9, s9, 0
	s_mov_b32 m0, s59
	v_lshl_add_u64 v[238:239], s[8:9], 0, v[162:163]
	ds_read_b128 v[174:177], v225 offset:32768
	ds_read_b128 v[178:181], v225 offset:33792
	ds_read_b128 v[182:185], v225 offset:34816
	ds_read_b128 v[186:189], v225 offset:35840
	ds_read_b128 v[190:193], v225 offset:36864
	ds_read_b128 v[202:205], v225 offset:37888
	ds_read_b128 v[206:209], v225 offset:38912
	ds_read_b128 v[210:213], v225 offset:39936
	global_load_lds_dwordx4 v[238:239], off
	v_lshl_add_u64 v[238:239], s[8:9], 0, v[166:167]
	s_mov_b32 m0, s60
	s_nop 0
	global_load_lds_dwordx4 v[238:239], off
	s_waitcnt vmcnt(8)
	s_waitcnt lgkmcnt(0)
	s_barrier
	s_setprio 0
	s_waitcnt lgkmcnt(0)
	v_mfma_f32_16x16x32_bf16 v[14:17], v[130:133], v[174:177], v[14:17]
	v_mfma_f32_16x16x32_bf16 v[10:13], v[138:141], v[174:177], v[10:13]
	v_mfma_f32_16x16x32_bf16 v[34:37], v[130:133], v[182:185], v[34:37]
	v_mfma_f32_16x16x32_bf16 v[26:29], v[138:141], v[182:185], v[26:29]
	v_mfma_f32_16x16x32_bf16 v[46:49], v[130:133], v[190:193], v[46:49]
	v_mfma_f32_16x16x32_bf16 v[42:45], v[138:141], v[190:193], v[42:45]
	v_mfma_f32_16x16x32_bf16 v[62:65], v[130:133], v[206:209], v[62:65]
	v_mfma_f32_16x16x32_bf16 v[58:61], v[138:141], v[206:209], v[58:61]
	v_mfma_f32_16x16x32_bf16 v[14:17], v[134:137], v[178:181], v[14:17]
	v_mfma_f32_16x16x32_bf16 v[10:13], v[142:145], v[178:181], v[10:13]
	v_mfma_f32_16x16x32_bf16 v[34:37], v[134:137], v[186:189], v[34:37]
	v_mfma_f32_16x16x32_bf16 v[26:29], v[142:145], v[186:189], v[26:29]
	v_mfma_f32_16x16x32_bf16 v[46:49], v[134:137], v[202:205], v[46:49]
	v_mfma_f32_16x16x32_bf16 v[42:45], v[142:145], v[202:205], v[42:45]
	v_mfma_f32_16x16x32_bf16 v[62:65], v[134:137], v[210:213], v[62:65]
	v_mfma_f32_16x16x32_bf16 v[58:61], v[142:145], v[210:213], v[58:61]
	v_mfma_f32_16x16x32_bf16 v[6:9], v[146:149], v[174:177], v[6:9]
	v_mfma_f32_16x16x32_bf16 v[2:5], v[154:157], v[174:177], v[2:5]
	v_mfma_f32_16x16x32_bf16 v[22:25], v[146:149], v[182:185], v[22:25]
	v_mfma_f32_16x16x32_bf16 v[18:21], v[154:157], v[182:185], v[18:21]
	v_mfma_f32_16x16x32_bf16 v[38:41], v[146:149], v[190:193], v[38:41]
	v_mfma_f32_16x16x32_bf16 v[30:33], v[154:157], v[190:193], v[30:33]
	v_mfma_f32_16x16x32_bf16 v[54:57], v[146:149], v[206:209], v[54:57]
	v_mfma_f32_16x16x32_bf16 v[50:53], v[154:157], v[206:209], v[50:53]
	v_mfma_f32_16x16x32_bf16 v[6:9], v[150:153], v[178:181], v[6:9]
	v_mfma_f32_16x16x32_bf16 v[2:5], v[158:161], v[178:181], v[2:5]
	v_mfma_f32_16x16x32_bf16 v[22:25], v[150:153], v[186:189], v[22:25]
	v_mfma_f32_16x16x32_bf16 v[18:21], v[158:161], v[186:189], v[18:21]
	v_mfma_f32_16x16x32_bf16 v[38:41], v[150:153], v[202:205], v[38:41]
	v_mfma_f32_16x16x32_bf16 v[30:33], v[158:161], v[202:205], v[30:33]
	v_mfma_f32_16x16x32_bf16 v[54:57], v[150:153], v[210:213], v[54:57]
	v_mfma_f32_16x16x32_bf16 v[50:53], v[158:161], v[210:213], v[50:53]
	s_setprio 1
	s_barrier
	s_add_i32 s8, s56, s33
	v_lshl_add_u64 v[194:195], v[194:195], 0, s[26:27]
	s_mov_b32 m0, s8
	ds_read_b128 v[174:177], v225 offset:49152
	ds_read_b128 v[178:181], v225 offset:50176
	ds_read_b128 v[182:185], v225 offset:51200
	ds_read_b128 v[186:189], v225 offset:52224
	ds_read_b128 v[190:193], v225 offset:53248
	ds_read_b128 v[202:205], v225 offset:54272
	ds_read_b128 v[206:209], v225 offset:55296
	ds_read_b128 v[210:213], v225 offset:56320
	global_load_lds_dwordx4 v[194:195], off
	s_add_i32 m0, s8, 0x2000
	s_add_u32 s6, s6, 0x100080
	v_lshl_add_u64 v[194:195], v[214:215], 0, s[26:27]
	s_addc_u32 s7, s7, 0
	s_add_i32 s8, s57, s33
	global_load_lds_dwordx4 v[194:195], off
	v_lshl_add_u64 v[194:195], s[6:7], 0, v[164:165]
	s_mov_b32 m0, s8
	s_nop 0
	global_load_lds_dwordx4 v[194:195], off
	v_lshl_add_u64 v[194:195], s[6:7], 0, v[168:169]
	s_add_i32 m0, s8, 0x2000
	s_nop 0
	global_load_lds_dwordx4 v[194:195], off
	v_lshl_add_u64 v[194:195], v[216:217], 0, s[26:27]
	s_mov_b32 m0, s65
	s_nop 0
	global_load_lds_dwordx4 v[194:195], off
	v_lshl_add_u64 v[194:195], v[218:219], 0, s[26:27]
	s_mov_b32 m0, s66
	s_nop 0
	global_load_lds_dwordx4 v[194:195], off
	s_waitcnt vmcnt(8)
	s_waitcnt lgkmcnt(0)
	s_barrier
	s_setprio 0
	s_waitcnt lgkmcnt(0)
	v_mfma_f32_16x16x32_bf16 v[78:81], v[130:133], v[174:177], v[78:81]
	v_mfma_f32_16x16x32_bf16 v[74:77], v[138:141], v[174:177], v[74:77]
	v_mfma_f32_16x16x32_bf16 v[94:97], v[130:133], v[182:185], v[94:97]
	v_mfma_f32_16x16x32_bf16 v[90:93], v[138:141], v[182:185], v[90:93]
	v_mfma_f32_16x16x32_bf16 v[110:113], v[130:133], v[190:193], v[110:113]
	v_mfma_f32_16x16x32_bf16 v[106:109], v[138:141], v[190:193], v[106:109]
	v_mfma_f32_16x16x32_bf16 v[118:121], v[130:133], v[206:209], v[118:121]
	v_mfma_f32_16x16x32_bf16 v[114:117], v[138:141], v[206:209], v[114:117]
	v_mfma_f32_16x16x32_bf16 v[78:81], v[134:137], v[178:181], v[78:81]
	v_mfma_f32_16x16x32_bf16 v[74:77], v[142:145], v[178:181], v[74:77]
	v_mfma_f32_16x16x32_bf16 v[94:97], v[134:137], v[186:189], v[94:97]
	v_mfma_f32_16x16x32_bf16 v[90:93], v[142:145], v[186:189], v[90:93]
	v_mfma_f32_16x16x32_bf16 v[110:113], v[134:137], v[202:205], v[110:113]
	v_mfma_f32_16x16x32_bf16 v[106:109], v[142:145], v[202:205], v[106:109]
	v_mfma_f32_16x16x32_bf16 v[118:121], v[134:137], v[210:213], v[118:121]
	v_mfma_f32_16x16x32_bf16 v[114:117], v[142:145], v[210:213], v[114:117]
	v_mfma_f32_16x16x32_bf16 v[70:73], v[146:149], v[174:177], v[70:73]
	v_mfma_f32_16x16x32_bf16 v[66:69], v[154:157], v[174:177], v[66:69]
	v_mfma_f32_16x16x32_bf16 v[86:89], v[146:149], v[182:185], v[86:89]
	v_mfma_f32_16x16x32_bf16 v[82:85], v[154:157], v[182:185], v[82:85]
	v_mfma_f32_16x16x32_bf16 v[102:105], v[146:149], v[190:193], v[102:105]
	v_mfma_f32_16x16x32_bf16 v[98:101], v[154:157], v[190:193], v[98:101]
	v_mfma_f32_16x16x32_bf16 v[122:125], v[146:149], v[206:209], v[122:125]
	v_mfma_f32_16x16x32_bf16 v[126:129], v[154:157], v[206:209], v[126:129]
	v_mfma_f32_16x16x32_bf16 v[70:73], v[150:153], v[178:181], v[70:73]
	v_mfma_f32_16x16x32_bf16 v[66:69], v[158:161], v[178:181], v[66:69]
	v_mfma_f32_16x16x32_bf16 v[86:89], v[150:153], v[186:189], v[86:89]
	v_mfma_f32_16x16x32_bf16 v[82:85], v[158:161], v[186:189], v[82:85]
	v_mfma_f32_16x16x32_bf16 v[102:105], v[150:153], v[202:205], v[102:105]
	v_mfma_f32_16x16x32_bf16 v[98:101], v[158:161], v[202:205], v[98:101]
	v_mfma_f32_16x16x32_bf16 v[122:125], v[150:153], v[210:213], v[122:125]
	v_mfma_f32_16x16x32_bf16 v[126:129], v[158:161], v[210:213], v[126:129]
	s_setprio 1
	s_barrier
	s_add_i32 s14, s14, 2
	s_add_u32 s4, s4, 0x100
	s_addc_u32 s5, s5, 0
	s_add_u32 s0, s0, 0x100
	s_addc_u32 s1, s1, 0
	s_cmp_gt_u32 s14, 61
	s_cbranch_scc0 .LBB0_817
	s_and_b64 vcc, exec, s[28:29]
	s_cbranch_vccz .LBB0_820
	s_barrier

.LBB0_961:
	ds_read_b128 v[158:161], v185
	ds_read_b128 v[154:157], v185 offset:1024
	ds_read_b128 v[150:153], v185 offset:2048
	ds_read_b128 v[146:149], v185 offset:3072
	ds_read_b128 v[142:145], v186
	ds_read_b128 v[138:141], v186 offset:1024
	ds_read_b128 v[134:137], v186 offset:2048
	ds_read_b128 v[130:133], v186 offset:3072
	s_add_u32 s30, s28, 0xfff80080
	s_addc_u32 s31, s29, -1
	s_cmp_eq_u32 s45, 28
	s_cselect_b32 s35, s1, s31
	s_cselect_b32 s34, s15, s30
	s_cselect_b32 s31, s19, s44
	s_cselect_b32 s30, s42, s43
	v_lshl_add_u64 v[220:221], s[28:29], 0, v[170:171]
	s_add_i32 m0, s27, 0xc000
	ds_read_b128 v[174:177], v187
	ds_read_b128 v[178:181], v187 offset:1024
	ds_read_b128 v[188:191], v187 offset:2048
	ds_read_b128 v[192:195], v187 offset:3072
	ds_read_b128 v[202:205], v187 offset:4096
	ds_read_b128 v[206:209], v187 offset:5120
	ds_read_b128 v[210:213], v187 offset:6144
	ds_read_b128 v[214:217], v187 offset:7168
	global_load_lds_dwordx4 v[220:221], off
	v_lshl_add_u64 v[220:221], s[28:29], 0, v[172:173]
	s_add_i32 m0, s27, 0xe000
	s_nop 0
	global_load_lds_dwordx4 v[220:221], off
	s_waitcnt vmcnt(8)
	s_waitcnt lgkmcnt(0)
	s_barrier
	s_setprio 0
	s_waitcnt lgkmcnt(0)
	v_mfma_i32_16x16x64_i8 v[126:129], v[158:161], v[174:177], v[126:129]
	v_mfma_i32_16x16x64_i8 v[126:129], v[154:157], v[178:181], v[126:129]
	v_mfma_i32_16x16x64_i8 v[122:125], v[150:153], v[174:177], v[122:125]
	v_mfma_i32_16x16x64_i8 v[122:125], v[146:149], v[178:181], v[122:125]
	v_mfma_i32_16x16x64_i8 v[110:113], v[158:161], v[188:191], v[110:113]
	v_mfma_i32_16x16x64_i8 v[110:113], v[154:157], v[192:195], v[110:113]
	v_mfma_i32_16x16x64_i8 v[106:109], v[150:153], v[188:191], v[106:109]
	v_mfma_i32_16x16x64_i8 v[106:109], v[146:149], v[192:195], v[106:109]
	v_mfma_i32_16x16x64_i8 v[94:97], v[158:161], v[202:205], v[94:97]
	v_mfma_i32_16x16x64_i8 v[94:97], v[154:157], v[206:209], v[94:97]
	v_mfma_i32_16x16x64_i8 v[90:93], v[150:153], v[202:205], v[90:93]
	v_mfma_i32_16x16x64_i8 v[90:93], v[146:149], v[206:209], v[90:93]
	v_mfma_i32_16x16x64_i8 v[78:81], v[158:161], v[210:213], v[78:81]
	v_mfma_i32_16x16x64_i8 v[78:81], v[154:157], v[214:217], v[78:81]
	v_mfma_i32_16x16x64_i8 v[74:77], v[150:153], v[210:213], v[74:77]
	v_mfma_i32_16x16x64_i8 v[74:77], v[146:149], v[214:217], v[74:77]
	v_mfma_i32_16x16x64_i8 v[118:121], v[142:145], v[174:177], v[118:121]
	v_mfma_i32_16x16x64_i8 v[118:121], v[138:141], v[178:181], v[118:121]
	v_mfma_i32_16x16x64_i8 v[114:117], v[134:137], v[174:177], v[114:117]
	v_mfma_i32_16x16x64_i8 v[114:117], v[130:133], v[178:181], v[114:117]
	v_mfma_i32_16x16x64_i8 v[102:105], v[142:145], v[188:191], v[102:105]
	v_mfma_i32_16x16x64_i8 v[102:105], v[138:141], v[192:195], v[102:105]
	v_mfma_i32_16x16x64_i8 v[98:101], v[134:137], v[188:191], v[98:101]
	v_mfma_i32_16x16x64_i8 v[98:101], v[130:133], v[192:195], v[98:101]
	v_mfma_i32_16x16x64_i8 v[86:89], v[142:145], v[202:205], v[86:89]
	v_mfma_i32_16x16x64_i8 v[86:89], v[138:141], v[206:209], v[86:89]
	v_mfma_i32_16x16x64_i8 v[82:85], v[134:137], v[202:205], v[82:85]
	v_mfma_i32_16x16x64_i8 v[82:85], v[130:133], v[206:209], v[82:85]
	v_mfma_i32_16x16x64_i8 v[70:73], v[142:145], v[210:213], v[70:73]
	v_mfma_i32_16x16x64_i8 v[70:73], v[138:141], v[214:217], v[70:73]
	v_mfma_i32_16x16x64_i8 v[66:69], v[134:137], v[210:213], v[66:69]
	v_mfma_i32_16x16x64_i8 v[66:69], v[130:133], v[214:217], v[66:69]
	s_setprio 1
	s_barrier
	s_add_i32 s46, s17, s9
	v_lshl_add_u64 v[174:175], s[30:31], 0, v[166:167]
	s_mov_b32 m0, s46
	ds_read_b128 v[188:191], v187 offset:16384
	ds_read_b128 v[192:195], v187 offset:17408
	ds_read_b128 v[202:205], v187 offset:18432
	ds_read_b128 v[206:209], v187 offset:19456
	ds_read_b128 v[210:213], v187 offset:20480
	ds_read_b128 v[214:217], v187 offset:21504
	ds_read_b128 v[220:223], v187 offset:22528
	ds_read_b128 v[224:227], v187 offset:23552
	global_load_lds_dwordx4 v[174:175], off
	s_add_i32 m0, s46, 0x2000
	s_add_u32 s46, s30, 0x80000
	v_lshl_add_u64 v[176:177], s[30:31], 0, v[162:163]
	s_addc_u32 s47, s31, 0
	s_add_i32 s48, s55, s9
	global_load_lds_dwordx4 v[176:177], off
	v_lshl_add_u64 v[178:179], s[46:47], 0, v[166:167]
	s_mov_b32 m0, s48
	v_lshl_add_u64 v[180:181], s[34:35], 0, v[164:165]
	global_load_lds_dwordx4 v[178:179], off
	v_lshl_add_u64 v[178:179], s[46:47], 0, v[162:163]
	s_add_i32 m0, s48, 0x2000
	s_nop 0
	global_load_lds_dwordx4 v[178:179], off
	v_lshl_add_u64 v[178:179], s[34:35], 0, v[168:169]
	s_mov_b32 m0, s27
	s_nop 0
	global_load_lds_dwordx4 v[178:179], off
	s_mov_b32 m0, s33
	s_nop 0
	global_load_lds_dwordx4 v[180:181], off
	s_waitcnt vmcnt(8)
	s_waitcnt lgkmcnt(0)
	s_barrier
	s_setprio 0
	s_waitcnt lgkmcnt(0)
	v_mfma_i32_16x16x64_i8 v[62:65], v[158:161], v[188:191], v[62:65]
	v_mfma_i32_16x16x64_i8 v[62:65], v[154:157], v[192:195], v[62:65]
	v_mfma_i32_16x16x64_i8 v[58:61], v[150:153], v[188:191], v[58:61]
	v_mfma_i32_16x16x64_i8 v[58:61], v[146:149], v[192:195], v[58:61]
	v_mfma_i32_16x16x64_i8 v[46:49], v[158:161], v[202:205], v[46:49]
	v_mfma_i32_16x16x64_i8 v[46:49], v[154:157], v[206:209], v[46:49]
	v_mfma_i32_16x16x64_i8 v[42:45], v[150:153], v[202:205], v[42:45]
	v_mfma_i32_16x16x64_i8 v[42:45], v[146:149], v[206:209], v[42:45]
	v_mfma_i32_16x16x64_i8 v[30:33], v[158:161], v[210:213], v[30:33]
	v_mfma_i32_16x16x64_i8 v[30:33], v[154:157], v[214:217], v[30:33]
	v_mfma_i32_16x16x64_i8 v[26:29], v[150:153], v[210:213], v[26:29]
	v_mfma_i32_16x16x64_i8 v[26:29], v[146:149], v[214:217], v[26:29]
	v_mfma_i32_16x16x64_i8 v[14:17], v[158:161], v[220:223], v[14:17]
	v_mfma_i32_16x16x64_i8 v[14:17], v[154:157], v[224:227], v[14:17]
	v_mfma_i32_16x16x64_i8 v[10:13], v[150:153], v[220:223], v[10:13]
	v_mfma_i32_16x16x64_i8 v[10:13], v[146:149], v[224:227], v[10:13]
	v_mfma_i32_16x16x64_i8 v[54:57], v[142:145], v[188:191], v[54:57]
	v_mfma_i32_16x16x64_i8 v[54:57], v[138:141], v[192:195], v[54:57]
	v_mfma_i32_16x16x64_i8 v[50:53], v[134:137], v[188:191], v[50:53]
	v_mfma_i32_16x16x64_i8 v[50:53], v[130:133], v[192:195], v[50:53]
	v_mfma_i32_16x16x64_i8 v[38:41], v[142:145], v[202:205], v[38:41]
	v_mfma_i32_16x16x64_i8 v[38:41], v[138:141], v[206:209], v[38:41]
	v_mfma_i32_16x16x64_i8 v[34:37], v[134:137], v[202:205], v[34:37]
	v_mfma_i32_16x16x64_i8 v[34:37], v[130:133], v[206:209], v[34:37]
	v_mfma_i32_16x16x64_i8 v[22:25], v[142:145], v[210:213], v[22:25]
	v_mfma_i32_16x16x64_i8 v[22:25], v[138:141], v[214:217], v[22:25]
	v_mfma_i32_16x16x64_i8 v[18:21], v[134:137], v[210:213], v[18:21]
	v_mfma_i32_16x16x64_i8 v[18:21], v[130:133], v[214:217], v[18:21]
	v_mfma_i32_16x16x64_i8 v[6:9], v[142:145], v[220:223], v[6:9]
	v_mfma_i32_16x16x64_i8 v[6:9], v[138:141], v[224:227], v[6:9]
	v_mfma_i32_16x16x64_i8 v[2:5], v[134:137], v[220:223], v[2:5]
	v_mfma_i32_16x16x64_i8 v[2:5], v[130:133], v[224:227], v[2:5]
	s_setprio 1
	s_barrier
	v_add_u32_e32 v142, s56, v183
	v_add_u32_e32 v158, s57, v183
	ds_read_b128 v[130:133], v142
	ds_read_b128 v[134:137], v142 offset:1024
	ds_read_b128 v[138:141], v142 offset:2048
	ds_read_b128 v[142:145], v142 offset:3072
	ds_read_b128 v[146:149], v158
	ds_read_b128 v[150:153], v158 offset:1024
	ds_read_b128 v[154:157], v158 offset:2048
	ds_read_b128 v[158:161], v158 offset:3072
	s_add_u32 s34, s34, 0x80000
	s_addc_u32 s35, s35, 0
	s_mov_b32 m0, s36
	v_lshl_add_u64 v[232:233], s[34:35], 0, v[168:169]
	ds_read_b128 v[188:191], v187 offset:32768
	ds_read_b128 v[192:195], v187 offset:33792
	ds_read_b128 v[202:205], v187 offset:34816
	ds_read_b128 v[206:209], v187 offset:35840
	ds_read_b128 v[210:213], v187 offset:36864
	ds_read_b128 v[214:217], v187 offset:37888
	ds_read_b128 v[220:223], v187 offset:38912
	ds_read_b128 v[224:227], v187 offset:39936
	global_load_lds_dwordx4 v[232:233], off
	v_lshl_add_u64 v[232:233], s[34:35], 0, v[164:165]
	s_mov_b32 m0, s37
	s_nop 0
	global_load_lds_dwordx4 v[232:233], off
	s_waitcnt vmcnt(8)
	s_waitcnt lgkmcnt(0)
	s_barrier
	s_setprio 0
	s_waitcnt lgkmcnt(0)
	v_mfma_i32_16x16x64_i8 v[126:129], v[130:133], v[188:191], v[126:129]
	v_mfma_i32_16x16x64_i8 v[126:129], v[134:137], v[192:195], v[126:129]
	v_mfma_i32_16x16x64_i8 v[122:125], v[138:141], v[188:191], v[122:125]
	v_mfma_i32_16x16x64_i8 v[122:125], v[142:145], v[192:195], v[122:125]
	v_mfma_i32_16x16x64_i8 v[110:113], v[130:133], v[202:205], v[110:113]
	v_mfma_i32_16x16x64_i8 v[110:113], v[134:137], v[206:209], v[110:113]
	v_mfma_i32_16x16x64_i8 v[106:109], v[138:141], v[202:205], v[106:109]
	v_mfma_i32_16x16x64_i8 v[106:109], v[142:145], v[206:209], v[106:109]
	v_mfma_i32_16x16x64_i8 v[94:97], v[130:133], v[210:213], v[94:97]
	v_mfma_i32_16x16x64_i8 v[94:97], v[134:137], v[214:217], v[94:97]
	v_mfma_i32_16x16x64_i8 v[90:93], v[138:141], v[210:213], v[90:93]
	v_mfma_i32_16x16x64_i8 v[90:93], v[142:145], v[214:217], v[90:93]
	v_mfma_i32_16x16x64_i8 v[78:81], v[130:133], v[220:223], v[78:81]
	v_mfma_i32_16x16x64_i8 v[78:81], v[134:137], v[224:227], v[78:81]
	v_mfma_i32_16x16x64_i8 v[74:77], v[138:141], v[220:223], v[74:77]
	v_mfma_i32_16x16x64_i8 v[74:77], v[142:145], v[224:227], v[74:77]
	v_mfma_i32_16x16x64_i8 v[118:121], v[146:149], v[188:191], v[118:121]
	v_mfma_i32_16x16x64_i8 v[118:121], v[150:153], v[192:195], v[118:121]
	v_mfma_i32_16x16x64_i8 v[114:117], v[154:157], v[188:191], v[114:117]
	v_mfma_i32_16x16x64_i8 v[114:117], v[158:161], v[192:195], v[114:117]
	v_mfma_i32_16x16x64_i8 v[102:105], v[146:149], v[202:205], v[102:105]
	v_mfma_i32_16x16x64_i8 v[102:105], v[150:153], v[206:209], v[102:105]
	v_mfma_i32_16x16x64_i8 v[98:101], v[154:157], v[202:205], v[98:101]
	v_mfma_i32_16x16x64_i8 v[98:101], v[158:161], v[206:209], v[98:101]
	v_mfma_i32_16x16x64_i8 v[86:89], v[146:149], v[210:213], v[86:89]
	v_mfma_i32_16x16x64_i8 v[86:89], v[150:153], v[214:217], v[86:89]
	v_mfma_i32_16x16x64_i8 v[82:85], v[154:157], v[210:213], v[82:85]
	v_mfma_i32_16x16x64_i8 v[82:85], v[158:161], v[214:217], v[82:85]
	v_mfma_i32_16x16x64_i8 v[70:73], v[146:149], v[220:223], v[70:73]
	v_mfma_i32_16x16x64_i8 v[70:73], v[150:153], v[224:227], v[70:73]
	v_mfma_i32_16x16x64_i8 v[66:69], v[154:157], v[220:223], v[66:69]
	v_mfma_i32_16x16x64_i8 v[66:69], v[158:161], v[224:227], v[66:69]
	s_setprio 1
	s_barrier
	s_add_i32 s34, s56, s9
	v_lshl_add_u64 v[174:175], v[174:175], 0, s[4:5]
	s_mov_b32 m0, s34
	ds_read_b128 v[188:191], v187 offset:49152
	ds_read_b128 v[192:195], v187 offset:50176
	ds_read_b128 v[202:205], v187 offset:51200
	ds_read_b128 v[206:209], v187 offset:52224
	ds_read_b128 v[210:213], v187 offset:53248
	ds_read_b128 v[214:217], v187 offset:54272
	ds_read_b128 v[220:223], v187 offset:55296
	ds_read_b128 v[224:227], v187 offset:56320
	global_load_lds_dwordx4 v[174:175], off
	s_add_i32 m0, s34, 0x2000
	s_add_u32 s30, s30, 0x80080
	v_lshl_add_u64 v[174:175], v[176:177], 0, s[4:5]
	s_addc_u32 s31, s31, 0
	s_add_i32 s34, s57, s9
	global_load_lds_dwordx4 v[174:175], off
	v_lshl_add_u64 v[174:175], s[30:31], 0, v[166:167]
	s_mov_b32 m0, s34
	s_nop 0
	global_load_lds_dwordx4 v[174:175], off
	v_lshl_add_u64 v[174:175], s[30:31], 0, v[162:163]
	s_add_i32 m0, s34, 0x2000
	s_nop 0
	global_load_lds_dwordx4 v[174:175], off
	v_lshl_add_u64 v[174:175], v[178:179], 0, s[4:5]
	s_mov_b32 m0, s39
	s_nop 0
	global_load_lds_dwordx4 v[174:175], off
	v_lshl_add_u64 v[174:175], v[180:181], 0, s[4:5]
	s_mov_b32 m0, s40
	s_nop 0
	global_load_lds_dwordx4 v[174:175], off
	s_waitcnt vmcnt(8)
	s_waitcnt lgkmcnt(0)
	s_barrier
	s_setprio 0
	s_waitcnt lgkmcnt(0)
	v_mfma_i32_16x16x64_i8 v[62:65], v[130:133], v[188:191], v[62:65]
	v_mfma_i32_16x16x64_i8 v[62:65], v[134:137], v[192:195], v[62:65]
	v_mfma_i32_16x16x64_i8 v[58:61], v[138:141], v[188:191], v[58:61]
	v_mfma_i32_16x16x64_i8 v[58:61], v[142:145], v[192:195], v[58:61]
	v_mfma_i32_16x16x64_i8 v[46:49], v[130:133], v[202:205], v[46:49]
	v_mfma_i32_16x16x64_i8 v[46:49], v[134:137], v[206:209], v[46:49]
	v_mfma_i32_16x16x64_i8 v[42:45], v[138:141], v[202:205], v[42:45]
	v_mfma_i32_16x16x64_i8 v[42:45], v[142:145], v[206:209], v[42:45]
	v_mfma_i32_16x16x64_i8 v[30:33], v[130:133], v[210:213], v[30:33]
	v_mfma_i32_16x16x64_i8 v[30:33], v[134:137], v[214:217], v[30:33]
	v_mfma_i32_16x16x64_i8 v[26:29], v[138:141], v[210:213], v[26:29]
	v_mfma_i32_16x16x64_i8 v[26:29], v[142:145], v[214:217], v[26:29]
	v_mfma_i32_16x16x64_i8 v[14:17], v[130:133], v[220:223], v[14:17]
	v_mfma_i32_16x16x64_i8 v[14:17], v[134:137], v[224:227], v[14:17]
	v_mfma_i32_16x16x64_i8 v[10:13], v[138:141], v[220:223], v[10:13]
	v_mfma_i32_16x16x64_i8 v[10:13], v[142:145], v[224:227], v[10:13]
	v_mfma_i32_16x16x64_i8 v[54:57], v[146:149], v[188:191], v[54:57]
	v_mfma_i32_16x16x64_i8 v[54:57], v[150:153], v[192:195], v[54:57]
	v_mfma_i32_16x16x64_i8 v[50:53], v[154:157], v[188:191], v[50:53]
	v_mfma_i32_16x16x64_i8 v[50:53], v[158:161], v[192:195], v[50:53]
	v_mfma_i32_16x16x64_i8 v[38:41], v[146:149], v[202:205], v[38:41]
	v_mfma_i32_16x16x64_i8 v[38:41], v[150:153], v[206:209], v[38:41]
	v_mfma_i32_16x16x64_i8 v[34:37], v[154:157], v[202:205], v[34:37]
	v_mfma_i32_16x16x64_i8 v[34:37], v[158:161], v[206:209], v[34:37]
	v_mfma_i32_16x16x64_i8 v[22:25], v[146:149], v[210:213], v[22:25]
	v_mfma_i32_16x16x64_i8 v[22:25], v[150:153], v[214:217], v[22:25]
	v_mfma_i32_16x16x64_i8 v[18:21], v[154:157], v[210:213], v[18:21]
	v_mfma_i32_16x16x64_i8 v[18:21], v[158:161], v[214:217], v[18:21]
	v_mfma_i32_16x16x64_i8 v[6:9], v[146:149], v[220:223], v[6:9]
	v_mfma_i32_16x16x64_i8 v[6:9], v[150:153], v[224:227], v[6:9]
	v_mfma_i32_16x16x64_i8 v[2:5], v[154:157], v[220:223], v[2:5]
	v_mfma_i32_16x16x64_i8 v[2:5], v[158:161], v[224:227], v[2:5]
	s_setprio 1
	s_barrier
	s_add_i32 s45, s45, 2
	s_add_u32 s28, s28, 0x100
	s_addc_u32 s29, s29, 0
	s_add_u32 s43, s43, 0x100
	s_addc_u32 s44, s44, 0
	s_cmp_gt_u32 s45, 29
	s_cbranch_scc0 .LBB0_961
	s_nop 15
	s_nop 15
	s_and_b64 vcc, exec, s[6:7]
	s_cbranch_vccz .LBB0_964
	s_barrier

.LBB0_1058:
	ds_read_b128 v[128:131], v194
	ds_read_b128 v[132:135], v194 offset:1024
	ds_read_b128 v[136:139], v194 offset:2048
	ds_read_b128 v[140:143], v194 offset:3072
	ds_read_b128 v[144:147], v195
	ds_read_b128 v[148:151], v195 offset:1024
	ds_read_b128 v[152:155], v195 offset:2048
	ds_read_b128 v[156:159], v195 offset:3072
	s_add_u32 s2, s0, 0x100
	s_addc_u32 s3, s1, 0
	s_cmpk_eq_i32 s39, 0xa8
	s_cselect_b32 s37, s31, s3
	s_cselect_b32 s36, s30, s2
	s_cselect_b32 s5, s7, s38
	s_cselect_b32 s4, s6, s29
	v_lshl_add_u64 v[188:189], s[0:1], 0, v[168:169]
	s_add_i32 m0, s27, 0xc000
	ds_read_b128 v[172:175], v196
	ds_read_b128 v[176:179], v196 offset:1024
	ds_read_b128 v[180:183], v196 offset:2048
	ds_read_b128 v[184:187], v196 offset:3072
	ds_read_b128 v[200:203], v196 offset:4096
	ds_read_b128 v[204:207], v196 offset:5120
	ds_read_b128 v[208:211], v196 offset:6144
	ds_read_b128 v[212:215], v196 offset:7168
	global_load_lds_dwordx4 v[188:189], off
	v_lshl_add_u64 v[188:189], s[0:1], 0, v[170:171]
	s_add_i32 m0, s27, 0xe000
	s_nop 0
	global_load_lds_dwordx4 v[188:189], off
	s_waitcnt vmcnt(8)
	s_waitcnt lgkmcnt(0)
	s_barrier
	s_setprio 0
	s_waitcnt lgkmcnt(0)
	v_mfma_f32_16x16x32_bf16 v[12:15], v[128:131], v[172:175], v[12:15]
	v_mfma_f32_16x16x32_bf16 v[8:11], v[136:139], v[172:175], v[8:11]
	v_mfma_f32_16x16x32_bf16 v[36:39], v[128:131], v[180:183], v[36:39]
	v_mfma_f32_16x16x32_bf16 v[32:35], v[136:139], v[180:183], v[32:35]
	v_mfma_f32_16x16x32_bf16 v[44:47], v[128:131], v[200:203], v[44:47]
	v_mfma_f32_16x16x32_bf16 v[40:43], v[136:139], v[200:203], v[40:43]
	v_mfma_f32_16x16x32_bf16 v[64:67], v[128:131], v[208:211], v[64:67]
	v_mfma_f32_16x16x32_bf16 v[56:59], v[136:139], v[208:211], v[56:59]
	v_mfma_f32_16x16x32_bf16 v[12:15], v[132:135], v[176:179], v[12:15]
	v_mfma_f32_16x16x32_bf16 v[8:11], v[140:143], v[176:179], v[8:11]
	v_mfma_f32_16x16x32_bf16 v[36:39], v[132:135], v[184:187], v[36:39]
	v_mfma_f32_16x16x32_bf16 v[32:35], v[140:143], v[184:187], v[32:35]
	v_mfma_f32_16x16x32_bf16 v[44:47], v[132:135], v[204:207], v[44:47]
	v_mfma_f32_16x16x32_bf16 v[40:43], v[140:143], v[204:207], v[40:43]
	v_mfma_f32_16x16x32_bf16 v[64:67], v[132:135], v[212:215], v[64:67]
	v_mfma_f32_16x16x32_bf16 v[56:59], v[140:143], v[212:215], v[56:59]
	v_mfma_f32_16x16x32_bf16 v[4:7], v[144:147], v[172:175], v[4:7]
	v_mfma_f32_16x16x32_bf16 v[0:3], v[152:155], v[172:175], v[0:3]
	v_mfma_f32_16x16x32_bf16 v[24:27], v[144:147], v[180:183], v[24:27]
	v_mfma_f32_16x16x32_bf16 v[16:19], v[152:155], v[180:183], v[16:19]
	v_mfma_f32_16x16x32_bf16 v[28:31], v[144:147], v[200:203], v[28:31]
	v_mfma_f32_16x16x32_bf16 v[20:23], v[152:155], v[200:203], v[20:23]
	v_mfma_f32_16x16x32_bf16 v[52:55], v[144:147], v[208:211], v[52:55]
	v_mfma_f32_16x16x32_bf16 v[48:51], v[152:155], v[208:211], v[48:51]
	v_mfma_f32_16x16x32_bf16 v[4:7], v[148:151], v[176:179], v[4:7]
	v_mfma_f32_16x16x32_bf16 v[0:3], v[156:159], v[176:179], v[0:3]
	v_mfma_f32_16x16x32_bf16 v[24:27], v[148:151], v[184:187], v[24:27]
	v_mfma_f32_16x16x32_bf16 v[16:19], v[156:159], v[184:187], v[16:19]
	v_mfma_f32_16x16x32_bf16 v[28:31], v[148:151], v[204:207], v[28:31]
	v_mfma_f32_16x16x32_bf16 v[20:23], v[156:159], v[204:207], v[20:23]
	v_mfma_f32_16x16x32_bf16 v[52:55], v[148:151], v[212:215], v[52:55]
	v_mfma_f32_16x16x32_bf16 v[48:51], v[156:159], v[212:215], v[48:51]
	s_setprio 1
	s_barrier
	s_add_i32 s0, s17, s25
	v_lshl_add_u64 v[188:189], s[4:5], 0, v[162:163]
	s_mov_b32 m0, s0
	ds_read_b128 v[172:175], v196 offset:16384
	ds_read_b128 v[176:179], v196 offset:17408
	ds_read_b128 v[180:183], v196 offset:18432
	ds_read_b128 v[184:187], v196 offset:19456
	ds_read_b128 v[200:203], v196 offset:20480
	ds_read_b128 v[204:207], v196 offset:21504
	ds_read_b128 v[208:211], v196 offset:22528
	ds_read_b128 v[212:215], v196 offset:23552
	global_load_lds_dwordx4 v[188:189], off
	s_add_i32 m0, s0, 0x2000
	s_add_u32 s0, s4, 0x2b0000
	v_lshl_add_u64 v[216:217], s[4:5], 0, v[166:167]
	s_addc_u32 s1, s5, 0
	s_add_i32 s40, s55, s25
	global_load_lds_dwordx4 v[216:217], off
	v_lshl_add_u64 v[220:221], s[0:1], 0, v[162:163]
	s_mov_b32 m0, s40
	v_lshl_add_u64 v[222:223], s[36:37], 0, v[164:165]
	global_load_lds_dwordx4 v[220:221], off
	v_lshl_add_u64 v[220:221], s[0:1], 0, v[166:167]
	s_add_i32 m0, s40, 0x2000
	s_nop 0
	global_load_lds_dwordx4 v[220:221], off
	v_lshl_add_u64 v[220:221], s[36:37], 0, v[160:161]
	s_mov_b32 m0, s27
	s_nop 0
	global_load_lds_dwordx4 v[220:221], off
	s_mov_b32 m0, s33
	s_nop 0
	global_load_lds_dwordx4 v[222:223], off
	s_waitcnt vmcnt(8)
	s_waitcnt lgkmcnt(0)
	s_barrier
	s_setprio 0
	s_waitcnt lgkmcnt(0)
	v_mfma_f32_16x16x32_bf16 v[76:79], v[128:131], v[172:175], v[76:79]
	v_mfma_f32_16x16x32_bf16 v[72:75], v[136:139], v[172:175], v[72:75]
	v_mfma_f32_16x16x32_bf16 v[92:95], v[128:131], v[180:183], v[92:95]
	v_mfma_f32_16x16x32_bf16 v[88:91], v[136:139], v[180:183], v[88:91]
	v_mfma_f32_16x16x32_bf16 v[108:111], v[128:131], v[200:203], v[108:111]
	v_mfma_f32_16x16x32_bf16 v[104:107], v[136:139], v[200:203], v[104:107]
	v_mfma_f32_16x16x32_bf16 v[124:127], v[128:131], v[208:211], v[124:127]
	v_mfma_f32_16x16x32_bf16 v[120:123], v[136:139], v[208:211], v[120:123]
	v_mfma_f32_16x16x32_bf16 v[76:79], v[132:135], v[176:179], v[76:79]
	v_mfma_f32_16x16x32_bf16 v[72:75], v[140:143], v[176:179], v[72:75]
	v_mfma_f32_16x16x32_bf16 v[92:95], v[132:135], v[184:187], v[92:95]
	v_mfma_f32_16x16x32_bf16 v[88:91], v[140:143], v[184:187], v[88:91]
	v_mfma_f32_16x16x32_bf16 v[108:111], v[132:135], v[204:207], v[108:111]
	v_mfma_f32_16x16x32_bf16 v[104:107], v[140:143], v[204:207], v[104:107]
	v_mfma_f32_16x16x32_bf16 v[124:127], v[132:135], v[212:215], v[124:127]
	v_mfma_f32_16x16x32_bf16 v[120:123], v[140:143], v[212:215], v[120:123]
	v_mfma_f32_16x16x32_bf16 v[68:71], v[144:147], v[172:175], v[68:71]
	v_mfma_f32_16x16x32_bf16 v[60:63], v[152:155], v[172:175], v[60:63]
	v_mfma_f32_16x16x32_bf16 v[84:87], v[144:147], v[180:183], v[84:87]
	v_mfma_f32_16x16x32_bf16 v[80:83], v[152:155], v[180:183], v[80:83]
	v_mfma_f32_16x16x32_bf16 v[100:103], v[144:147], v[200:203], v[100:103]
	v_mfma_f32_16x16x32_bf16 v[96:99], v[152:155], v[200:203], v[96:99]
	v_mfma_f32_16x16x32_bf16 v[116:119], v[144:147], v[208:211], v[116:119]
	v_mfma_f32_16x16x32_bf16 v[112:115], v[152:155], v[208:211], v[112:115]
	v_mfma_f32_16x16x32_bf16 v[68:71], v[148:151], v[176:179], v[68:71]
	v_mfma_f32_16x16x32_bf16 v[60:63], v[156:159], v[176:179], v[60:63]
	v_mfma_f32_16x16x32_bf16 v[84:87], v[148:151], v[184:187], v[84:87]
	v_mfma_f32_16x16x32_bf16 v[80:83], v[156:159], v[184:187], v[80:83]
	v_mfma_f32_16x16x32_bf16 v[100:103], v[148:151], v[204:207], v[100:103]
	v_mfma_f32_16x16x32_bf16 v[96:99], v[156:159], v[204:207], v[96:99]
	v_mfma_f32_16x16x32_bf16 v[116:119], v[148:151], v[212:215], v[116:119]
	v_mfma_f32_16x16x32_bf16 v[112:115], v[156:159], v[212:215], v[112:115]
	s_setprio 1
	s_barrier
	v_add_u32_e32 v140, s56, v193
	v_add_u32_e32 v156, s57, v193
	ds_read_b128 v[128:131], v140
	ds_read_b128 v[132:135], v140 offset:1024
	ds_read_b128 v[136:139], v140 offset:2048
	ds_read_b128 v[140:143], v140 offset:3072
	ds_read_b128 v[144:147], v156
	ds_read_b128 v[148:151], v156 offset:1024
	ds_read_b128 v[152:155], v156 offset:2048
	ds_read_b128 v[156:159], v156 offset:3072
	s_add_u32 s0, s36, 0x2b0000
	s_addc_u32 s1, s37, 0
	s_mov_b32 m0, s46
	v_lshl_add_u64 v[224:225], s[0:1], 0, v[160:161]
	ds_read_b128 v[172:175], v196 offset:32768
	ds_read_b128 v[176:179], v196 offset:33792
	ds_read_b128 v[180:183], v196 offset:34816
	ds_read_b128 v[184:187], v196 offset:35840
	ds_read_b128 v[200:203], v196 offset:36864
	ds_read_b128 v[204:207], v196 offset:37888
	ds_read_b128 v[208:211], v196 offset:38912
	ds_read_b128 v[212:215], v196 offset:39936
	global_load_lds_dwordx4 v[224:225], off
	v_lshl_add_u64 v[224:225], s[0:1], 0, v[164:165]
	s_mov_b32 m0, s47
	s_nop 0
	global_load_lds_dwordx4 v[224:225], off
	s_waitcnt vmcnt(8)
	s_waitcnt lgkmcnt(0)
	s_barrier
	s_setprio 0
	s_waitcnt lgkmcnt(0)
	v_mfma_f32_16x16x32_bf16 v[12:15], v[128:131], v[172:175], v[12:15]
	v_mfma_f32_16x16x32_bf16 v[8:11], v[136:139], v[172:175], v[8:11]
	v_mfma_f32_16x16x32_bf16 v[36:39], v[128:131], v[180:183], v[36:39]
	v_mfma_f32_16x16x32_bf16 v[32:35], v[136:139], v[180:183], v[32:35]
	v_mfma_f32_16x16x32_bf16 v[44:47], v[128:131], v[200:203], v[44:47]
	v_mfma_f32_16x16x32_bf16 v[40:43], v[136:139], v[200:203], v[40:43]
	v_mfma_f32_16x16x32_bf16 v[64:67], v[128:131], v[208:211], v[64:67]
	v_mfma_f32_16x16x32_bf16 v[56:59], v[136:139], v[208:211], v[56:59]
	v_mfma_f32_16x16x32_bf16 v[12:15], v[132:135], v[176:179], v[12:15]
	v_mfma_f32_16x16x32_bf16 v[8:11], v[140:143], v[176:179], v[8:11]
	v_mfma_f32_16x16x32_bf16 v[36:39], v[132:135], v[184:187], v[36:39]
	v_mfma_f32_16x16x32_bf16 v[32:35], v[140:143], v[184:187], v[32:35]
	v_mfma_f32_16x16x32_bf16 v[44:47], v[132:135], v[204:207], v[44:47]
	v_mfma_f32_16x16x32_bf16 v[40:43], v[140:143], v[204:207], v[40:43]
	v_mfma_f32_16x16x32_bf16 v[64:67], v[132:135], v[212:215], v[64:67]
	v_mfma_f32_16x16x32_bf16 v[56:59], v[140:143], v[212:215], v[56:59]
	v_mfma_f32_16x16x32_bf16 v[4:7], v[144:147], v[172:175], v[4:7]
	v_mfma_f32_16x16x32_bf16 v[0:3], v[152:155], v[172:175], v[0:3]
	v_mfma_f32_16x16x32_bf16 v[24:27], v[144:147], v[180:183], v[24:27]
	v_mfma_f32_16x16x32_bf16 v[16:19], v[152:155], v[180:183], v[16:19]
	v_mfma_f32_16x16x32_bf16 v[28:31], v[144:147], v[200:203], v[28:31]
	v_mfma_f32_16x16x32_bf16 v[20:23], v[152:155], v[200:203], v[20:23]
	v_mfma_f32_16x16x32_bf16 v[52:55], v[144:147], v[208:211], v[52:55]
	v_mfma_f32_16x16x32_bf16 v[48:51], v[152:155], v[208:211], v[48:51]
	v_mfma_f32_16x16x32_bf16 v[4:7], v[148:151], v[176:179], v[4:7]
	v_mfma_f32_16x16x32_bf16 v[0:3], v[156:159], v[176:179], v[0:3]
	v_mfma_f32_16x16x32_bf16 v[24:27], v[148:151], v[184:187], v[24:27]
	v_mfma_f32_16x16x32_bf16 v[16:19], v[156:159], v[184:187], v[16:19]
	v_mfma_f32_16x16x32_bf16 v[28:31], v[148:151], v[204:207], v[28:31]
	v_mfma_f32_16x16x32_bf16 v[20:23], v[156:159], v[204:207], v[20:23]
	v_mfma_f32_16x16x32_bf16 v[52:55], v[148:151], v[212:215], v[52:55]
	v_mfma_f32_16x16x32_bf16 v[48:51], v[156:159], v[212:215], v[48:51]
	s_setprio 1
	s_barrier
	s_add_i32 s0, s56, s25
	v_lshl_add_u64 v[188:189], v[188:189], 0, s[18:19]
	s_mov_b32 m0, s0
	ds_read_b128 v[172:175], v196 offset:49152
	ds_read_b128 v[176:179], v196 offset:50176
	ds_read_b128 v[180:183], v196 offset:51200
	ds_read_b128 v[184:187], v196 offset:52224
	ds_read_b128 v[200:203], v196 offset:53248
	ds_read_b128 v[204:207], v196 offset:54272
	ds_read_b128 v[208:211], v196 offset:55296
	ds_read_b128 v[212:215], v196 offset:56320
	global_load_lds_dwordx4 v[188:189], off
	s_add_i32 m0, s0, 0x2000
	s_add_u32 s0, s4, 0x2b0080
	v_lshl_add_u64 v[188:189], v[216:217], 0, s[18:19]
	s_addc_u32 s1, s5, 0
	s_add_i32 s4, s57, s25
	global_load_lds_dwordx4 v[188:189], off
	v_lshl_add_u64 v[188:189], s[0:1], 0, v[162:163]
	s_mov_b32 m0, s4
	s_nop 0
	global_load_lds_dwordx4 v[188:189], off
	v_lshl_add_u64 v[188:189], s[0:1], 0, v[166:167]
	s_add_i32 m0, s4, 0x2000
	s_nop 0
	global_load_lds_dwordx4 v[188:189], off
	v_lshl_add_u64 v[188:189], v[220:221], 0, s[18:19]
	s_mov_b32 m0, s52
	s_nop 0
	global_load_lds_dwordx4 v[188:189], off
	v_lshl_add_u64 v[188:189], v[222:223], 0, s[18:19]
	s_mov_b32 m0, s53
	s_nop 0
	global_load_lds_dwordx4 v[188:189], off
	s_waitcnt vmcnt(8)
	s_waitcnt lgkmcnt(0)
	s_barrier
	s_setprio 0
	s_waitcnt lgkmcnt(0)
	v_mfma_f32_16x16x32_bf16 v[76:79], v[128:131], v[172:175], v[76:79]
	v_mfma_f32_16x16x32_bf16 v[72:75], v[136:139], v[172:175], v[72:75]
	v_mfma_f32_16x16x32_bf16 v[92:95], v[128:131], v[180:183], v[92:95]
	v_mfma_f32_16x16x32_bf16 v[88:91], v[136:139], v[180:183], v[88:91]
	v_mfma_f32_16x16x32_bf16 v[108:111], v[128:131], v[200:203], v[108:111]
	v_mfma_f32_16x16x32_bf16 v[104:107], v[136:139], v[200:203], v[104:107]
	v_mfma_f32_16x16x32_bf16 v[124:127], v[128:131], v[208:211], v[124:127]
	v_mfma_f32_16x16x32_bf16 v[120:123], v[136:139], v[208:211], v[120:123]
	v_mfma_f32_16x16x32_bf16 v[76:79], v[132:135], v[176:179], v[76:79]
	v_mfma_f32_16x16x32_bf16 v[72:75], v[140:143], v[176:179], v[72:75]
	v_mfma_f32_16x16x32_bf16 v[92:95], v[132:135], v[184:187], v[92:95]
	v_mfma_f32_16x16x32_bf16 v[88:91], v[140:143], v[184:187], v[88:91]
	v_mfma_f32_16x16x32_bf16 v[108:111], v[132:135], v[204:207], v[108:111]
	v_mfma_f32_16x16x32_bf16 v[104:107], v[140:143], v[204:207], v[104:107]
	v_mfma_f32_16x16x32_bf16 v[124:127], v[132:135], v[212:215], v[124:127]
	v_mfma_f32_16x16x32_bf16 v[120:123], v[140:143], v[212:215], v[120:123]
	v_mfma_f32_16x16x32_bf16 v[68:71], v[144:147], v[172:175], v[68:71]
	v_mfma_f32_16x16x32_bf16 v[60:63], v[152:155], v[172:175], v[60:63]
	v_mfma_f32_16x16x32_bf16 v[84:87], v[144:147], v[180:183], v[84:87]
	v_mfma_f32_16x16x32_bf16 v[80:83], v[152:155], v[180:183], v[80:83]
	v_mfma_f32_16x16x32_bf16 v[100:103], v[144:147], v[200:203], v[100:103]
	v_mfma_f32_16x16x32_bf16 v[96:99], v[152:155], v[200:203], v[96:99]
	v_mfma_f32_16x16x32_bf16 v[116:119], v[144:147], v[208:211], v[116:119]
	v_mfma_f32_16x16x32_bf16 v[112:115], v[152:155], v[208:211], v[112:115]
	v_mfma_f32_16x16x32_bf16 v[68:71], v[148:151], v[176:179], v[68:71]
	v_mfma_f32_16x16x32_bf16 v[60:63], v[156:159], v[176:179], v[60:63]
	v_mfma_f32_16x16x32_bf16 v[84:87], v[148:151], v[184:187], v[84:87]
	v_mfma_f32_16x16x32_bf16 v[80:83], v[156:159], v[184:187], v[80:83]
	v_mfma_f32_16x16x32_bf16 v[100:103], v[148:151], v[204:207], v[100:103]
	v_mfma_f32_16x16x32_bf16 v[96:99], v[156:159], v[204:207], v[96:99]
	v_mfma_f32_16x16x32_bf16 v[116:119], v[148:151], v[212:215], v[116:119]
	v_mfma_f32_16x16x32_bf16 v[112:115], v[156:159], v[212:215], v[112:115]
	s_setprio 1
	s_barrier
	s_add_i32 s39, s39, 2
	s_add_u32 s29, s29, 0x100
	s_addc_u32 s38, s38, 0
	s_cmpk_gt_u32 s39, 0xa9
	s_mov_b64 s[0:1], s[2:3]
	s_cbranch_scc0 .LBB0_1058
	s_and_b64 vcc, exec, s[20:21]
	s_cbranch_vccz .LBB0_1061
	s_barrier
